# RG-LRU passes: serialized chunk-prefix global loads and 64-step LDS scans replaced by 8-deep batched loads followed by the dependent fma chain (same order, f32)
# speedup vs baseline: 1.2312x; 1.0271x over previous
; #define G_STORE(S, bf) { *(uint4*)&s->a[bf][srow][skc] = S##a0; *(uint4*)&s->a[bf][srow + 32][skc] = S##a1; \
;     if (MB == 2) { *(uint4*)&s->a[bf][srow + 64][skc] = S##a2; *(uint4*)&s->a[bf][srow + 96][skc] = S##a3; } \
;     *(uint4*)&s->b[bf][srow][skc] = S##b0; *(uint4*)&s->b[bf][srow + 32][skc] = S##b1; *(uint4*)&s->b[bf][srow + 64][skc] = S##b2; *(uint4*)&s->b[bf][srow + 96][skc] = S##b3; }
; template <int MB, bool PF2 = true>
; DI void gemm_main(const u16* __restrict__ A, int lda, const u16* __restrict__ B, int ldb, int K, f32x16 (&acc)[MB][2], GemmLds* s, int tid) {
;     ...
;   __syncthreads();
;   G_LOAD(p, 0); G_STORE(p, 0);
;   if (!PF2) {
;     __syncthreads();
;     for (int kt = 0; kt < KT; kt++) {
;       const int buf = kt & 1;
;       if (kt + 1 < KT) G_LOAD(p, (kt + 1) * 64);
;       if (buf) { G_COMPUTE(1); } else { G_COMPUTE(0); }
;       if (kt + 1 < KT) { if (buf) { G_STORE(p, 0); } else { G_STORE(p, 1); } }
;       __syncthreads();
;     }
;     return;
;   }
;   const int klast = K - 64;
;   G_LOAD(p, 64);
;   __syncthreads();
; DI void phase_inproj(const Params& p, int l, char* smem, int tid) {
;     ...
;   for (int it = blockIdx.x; it < 272 * 24; it += gridDim.x) {
;     const int mt = it / 24, nt = it % 24, m0 = mt * 128, n0 = nt * 128;
;     f32x16 acc[2][2]; zero_acc<2>(acc);
;     gemm_main<2>(p.xn + (size_t)m0 * 1024, 1024, Wt + (size_t)n0 * 1024, 1024, 1024, acc, s, tid);
.Lip_item:
	s_cmpk_lt_u32 s12, 0x1980
	s_cbranch_scc0 .Lip_done
	s_mov_b32 s94, 0
.Lip_again:
	s_barrier
	s_mul_hi_u32 s0, s12, 0xaaaaaaab
	s_lshr_b32 s0, s0, 4
	s_mul_i32 s1, s0, 24
	s_sub_u32 s1, s12, s1
	s_lshl_b32 s2, s0, 18
	s_add_u32 s4, s96, s2
	s_addc_u32 s5, s97, 0
	s_lshl_b32 s2, s1, 18
	s_add_u32 s8, s14, s2
	s_addc_u32 s9, s15, 0
	v_mov_b32_e32 v2, 0
	v_mov_b32_e32 v3, 0
	v_mov_b32_e32 v4, 0
	v_mov_b32_e32 v5, 0
	v_mov_b32_e32 v6, 0
	v_mov_b32_e32 v7, 0
	v_mov_b32_e32 v8, 0
	v_mov_b32_e32 v9, 0
	v_mov_b32_e32 v10, 0
	v_mov_b32_e32 v11, 0
	v_mov_b32_e32 v12, 0
	v_mov_b32_e32 v13, 0
	v_mov_b32_e32 v14, 0
	v_mov_b32_e32 v15, 0
	v_mov_b32_e32 v16, 0
	v_mov_b32_e32 v17, 0
	v_mov_b32_e32 v18, 0
	v_mov_b32_e32 v19, 0
	v_mov_b32_e32 v20, 0
	v_mov_b32_e32 v21, 0
	v_mov_b32_e32 v22, 0
	v_mov_b32_e32 v23, 0
	v_mov_b32_e32 v24, 0
	v_mov_b32_e32 v25, 0
	v_mov_b32_e32 v26, 0
	v_mov_b32_e32 v27, 0
	v_mov_b32_e32 v28, 0
	v_mov_b32_e32 v29, 0
	v_mov_b32_e32 v30, 0
	v_mov_b32_e32 v31, 0
	v_mov_b32_e32 v32, 0
	v_mov_b32_e32 v33, 0
	v_mov_b32_e32 v34, 0
	v_mov_b32_e32 v35, 0
	v_mov_b32_e32 v36, 0
	v_mov_b32_e32 v37, 0
	v_mov_b32_e32 v38, 0
	v_mov_b32_e32 v39, 0
	v_mov_b32_e32 v40, 0
	v_mov_b32_e32 v41, 0
	v_mov_b32_e32 v42, 0
	v_mov_b32_e32 v43, 0
	v_mov_b32_e32 v44, 0
	v_mov_b32_e32 v45, 0
	v_mov_b32_e32 v46, 0
	v_mov_b32_e32 v47, 0
	v_mov_b32_e32 v48, 0
	v_mov_b32_e32 v49, 0
	v_mov_b32_e32 v50, 0
	v_mov_b32_e32 v51, 0
	v_mov_b32_e32 v52, 0
	v_mov_b32_e32 v53, 0
	v_mov_b32_e32 v54, 0
	v_mov_b32_e32 v55, 0
	v_mov_b32_e32 v56, 0
	v_mov_b32_e32 v57, 0
	v_mov_b32_e32 v58, 0
	v_mov_b32_e32 v59, 0
	v_mov_b32_e32 v60, 0
	v_mov_b32_e32 v61, 0
	v_mov_b32_e32 v62, 0
	v_mov_b32_e32 v63, 0
	v_mov_b32_e32 v64, 0
	v_mov_b32_e32 v65, 0
	s_add_u32 m0, s10, 0x0
	s_nop 0
	global_load_lds_dwordx4 v98, s[4:5]
	s_add_u32 m0, s10, 0x400
	s_nop 0
	global_load_lds_dwordx4 v99, s[4:5]
	s_add_u32 m0, s10, 0x800
	s_nop 0
	global_load_lds_dwordx4 v100, s[4:5]
	s_add_u32 m0, s10, 0xc00
	s_nop 0
	global_load_lds_dwordx4 v101, s[4:5]
	s_add_u32 m0, s10, 0x4000
	s_nop 0
	global_load_lds_dwordx4 v98, s[8:9]
	s_add_u32 m0, s10, 0x4400
	s_nop 0
	global_load_lds_dwordx4 v99, s[8:9]
	s_add_u32 m0, s10, 0x4800
	s_nop 0
	global_load_lds_dwordx4 v100, s[8:9]
	s_add_u32 m0, s10, 0x4c00
	s_nop 0
	global_load_lds_dwordx4 v101, s[8:9]
	s_add_u32 s4, s4, 128
	s_addc_u32 s5, s5, 0
	s_add_u32 s8, s8, 128
	s_addc_u32 s9, s9, 0
	s_waitcnt vmcnt(0) lgkmcnt(0)
	s_barrier
	ds_read_b128 v[66:69], v102 offset:0
	ds_read_b128 v[74:77], v106 offset:0
	ds_read_b128 v[70:73], v102 offset:4096
	ds_read_b128 v[78:81], v106 offset:4096
	s_add_u32 m0, s10, 0x8000
	s_nop 0
	global_load_lds_dwordx4 v98, s[4:5]
	s_add_u32 m0, s10, 0x8400
	s_nop 0
	global_load_lds_dwordx4 v99, s[4:5]
	s_add_u32 m0, s10, 0x8800
	s_nop 0
	global_load_lds_dwordx4 v100, s[4:5]
	s_add_u32 m0, s10, 0x8c00
	s_nop 0
	global_load_lds_dwordx4 v101, s[4:5]
	s_add_u32 s4, s4, 128
	s_addc_u32 s5, s5, 0
	s_mov_b32 s11, 7

; #define MFMA(a, b, c) __builtin_amdgcn_mfma_f32_32x32x16_bf16((a), (b), (c), 0, 0, 0)
; DI u16 f2bf(float x) { return (u16)(pack2(x, 0.f) & 0xffffu); }
; DI float bf2f(u16 v) { return __uint_as_float(((unsigned)v) << 16); }
; DI void lru_item(const Params& p, int l, int b, int chunk, int blk, bool fin, char* smem, int tid) {
;     ...
;     const int ch = tid & 63;
;     const float* cw = p.cw + (size_t)l * 4 * 256 + c0 + ch;
;     const float w0 = cw[0], w1 = cw[256], w2 = cw[512], w3 = cw[768], bias = p.cb[l * 256 + c0 + ch];
; #pragma unroll 4
;     for (int e = 0; e < 16; e++) {
;       const int t = (tid >> 6) + 4 * e;
;       float v = w0 * bf2f(xr[t * 64 + ch]) + w1 * bf2f(xr[(t + 1) * 64 + ch]) + w2 * bf2f(xr[(t + 2) * 64 + ch]) + w3 * bf2f(xr[(t + 3) * 64 + ch]) + bias;
;       xcb[t][ch] = f2bf(v);
;     }
;   }
;   __syncthreads();
;   {
;     const int tb = w & 1, ob = w >> 1;
;     const int chn = ob * 32 + r;
; #pragma unroll
;     for (int dir = 0; dir < 2; dir++) {
;       f32x16 ga, gx;
; #pragma unroll
;       for (int i = 0; i < 16; i++) { ga[i] = 0.f; gx[i] = 0.f; }
;       const u16* wa = p.WtA + (((size_t)l * 2 + dir) * 4 + blk) * 4096 + (size_t)chn * 64 + h * 8;
;       const u16* wx = p.WtX + (((size_t)l * 2 + dir) * 4 + blk) * 4096 + (size_t)chn * 64 + h * 8;
; #pragma unroll
;       for (int ks = 0; ks < 4; ks++) {
;         bf16x8 a = *(const bf16x8*)&xcb[tb * 32 + r][ks * 16 + h * 8];
;         bf16x8 ba = *(const bf16x8*)(wa + ks * 16), bx = *(const bf16x8*)(wx + ks * 16);
;         ga = MFMA(a, ba, ga); gx = MFMA(a, bx, gx);
;       }
;       const int pi = (l * 2 + dir) * 256 + c0 + chn;
;       const float b_a = p.ba[pi], b_x = p.bx[pi], lam = p.lam[pi];
;       const float sp = log1pf(__expf(-lam));
.LBB0_791:
	ds_read_u16 v7, v6 offset:9216
	ds_read_u16 v8, v6 offset:9344
	ds_read_u16 v10, v6 offset:9472
	ds_read_u16 v11, v6 offset:9600
	v_add_u32_e32 v12, s6, v48
	s_addk_i32 s6, 0x900
	s_waitcnt lgkmcnt(2)
	v_lshlrev_b32_e32 v9, 16, v8
	v_lshlrev_b32_e32 v8, 16, v7
	s_waitcnt lgkmcnt(0)
	v_lshlrev_b32_e32 v11, 16, v11
	v_lshlrev_b32_e32 v10, 16, v10
	s_waitcnt vmcnt(3)
	v_pk_mul_f32 v[8:9], v[2:3], v[8:9]
	s_waitcnt vmcnt(1)
	v_pk_mul_f32 v[10:11], v[4:5], v[10:11]
	v_add_f32_e32 v7, v8, v9
	v_add_f32_e32 v7, v7, v10
	v_add_f32_e32 v7, v7, v11
	s_waitcnt vmcnt(0)
	v_add_f32_e32 v7, v0, v7
	v_cvt_pk_bf16_f32 v7, v7, s0
	ds_write_b16 v12, v7
	ds_read_u16 v7, v6 offset:9856
	ds_read_u16 v10, v6 offset:9984
	ds_read_u16 v8, v6 offset:9728
	ds_read_u16 v11, v6 offset:10112
	s_cmpk_eq_i32 s6, 0x2400
	s_waitcnt lgkmcnt(3)
	v_lshlrev_b32_e32 v9, 16, v7
	s_waitcnt lgkmcnt(2)
	v_lshlrev_b32_e32 v10, 16, v10
	s_waitcnt lgkmcnt(1)
	v_lshlrev_b32_e32 v8, 16, v8
	s_waitcnt lgkmcnt(0)
	v_lshlrev_b32_e32 v11, 16, v11
	v_pk_mul_f32 v[8:9], v[2:3], v[8:9]
	v_pk_mul_f32 v[10:11], v[4:5], v[10:11]
	v_add_f32_e32 v7, v8, v9
	v_add_f32_e32 v7, v7, v10
	v_add_f32_e32 v7, v7, v11
	v_add_f32_e32 v7, v0, v7
	v_cvt_pk_bf16_f32 v7, v7, s0
	ds_write_b16 v12, v7 offset:576
	ds_read_u16 v7, v6 offset:10368
	ds_read_u16 v10, v6 offset:10496
	ds_read_u16 v8, v6 offset:10240
	ds_read_u16 v11, v6 offset:10624
	s_waitcnt lgkmcnt(3)
	v_lshlrev_b32_e32 v9, 16, v7
	s_waitcnt lgkmcnt(2)
	v_lshlrev_b32_e32 v10, 16, v10
	s_waitcnt lgkmcnt(1)
	v_lshlrev_b32_e32 v8, 16, v8
	s_waitcnt lgkmcnt(0)
	v_lshlrev_b32_e32 v11, 16, v11
	v_pk_mul_f32 v[8:9], v[2:3], v[8:9]
	v_pk_mul_f32 v[10:11], v[4:5], v[10:11]
	v_add_f32_e32 v7, v8, v9
	v_add_f32_e32 v7, v7, v10
	v_add_f32_e32 v7, v7, v11
	v_add_f32_e32 v7, v0, v7
	v_cvt_pk_bf16_f32 v7, v7, s0
	ds_write_b16 v12, v7 offset:1152
	ds_read_u16 v7, v6 offset:10880
	ds_read_u16 v10, v6 offset:11008
	ds_read_u16 v8, v6 offset:10752
	ds_read_u16 v11, v6 offset:11136
	v_add_u32_e32 v6, 0x800, v6
	s_waitcnt lgkmcnt(3)
	v_lshlrev_b32_e32 v9, 16, v7
	s_waitcnt lgkmcnt(2)
	v_lshlrev_b32_e32 v10, 16, v10
	s_waitcnt lgkmcnt(1)
	v_lshlrev_b32_e32 v8, 16, v8
	s_waitcnt lgkmcnt(0)
	v_lshlrev_b32_e32 v11, 16, v11
	v_pk_mul_f32 v[8:9], v[2:3], v[8:9]
	v_pk_mul_f32 v[10:11], v[4:5], v[10:11]
	v_add_f32_e32 v7, v8, v9
	v_add_f32_e32 v7, v7, v10
	v_add_f32_e32 v7, v7, v11
	v_add_f32_e32 v7, v0, v7
	v_cvt_pk_bf16_f32 v7, v7, s0
	ds_write_b16 v12, v7 offset:1728
	s_cbranch_scc0 .LBB0_791
	s_lshl_b32 s6, s19, 12
	s_or_b32 s6, s10, s6
	s_mov_b32 s7, s11
	s_lshl_b64 s[12:13], s[6:7], 1
	v_lshl_add_u64 v[88:89], v[40:41], 0, s[12:13]
	s_waitcnt lgkmcnt(0)
	s_barrier
	v_lshl_add_u64 v[90:91], v[42:43], 0, s[12:13]
	global_load_dwordx4 v[2:5], v[88:89], off
	global_load_dwordx4 v[6:9], v[90:91], off
	ds_read_b128 v[10:13], v61
	ds_read_b128 v[54:57], v61 offset:32
	global_load_dwordx4 v[80:83], v[88:89], off offset:32
	global_load_dwordx4 v[84:87], v[90:91], off offset:32
	v_add_u32_e32 v58, s94, v62
	v_ashrrev_i32_e32 v59, 31, v58
	v_readlane_b32 s52, v252, 16
	v_readlane_b32 s53, v252, 17
	v_readlane_b32 s54, v252, 18
	v_readlane_b32 s55, v252, 19
	v_readlane_b32 s56, v252, 20
	v_readlane_b32 s57, v252, 21
	v_readlane_b32 s58, v252, 22
	v_readlane_b32 s59, v252, 23
	v_readlane_b32 s60, v252, 24
	v_readlane_b32 s61, v252, 25
	v_readlane_b32 s62, v252, 26
	v_readlane_b32 s63, v252, 27
	v_readlane_b32 s64, v252, 28
	v_readlane_b32 s65, v252, 29
	v_readlane_b32 s66, v252, 30
	v_readlane_b32 s67, v252, 31
	s_mov_b32 s14, 0x3f2aaaab
	s_mov_b32 s15, 0x3f317218
	s_mov_b32 s16, 0x7f800000
	s_mov_b32 s17, 0x33800000
	s_mov_b32 s20, 0xc1000000
	s_mov_b32 s19, 0xbe800000
	s_bitset1_b32 s12, 15
	v_lshl_add_u64 v[96:97], v[42:43], 0, s[12:13]
	s_waitcnt vmcnt(3) lgkmcnt(1)
	v_mfma_f32_32x32x16_bf16 v[18:33], v[10:13], v[2:5], 0
	s_waitcnt vmcnt(2)
	v_mfma_f32_32x32x16_bf16 v[2:17], v[10:13], v[6:9], 0
	s_waitcnt vmcnt(1) lgkmcnt(0)
	v_mfma_f32_32x32x16_bf16 v[18:33], v[54:57], v[80:83], v[18:33]
	s_waitcnt vmcnt(0)
	v_mfma_f32_32x32x16_bf16 v[2:17], v[54:57], v[84:87], v[2:17]
	ds_read_b128 v[54:57], v61 offset:64
	global_load_dwordx4 v[80:83], v[88:89], off offset:64
	global_load_dwordx4 v[84:87], v[90:91], off offset:64
	s_waitcnt vmcnt(1) lgkmcnt(0)
	v_mfma_f32_32x32x16_bf16 v[18:33], v[54:57], v[80:83], v[18:33]
	s_waitcnt vmcnt(0)
	v_mfma_f32_32x32x16_bf16 v[2:17], v[54:57], v[84:87], v[2:17]
	ds_read_b128 v[54:57], v61 offset:96
	global_load_dwordx4 v[80:83], v[88:89], off offset:96
	global_load_dwordx4 v[84:87], v[90:91], off offset:96
	s_waitcnt vmcnt(1) lgkmcnt(0)
	v_mfma_f32_32x32x16_bf16 v[18:33], v[54:57], v[80:83], v[18:33]
	s_waitcnt vmcnt(0)
	v_mfma_f32_32x32x16_bf16 v[2:17], v[54:57], v[84:87], v[2:17]
	v_lshlrev_b64 v[54:55], 2, v[58:59]
	v_lshl_add_u64 v[56:57], s[66:67], 0, v[54:55]
	v_readlane_b32 s52, v252, 32
	v_readlane_b32 s54, v252, 34
	v_readlane_b32 s55, v252, 35
	v_readlane_b32 s56, v252, 36
	v_readlane_b32 s57, v252, 37
	v_lshl_add_u64 v[58:59], s[54:55], 0, v[54:55]
	global_load_dword v81, v[58:59], off
	v_lshl_add_u64 v[54:55], s[56:57], 0, v[54:55]
	global_load_dword v0, v[54:55], off
	global_load_dword v51, v[56:57], off
	v_readlane_b32 s53, v252, 33
	v_readlane_b32 s58, v252, 38
	v_readlane_b32 s59, v252, 39
	v_readlane_b32 s60, v252, 40
	v_readlane_b32 s61, v252, 41
	v_readlane_b32 s62, v252, 42
	v_readlane_b32 s63, v252, 43
	v_readlane_b32 s64, v252, 44
	v_readlane_b32 s65, v252, 45
	v_readlane_b32 s66, v252, 46
	v_readlane_b32 s67, v252, 47
	s_waitcnt vmcnt(2)
	v_add_f32_e32 v2, v2, v81
	v_mul_f32_e32 v2, 0xbfb8aa3b, v2
	s_waitcnt vmcnt(1)
; DI float bf2f(u16 v) { return __uint_as_float(((unsigned)v) << 16); }
; DI int crow(int i, int h) { return (i & 3) + 8 * (i >> 2) + 4 * h; }
; DI void lru_item(const Params& p, int l, int b, int chunk, int blk, bool fin, char* smem, int tid) {
;     ...
;       const int pi = (l * 2 + dir) * 256 + c0 + chn;
;       const float b_a = p.ba[pi], b_x = p.bx[pi], lam = p.lam[pi];
;       const float sp = log1pf(__expf(-lam));
; #pragma unroll
;       for (int i = 0; i < 16; i++) {
;         const int tok = tb * 32 + crow(i, h);
;         const float rr = __builtin_amdgcn_rcpf(1.f + __expf(-(ga[i] + b_a))), ii = __builtin_amdgcn_rcpf(1.f + __expf(-(gx[i] + b_x)));
;         const float la = -8.f * rr * sp;
;         const float a = __expf(la);
;         const float x2 = 2.f * la;
;         const float ser = -x2 * (1.f + x2 * (0.5f + x2 * (0.16666667f + x2 * (0.041666668f + x2 * 0.0083333338f))));
;         const float om = (x2 > -0.25f) ? ser : (1.f - a * a);
;         const float u = __builtin_amdgcn_sqrtf(fmaxf(om, 0.f)) * ii * bf2f(xcb[tok][chn]);
;         au[(dir * 64 + tok) * 64 + chn] = make_float2(a, u);
	v_mul_f32_e32 v0, 0xbfb8aa3b, v0
	v_exp_f32_e32 v0, v0
	v_exp_f32_e32 v2, v2
	s_waitcnt vmcnt(0)
	v_add_f32_e32 v18, v18, v51
	v_mul_f32_e32 v18, 0xbfb8aa3b, v18
	v_add_f32_e32 v80, 1.0, v0
	v_add_f32_e32 v82, -1.0, v80
	v_sub_f32_e32 v83, v82, v80
	v_add_f32_e32 v83, 1.0, v83
	v_sub_f32_e32 v82, v0, v82
	v_add_f32_e32 v84, v82, v83
	v_frexp_mant_f32_e32 v82, v80
	v_cmp_gt_f32_e64 s[6:7], s14, v82
	v_cvt_f64_f32_e32 v[82:83], v80
	v_frexp_exp_i32_f64_e32 v82, v[82:83]
	v_subbrev_co_u32_e64 v90, s[6:7], 0, v82, s[6:7]
	v_sub_u32_e32 v82, 0, v90
	v_ldexp_f32 v80, v80, v82
	v_ldexp_f32 v82, v84, v82
	v_add_f32_e32 v84, -1.0, v80
	v_add_f32_e32 v83, 1.0, v84
	v_sub_f32_e32 v83, v80, v83
	v_add_f32_e32 v85, v82, v83
	v_add_f32_e32 v83, 1.0, v80
	v_add_f32_e32 v86, -1.0, v83
	v_sub_f32_e32 v80, v80, v86
	v_add_f32_e32 v80, v82, v80
	v_add_f32_e32 v91, v83, v80
	v_rcp_f32_e32 v92, v91
	v_sub_f32_e32 v82, v91, v83
	v_add_f32_e32 v83, v84, v85
	v_sub_f32_e32 v80, v80, v82
	v_mul_f32_e32 v94, v83, v92
	v_sub_f32_e32 v82, v83, v84
	v_mul_f32_e32 v84, v91, v94
	v_fma_f32 v86, v94, v91, -v84
	v_fmac_f32_e32 v86, v94, v80
	v_sub_f32_e32 v93, v85, v82
	v_add_f32_e32 v82, v84, v86
	v_sub_f32_e32 v85, v83, v82
	v_pk_add_f32 v[88:89], v[82:83], v[84:85] neg_lo:[0,1] neg_hi:[0,1]
	v_mov_b32_e32 v87, v82
	v_pk_add_f32 v[82:83], v[88:89], v[86:87] neg_lo:[0,1] neg_hi:[0,1]
	v_cmp_neq_f32_e64 s[6:7], s16, v0
	v_add_f32_e32 v83, v93, v83
	v_add_f32_e32 v82, v82, v83
	v_add_f32_e32 v83, v85, v82
	v_mul_f32_e32 v93, v92, v83
	v_mul_f32_e32 v84, v91, v93
	v_fma_f32 v86, v93, v91, -v84
	v_fmac_f32_e32 v86, v93, v80
	v_sub_f32_e32 v80, v85, v83
	v_add_f32_e32 v80, v82, v80
	v_add_f32_e32 v82, v84, v86
	v_sub_f32_e32 v85, v83, v82
	v_pk_add_f32 v[88:89], v[82:83], v[84:85] neg_lo:[0,1] neg_hi:[0,1]
	v_mov_b32_e32 v87, v82
	v_pk_add_f32 v[82:83], v[88:89], v[86:87] neg_lo:[0,1] neg_hi:[0,1]
	v_add_f32_e32 v2, 1.0, v2
	v_add_f32_e32 v80, v80, v83
	v_add_f32_e32 v80, v82, v80
	v_add_f32_e32 v83, v94, v93
	v_add_f32_e32 v80, v85, v80
	v_sub_f32_e32 v82, v83, v94
	v_mul_f32_e32 v80, v92, v80
	v_sub_f32_e32 v82, v93, v82
	v_add_f32_e32 v80, v82, v80
	v_add_f32_e32 v84, v83, v80
	v_mul_f32_e32 v86, v84, v84
	v_fmamk_f32 v82, v86, 0x3e9b6dac, v211
	v_fmaak_f32 v153, v86, v82, 0x3f2aaada
	v_cvt_f32_i32_e32 v82, v90
	v_sub_f32_e32 v83, v84, v83
	v_sub_f32_e32 v80, v80, v83
	v_mul_f32_e32 v83, v84, v86
	v_pk_mul_f32 v[86:87], v[82:83], v[152:153]
	v_ldexp_f32 v85, v84, 1
	v_fma_f32 v84, v82, s15, -v86
	v_fmac_f32_e32 v84, 0xb102e308, v82
	v_pk_add_f32 v[82:83], v[86:87], v[84:85]
	v_ldexp_f32 v80, v80, 1
	v_sub_f32_e32 v85, v83, v85
	v_sub_f32_e32 v85, v87, v85
	v_add_f32_e32 v89, v80, v85
	v_mov_b32_e32 v88, v86
	v_pk_add_f32 v[86:87], v[82:83], v[86:87] neg_lo:[0,1] neg_hi:[0,1]
	v_pk_add_f32 v[90:91], v[82:83], v[88:89]
	v_mov_b32_e32 v85, v82
	v_mov_b32_e32 v87, v91
	v_pk_add_f32 v[92:93], v[84:85], v[86:87] neg_lo:[0,1] neg_hi:[0,1]
	v_pk_add_f32 v[84:85], v[84:85], v[86:87]
	v_mov_b32_e32 v88, v89
	v_pk_add_f32 v[86:87], v[84:85], v[82:83] op_sel:[1,0] op_sel_hi:[0,1] neg_lo:[0,1] neg_hi:[0,1]
	v_pk_add_f32 v[94:95], v[90:91], v[86:87] op_sel_hi:[1,0] neg_lo:[0,1] neg_hi:[0,1]
	v_mov_b32_e32 v90, v91
	v_mov_b32_e32 v91, v85
	v_pk_mov_b32 v[86:87], v[82:83], v[86:87] op_sel:[1,0]
	v_mov_b32_e32 v89, v82
	v_pk_add_f32 v[86:87], v[90:91], v[86:87] neg_lo:[0,1] neg_hi:[0,1]
	v_mov_b32_e32 v94, v92
	v_pk_add_f32 v[82:83], v[88:89], v[86:87] neg_lo:[0,1] neg_hi:[0,1]
	v_mov_b32_e32 v93, v85
	v_pk_add_f32 v[86:87], v[94:95], v[82:83]
	v_exp_f32_e32 v18, v18
	v_pk_add_f32 v[88:89], v[86:87], v[86:87] op_sel:[0,1] op_sel_hi:[1,0]
	v_lshl_add_u64 v[94:95], v[40:41], 0, s[12:13]
	v_pk_add_f32 v[84:85], v[84:85], v[88:89] op_sel:[1,0] op_sel_hi:[0,1]
	v_mov_b32_e32 v87, v84
	v_pk_add_f32 v[90:91], v[86:87], v[92:93] neg_lo:[0,1] neg_hi:[0,1]
	v_mov_b32_e32 v83, v88
	v_sub_f32_e32 v80, v86, v90
	v_pk_add_f32 v[82:83], v[82:83], v[90:91] neg_lo:[0,1] neg_hi:[0,1]
	v_sub_f32_e32 v80, v92, v80
	v_add_f32_e32 v80, v82, v80
	v_add_f32_e32 v80, v80, v83
	v_add_f32_e32 v80, v84, v80
	v_cndmask_b32_e64 v80, v217, v80, s[6:7]
	v_cmp_ngt_f32_e64 s[6:7], -1.0, v0
	v_add_f32_e32 v18, 1.0, v18
	v_rcp_f32_e32 v83, v18
	v_cndmask_b32_e64 v80, v218, v80, s[6:7]
	v_cmp_neq_f32_e64 s[6:7], -1.0, v0
	s_nop 1
	v_cndmask_b32_e64 v80, v219, v80, s[6:7]
	v_cmp_lt_f32_e64 s[6:7], |v0|, s17
	s_nop 1
	v_cndmask_b32_e64 v0, v80, v0, s[6:7]
	v_rcp_f32_e32 v80, v2
	ds_read_u16 v2, v37
	s_waitcnt lgkmcnt(0)
	v_lshlrev_b32_e32 v84, 16, v2
	v_add_f32_e32 v2, v19, v51
	v_mul_f32_e32 v2, 0xbfb8aa3b, v2
	v_exp_f32_e32 v2, v2
	s_nop 0
	v_add_f32_e32 v2, 1.0, v2
	v_rcp_f32_e32 v82, v2
	v_add_f32_e32 v2, v3, v81
	v_mul_f32_e32 v2, 0xbfb8aa3b, v2
	v_exp_f32_e32 v2, v2
	s_nop 0
	v_add_f32_e32 v2, 1.0, v2
	v_rcp_f32_e32 v85, v2
	v_pk_mul_f32 v[2:3], v[82:83], s[20:21] op_sel_hi:[1,0]
	s_nop 0
	v_pk_mul_f32 v[2:3], v[2:3], v[0:1] op_sel_hi:[1,0]
	s_nop 0
	v_mul_f32_e32 v18, 0x3fb8aa3b, v3
	v_pk_add_f32 v[82:83], v[2:3], v[2:3]
	v_exp_f32_e32 v18, v18
	v_fmamk_f32 v3, v83, 0x3c088889, v212
	v_fmaak_f32 v3, v83, v3, 0x3e2aaaab
	v_fma_f32 v3, v83, v3, 0.5
	v_fma_f32 v3, v83, v3, 1.0
	v_mul_f32_e64 v3, v3, -v83
	v_fma_f32 v19, -v18, v18, 1.0
	v_cmp_lt_f32_e64 s[8:9], s19, v83
	v_mul_f32_e32 v2, 0x3fb8aa3b, v2
	v_exp_f32_e32 v2, v2
	v_cndmask_b32_e64 v3, v19, v3, s[8:9]
	v_max_f32_e32 v3, 0, v3
	v_sqrt_f32_e32 v3, v3
	v_cmp_lt_f32_e64 s[6:7], s19, v82
	v_mul_f32_e32 v3, v80, v3
	v_mul_f32_e32 v19, v3, v84
	v_fmamk_f32 v3, v82, 0x3c088889, v212
	v_fmaak_f32 v3, v82, v3, 0x3e2aaaab
	v_fma_f32 v3, v82, v3, 0.5
	v_add_u32_e32 v80, v36, v63
	v_fma_f32 v3, v82, v3, 1.0
	ds_write_b64 v80, v[18:19] offset:9216
	v_mul_f32_e64 v3, v3, -v82
	v_fma_f32 v18, -v2, v2, 1.0
	v_cndmask_b32_e64 v3, v18, v3, s[6:7]
	v_max_f32_e32 v3, 0, v3
	ds_read_u16 v18, v37 offset:144
	v_sqrt_f32_e32 v3, v3
	s_waitcnt lgkmcnt(0)
; DI float bf2f(u16 v) { return __uint_as_float(((unsigned)v) << 16); }
; DI int crow(int i, int h) { return (i & 3) + 8 * (i >> 2) + 4 * h; }
; DI void lru_item(const Params& p, int l, int b, int chunk, int blk, bool fin, char* smem, int tid) {
;     ...
;       for (int i = 0; i < 16; i++) {
;         const int tok = tb * 32 + crow(i, h);
;         const float rr = __builtin_amdgcn_rcpf(1.f + __expf(-(ga[i] + b_a))), ii = __builtin_amdgcn_rcpf(1.f + __expf(-(gx[i] + b_x)));
;         const float la = -8.f * rr * sp;
;         const float a = __expf(la);
;         const float x2 = 2.f * la;
;         const float ser = -x2 * (1.f + x2 * (0.5f + x2 * (0.16666667f + x2 * (0.041666668f + x2 * 0.0083333338f))));
;         const float om = (x2 > -0.25f) ? ser : (1.f - a * a);
;         const float u = __builtin_amdgcn_sqrtf(fmaxf(om, 0.f)) * ii * bf2f(xcb[tok][chn]);
;         au[(dir * 64 + tok) * 64 + chn] = make_float2(a, u);
	v_lshlrev_b32_e32 v18, 16, v18
	v_mul_f32_e32 v3, v85, v3
	v_mul_f32_e32 v3, v3, v18
	ds_write_b64 v49, v[2:3] offset:9216
	v_add_f32_e32 v2, v20, v51
	v_mul_f32_e32 v2, 0xbfb8aa3b, v2
	v_exp_f32_e32 v2, v2
	s_nop 0
	v_add_f32_e32 v2, 1.0, v2
	v_rcp_f32_e32 v3, v2
	v_add_f32_e32 v2, v4, v81
	v_mul_f32_e32 v2, 0xbfb8aa3b, v2
	v_exp_f32_e32 v2, v2
	v_add_f32_e32 v4, v5, v81
	v_mul_f32_e32 v4, 0xbfb8aa3b, v4
	v_exp_f32_e32 v4, v4
	v_add_f32_e32 v2, 1.0, v2
	v_rcp_f32_e32 v20, v2
	ds_read_u16 v2, v37 offset:288
	v_add_f32_e32 v4, 1.0, v4
	s_waitcnt lgkmcnt(0)
	v_lshlrev_b32_e32 v82, 16, v2
	v_add_f32_e32 v2, v21, v51
	v_mul_f32_e32 v2, 0xbfb8aa3b, v2
	v_exp_f32_e32 v2, v2
	v_rcp_f32_e32 v21, v4
	v_add_f32_e32 v2, 1.0, v2
	v_rcp_f32_e32 v2, v2
	s_nop 0
	v_pk_mul_f32 v[2:3], v[2:3], s[20:21] op_sel_hi:[1,0]
	s_nop 0
	v_pk_mul_f32 v[2:3], v[2:3], v[0:1] op_sel_hi:[1,0]
	s_nop 0
	v_mul_f32_e32 v4, 0x3fb8aa3b, v3
	v_pk_add_f32 v[18:19], v[2:3], v[2:3]
	v_exp_f32_e32 v4, v4
	v_fmamk_f32 v3, v19, 0x3c088889, v212
	v_fmaak_f32 v3, v19, v3, 0x3e2aaaab
	v_fma_f32 v3, v19, v3, 0.5
	v_fma_f32 v3, v19, v3, 1.0
	v_mul_f32_e64 v3, v3, -v19
	v_fma_f32 v5, -v4, v4, 1.0
	v_cmp_lt_f32_e64 s[8:9], s19, v19
	v_mul_f32_e32 v2, 0x3fb8aa3b, v2
	v_exp_f32_e32 v2, v2
	v_cndmask_b32_e64 v3, v5, v3, s[8:9]
	v_max_f32_e32 v3, 0, v3
	v_sqrt_f32_e32 v3, v3
	v_cmp_lt_f32_e64 s[6:7], s19, v18
	v_mul_f32_e32 v3, v20, v3
	v_mul_f32_e32 v5, v3, v82
	v_fmamk_f32 v3, v18, 0x3c088889, v212
	v_fmaak_f32 v3, v18, v3, 0x3e2aaaab
	v_fma_f32 v3, v18, v3, 0.5
	v_fma_f32 v3, v18, v3, 1.0
	ds_write_b64 v66, v[4:5] offset:9216
	v_mul_f32_e64 v3, v3, -v18
	v_fma_f32 v4, -v2, v2, 1.0
	v_cndmask_b32_e64 v3, v4, v3, s[6:7]
	v_max_f32_e32 v3, 0, v3
	ds_read_u16 v4, v37 offset:432
	v_sqrt_f32_e32 v3, v3
	s_waitcnt lgkmcnt(0)
	v_lshlrev_b32_e32 v4, 16, v4
	v_mul_f32_e32 v3, v21, v3
	v_mul_f32_e32 v3, v3, v4
	ds_write_b64 v67, v[2:3] offset:9216
	v_add_f32_e32 v2, v22, v51
	v_mul_f32_e32 v2, 0xbfb8aa3b, v2
	v_exp_f32_e32 v2, v2
	v_add_f32_e32 v4, v7, v81
	v_mul_f32_e32 v4, 0xbfb8aa3b, v4
	v_exp_f32_e32 v4, v4
	v_add_f32_e32 v2, 1.0, v2
	v_rcp_f32_e32 v3, v2
	v_add_f32_e32 v2, v6, v81
	v_mul_f32_e32 v2, 0xbfb8aa3b, v2
	v_exp_f32_e32 v2, v2
	v_add_f32_e32 v4, 1.0, v4
	v_rcp_f32_e32 v19, v4
	v_add_f32_e32 v2, 1.0, v2
	v_rcp_f32_e32 v5, v2
	ds_read_u16 v2, v37 offset:1152
	s_waitcnt lgkmcnt(0)
	v_lshlrev_b32_e32 v18, 16, v2
	v_add_f32_e32 v2, v23, v51
	v_mul_f32_e32 v2, 0xbfb8aa3b, v2
	v_exp_f32_e32 v2, v2
	s_nop 0
	v_add_f32_e32 v2, 1.0, v2
	v_rcp_f32_e32 v2, v2
	s_nop 0
	v_pk_mul_f32 v[2:3], v[2:3], s[20:21] op_sel_hi:[1,0]
	s_nop 0
	v_pk_mul_f32 v[2:3], v[2:3], v[0:1] op_sel_hi:[1,0]
	s_nop 0
	v_mul_f32_e32 v4, 0x3fb8aa3b, v3
	v_pk_add_f32 v[6:7], v[2:3], v[2:3]
	v_exp_f32_e32 v4, v4
	v_fmamk_f32 v3, v7, 0x3c088889, v212
	v_fmaak_f32 v3, v7, v3, 0x3e2aaaab
	v_fma_f32 v3, v7, v3, 0.5
	v_fma_f32 v3, v7, v3, 1.0
	v_mul_f32_e64 v3, v3, -v7
	v_fma_f32 v20, -v4, v4, 1.0
	v_cmp_lt_f32_e64 s[8:9], s19, v7
	v_mul_f32_e32 v2, 0x3fb8aa3b, v2
	v_exp_f32_e32 v2, v2
	v_cndmask_b32_e64 v3, v20, v3, s[8:9]
	v_max_f32_e32 v3, 0, v3
	v_sqrt_f32_e32 v3, v3
	v_cmp_lt_f32_e64 s[6:7], s19, v6
	v_mul_f32_e32 v3, v5, v3
	v_mul_f32_e32 v5, v3, v18
	v_fmamk_f32 v3, v6, 0x3c088889, v212
	v_fmaak_f32 v3, v6, v3, 0x3e2aaaab
	v_fma_f32 v3, v6, v3, 0.5
	v_fma_f32 v3, v6, v3, 1.0
	ds_write_b64 v68, v[4:5] offset:9216
	v_mul_f32_e64 v3, v3, -v6
	v_fma_f32 v4, -v2, v2, 1.0
	v_cndmask_b32_e64 v3, v4, v3, s[6:7]
	v_max_f32_e32 v3, 0, v3
	ds_read_u16 v4, v37 offset:1296
	v_sqrt_f32_e32 v3, v3
	s_waitcnt lgkmcnt(0)
	v_lshlrev_b32_e32 v4, 16, v4
	v_mul_f32_e32 v3, v19, v3
	v_mul_f32_e32 v3, v3, v4
	ds_write_b64 v69, v[2:3] offset:9216
	v_add_f32_e32 v2, v24, v51
	v_mul_f32_e32 v2, 0xbfb8aa3b, v2
	v_exp_f32_e32 v2, v2
	v_add_f32_e32 v4, v9, v81
	v_mul_f32_e32 v4, 0xbfb8aa3b, v4
	v_exp_f32_e32 v4, v4
	v_add_f32_e32 v2, 1.0, v2
	v_rcp_f32_e32 v3, v2
	v_add_f32_e32 v2, v8, v81
	v_mul_f32_e32 v2, 0xbfb8aa3b, v2
	v_exp_f32_e32 v2, v2
	v_add_f32_e32 v4, 1.0, v4
	v_rcp_f32_e32 v9, v4
	v_add_f32_e32 v2, 1.0, v2
	v_rcp_f32_e32 v5, v2
	ds_read_u16 v2, v37 offset:1440
	s_waitcnt lgkmcnt(0)
	v_lshlrev_b32_e32 v8, 16, v2
	v_add_f32_e32 v2, v25, v51
	v_mul_f32_e32 v2, 0xbfb8aa3b, v2
	v_exp_f32_e32 v2, v2
	s_nop 0
	v_add_f32_e32 v2, 1.0, v2
	v_rcp_f32_e32 v2, v2
	s_nop 0
	v_pk_mul_f32 v[2:3], v[2:3], s[20:21] op_sel_hi:[1,0]
	s_nop 0
	v_pk_mul_f32 v[2:3], v[2:3], v[0:1] op_sel_hi:[1,0]
	s_nop 0
	v_mul_f32_e32 v4, 0x3fb8aa3b, v3
	v_pk_add_f32 v[6:7], v[2:3], v[2:3]
	v_exp_f32_e32 v4, v4
	v_fmamk_f32 v3, v7, 0x3c088889, v212
	v_fmaak_f32 v3, v7, v3, 0x3e2aaaab
	v_fma_f32 v3, v7, v3, 0.5
	v_fma_f32 v3, v7, v3, 1.0
	v_mul_f32_e64 v3, v3, -v7
	v_fma_f32 v18, -v4, v4, 1.0
	v_cmp_lt_f32_e64 s[8:9], s19, v7
	v_mul_f32_e32 v2, 0x3fb8aa3b, v2
	v_exp_f32_e32 v2, v2
	v_cndmask_b32_e64 v3, v18, v3, s[8:9]
	v_max_f32_e32 v3, 0, v3
	v_sqrt_f32_e32 v3, v3
	v_cmp_lt_f32_e64 s[6:7], s19, v6
	v_mul_f32_e32 v3, v5, v3
	v_mul_f32_e32 v5, v3, v8
	v_fmamk_f32 v3, v6, 0x3c088889, v212
	v_fmaak_f32 v3, v6, v3, 0x3e2aaaab
	v_fma_f32 v3, v6, v3, 0.5
	v_fma_f32 v3, v6, v3, 1.0
	ds_write_b64 v70, v[4:5] offset:9216
	v_mul_f32_e64 v3, v3, -v6
	v_fma_f32 v4, -v2, v2, 1.0
	v_cndmask_b32_e64 v3, v4, v3, s[6:7]
	v_max_f32_e32 v3, 0, v3
	ds_read_u16 v4, v37 offset:1584
	v_sqrt_f32_e32 v3, v3
	s_waitcnt lgkmcnt(0)
; DI float bf2f(u16 v) { return __uint_as_float(((unsigned)v) << 16); }
; DI int crow(int i, int h) { return (i & 3) + 8 * (i >> 2) + 4 * h; }
; DI void lru_item(const Params& p, int l, int b, int chunk, int blk, bool fin, char* smem, int tid) {
;     ...
;       for (int i = 0; i < 16; i++) {
;         const int tok = tb * 32 + crow(i, h);
;         const float rr = __builtin_amdgcn_rcpf(1.f + __expf(-(ga[i] + b_a))), ii = __builtin_amdgcn_rcpf(1.f + __expf(-(gx[i] + b_x)));
;         const float la = -8.f * rr * sp;
;         const float a = __expf(la);
;         const float x2 = 2.f * la;
;         const float ser = -x2 * (1.f + x2 * (0.5f + x2 * (0.16666667f + x2 * (0.041666668f + x2 * 0.0083333338f))));
;         const float om = (x2 > -0.25f) ? ser : (1.f - a * a);
;         const float u = __builtin_amdgcn_sqrtf(fmaxf(om, 0.f)) * ii * bf2f(xcb[tok][chn]);
;         au[(dir * 64 + tok) * 64 + chn] = make_float2(a, u);
	v_lshlrev_b32_e32 v4, 16, v4
	v_mul_f32_e32 v3, v9, v3
	v_mul_f32_e32 v3, v3, v4
	ds_write_b64 v71, v[2:3] offset:9216
	v_add_f32_e32 v2, v26, v51
	v_mul_f32_e32 v2, 0xbfb8aa3b, v2
	v_exp_f32_e32 v2, v2
	v_add_f32_e32 v4, v11, v81
	v_mul_f32_e32 v4, 0xbfb8aa3b, v4
	v_exp_f32_e32 v4, v4
	v_add_f32_e32 v2, 1.0, v2
	v_rcp_f32_e32 v3, v2
	v_add_f32_e32 v2, v10, v81
	v_mul_f32_e32 v2, 0xbfb8aa3b, v2
	v_exp_f32_e32 v2, v2
	v_add_f32_e32 v4, 1.0, v4
	v_rcp_f32_e32 v9, v4
	v_add_f32_e32 v2, 1.0, v2
	v_rcp_f32_e32 v5, v2
	ds_read_u16 v2, v37 offset:2304
	s_waitcnt lgkmcnt(0)
	v_lshlrev_b32_e32 v8, 16, v2
	v_add_f32_e32 v2, v27, v51
	v_mul_f32_e32 v2, 0xbfb8aa3b, v2
	v_exp_f32_e32 v2, v2
	s_nop 0
	v_add_f32_e32 v2, 1.0, v2
	v_rcp_f32_e32 v2, v2
	s_nop 0
	v_pk_mul_f32 v[2:3], v[2:3], s[20:21] op_sel_hi:[1,0]
	s_nop 0
	v_pk_mul_f32 v[2:3], v[2:3], v[0:1] op_sel_hi:[1,0]
	s_nop 0
	v_mul_f32_e32 v4, 0x3fb8aa3b, v3
	v_pk_add_f32 v[6:7], v[2:3], v[2:3]
	v_exp_f32_e32 v4, v4
	v_fmamk_f32 v3, v7, 0x3c088889, v212
	v_fmaak_f32 v3, v7, v3, 0x3e2aaaab
	v_fma_f32 v3, v7, v3, 0.5
	v_fma_f32 v3, v7, v3, 1.0
	v_mul_f32_e64 v3, v3, -v7
	v_fma_f32 v10, -v4, v4, 1.0
	v_cmp_lt_f32_e64 s[8:9], s19, v7
	v_mul_f32_e32 v2, 0x3fb8aa3b, v2
	v_exp_f32_e32 v2, v2
	v_cndmask_b32_e64 v3, v10, v3, s[8:9]
	v_max_f32_e32 v3, 0, v3
	v_sqrt_f32_e32 v3, v3
	v_cmp_lt_f32_e64 s[6:7], s19, v6
	v_mul_f32_e32 v3, v5, v3
	v_mul_f32_e32 v5, v3, v8
	v_fmamk_f32 v3, v6, 0x3c088889, v212
	v_fmaak_f32 v3, v6, v3, 0x3e2aaaab
	v_fma_f32 v3, v6, v3, 0.5
	v_fma_f32 v3, v6, v3, 1.0
	ds_write_b64 v72, v[4:5] offset:9216
	v_mul_f32_e64 v3, v3, -v6
	v_fma_f32 v4, -v2, v2, 1.0
	v_cndmask_b32_e64 v3, v4, v3, s[6:7]
	v_max_f32_e32 v3, 0, v3
	ds_read_u16 v4, v37 offset:2448
	v_sqrt_f32_e32 v3, v3
	s_waitcnt lgkmcnt(0)
	v_lshlrev_b32_e32 v4, 16, v4
	v_mul_f32_e32 v3, v9, v3
	v_mul_f32_e32 v3, v3, v4
	ds_write_b64 v73, v[2:3] offset:9216
	v_add_f32_e32 v2, v28, v51
	v_mul_f32_e32 v2, 0xbfb8aa3b, v2
	v_exp_f32_e32 v2, v2
	v_add_f32_e32 v4, v13, v81
	v_mul_f32_e32 v4, 0xbfb8aa3b, v4
	v_exp_f32_e32 v4, v4
	v_add_f32_e32 v2, 1.0, v2
	v_rcp_f32_e32 v3, v2
	v_add_f32_e32 v2, v12, v81
	v_mul_f32_e32 v2, 0xbfb8aa3b, v2
	v_exp_f32_e32 v2, v2
	v_add_f32_e32 v4, 1.0, v4
	v_rcp_f32_e32 v9, v4
	v_add_f32_e32 v2, 1.0, v2
	v_rcp_f32_e32 v5, v2
	ds_read_u16 v2, v37 offset:2592
	s_waitcnt lgkmcnt(0)
	v_lshlrev_b32_e32 v8, 16, v2
	v_add_f32_e32 v2, v29, v51
	v_mul_f32_e32 v2, 0xbfb8aa3b, v2
	v_exp_f32_e32 v2, v2
	s_nop 0
	v_add_f32_e32 v2, 1.0, v2
	v_rcp_f32_e32 v2, v2
	s_nop 0
	v_pk_mul_f32 v[2:3], v[2:3], s[20:21] op_sel_hi:[1,0]
	s_nop 0
	v_pk_mul_f32 v[2:3], v[2:3], v[0:1] op_sel_hi:[1,0]
	s_nop 0
	v_mul_f32_e32 v4, 0x3fb8aa3b, v3
	v_pk_add_f32 v[6:7], v[2:3], v[2:3]
	v_exp_f32_e32 v4, v4
	v_fmamk_f32 v3, v7, 0x3c088889, v212
	v_fmaak_f32 v3, v7, v3, 0x3e2aaaab
	v_fma_f32 v3, v7, v3, 0.5
	v_fma_f32 v3, v7, v3, 1.0
	v_mul_f32_e64 v3, v3, -v7
	v_fma_f32 v10, -v4, v4, 1.0
	v_cmp_lt_f32_e64 s[8:9], s19, v7
	v_mul_f32_e32 v2, 0x3fb8aa3b, v2
	v_exp_f32_e32 v2, v2
	v_cndmask_b32_e64 v3, v10, v3, s[8:9]
	v_max_f32_e32 v3, 0, v3
	v_sqrt_f32_e32 v3, v3
	v_cmp_lt_f32_e64 s[6:7], s19, v6
	v_mul_f32_e32 v3, v5, v3
	v_mul_f32_e32 v5, v3, v8
	v_fmamk_f32 v3, v6, 0x3c088889, v212
	v_fmaak_f32 v3, v6, v3, 0x3e2aaaab
	v_fma_f32 v3, v6, v3, 0.5
	v_fma_f32 v3, v6, v3, 1.0
	ds_write_b64 v74, v[4:5] offset:9216
	v_mul_f32_e64 v3, v3, -v6
	v_fma_f32 v4, -v2, v2, 1.0
	v_cndmask_b32_e64 v3, v4, v3, s[6:7]
	v_max_f32_e32 v3, 0, v3
	ds_read_u16 v4, v37 offset:2736
	v_sqrt_f32_e32 v3, v3
	s_waitcnt lgkmcnt(0)
	v_lshlrev_b32_e32 v4, 16, v4
	v_mul_f32_e32 v3, v9, v3
	v_mul_f32_e32 v3, v3, v4
	ds_write_b64 v75, v[2:3] offset:9216
	v_add_f32_e32 v2, v30, v51
	v_mul_f32_e32 v2, 0xbfb8aa3b, v2
	v_exp_f32_e32 v2, v2
	v_add_f32_e32 v4, v15, v81
	v_mul_f32_e32 v4, 0xbfb8aa3b, v4
	v_exp_f32_e32 v4, v4
	v_add_f32_e32 v2, 1.0, v2
	v_rcp_f32_e32 v3, v2
	v_add_f32_e32 v2, v14, v81
	v_mul_f32_e32 v2, 0xbfb8aa3b, v2
	v_exp_f32_e32 v2, v2
	v_add_f32_e32 v4, 1.0, v4
	v_rcp_f32_e32 v9, v4
	v_add_f32_e32 v2, 1.0, v2
	v_rcp_f32_e32 v5, v2
	ds_read_u16 v2, v37 offset:3456
	s_waitcnt lgkmcnt(0)
	v_lshlrev_b32_e32 v8, 16, v2
	v_add_f32_e32 v2, v31, v51
	v_mul_f32_e32 v2, 0xbfb8aa3b, v2
	v_exp_f32_e32 v2, v2
	s_nop 0
	v_add_f32_e32 v2, 1.0, v2
	v_rcp_f32_e32 v2, v2
	s_nop 0
	v_pk_mul_f32 v[2:3], v[2:3], s[20:21] op_sel_hi:[1,0]
	s_nop 0
	v_pk_mul_f32 v[2:3], v[2:3], v[0:1] op_sel_hi:[1,0]
	s_nop 0
	v_mul_f32_e32 v4, 0x3fb8aa3b, v3
	v_pk_add_f32 v[6:7], v[2:3], v[2:3]
	v_exp_f32_e32 v4, v4
	v_fmamk_f32 v3, v7, 0x3c088889, v212
	v_fmaak_f32 v3, v7, v3, 0x3e2aaaab
	v_fma_f32 v3, v7, v3, 0.5
	v_fma_f32 v3, v7, v3, 1.0
	v_mul_f32_e64 v3, v3, -v7
	v_fma_f32 v10, -v4, v4, 1.0
	v_cmp_lt_f32_e64 s[8:9], s19, v7
	v_mul_f32_e32 v2, 0x3fb8aa3b, v2
	v_exp_f32_e32 v2, v2
	v_cndmask_b32_e64 v3, v10, v3, s[8:9]
	v_max_f32_e32 v3, 0, v3
	v_sqrt_f32_e32 v3, v3
	v_cmp_lt_f32_e64 s[6:7], s19, v6
	v_mul_f32_e32 v3, v5, v3
	v_mul_f32_e32 v5, v3, v8
	v_fmamk_f32 v3, v6, 0x3c088889, v212
	v_fmaak_f32 v3, v6, v3, 0x3e2aaaab
	v_fma_f32 v3, v6, v3, 0.5
	v_fma_f32 v3, v6, v3, 1.0
	ds_write_b64 v76, v[4:5] offset:9216
	v_mul_f32_e64 v3, v3, -v6
	v_fma_f32 v4, -v2, v2, 1.0
	v_cndmask_b32_e64 v3, v4, v3, s[6:7]
	v_max_f32_e32 v3, 0, v3
	ds_read_u16 v4, v37 offset:3600
	v_sqrt_f32_e32 v3, v3
	s_waitcnt lgkmcnt(0)
	v_lshlrev_b32_e32 v4, 16, v4
	v_mul_f32_e32 v3, v9, v3
	v_mul_f32_e32 v3, v3, v4
	ds_write_b64 v77, v[2:3] offset:9216
	v_add_f32_e32 v2, v32, v51
	v_mul_f32_e32 v2, 0xbfb8aa3b, v2
	v_exp_f32_e32 v2, v2
	v_add_f32_e32 v4, v17, v81
	v_mul_f32_e32 v4, 0xbfb8aa3b, v4
	v_exp_f32_e32 v4, v4
	v_add_f32_e32 v2, 1.0, v2
	v_rcp_f32_e32 v3, v2
	v_add_f32_e32 v2, v16, v81
	v_mul_f32_e32 v2, 0xbfb8aa3b, v2
	v_exp_f32_e32 v2, v2
	v_add_f32_e32 v4, 1.0, v4
	v_rcp_f32_e32 v9, v4
	v_add_f32_e32 v2, 1.0, v2
	v_rcp_f32_e32 v5, v2
	ds_read_u16 v2, v37 offset:3744
	s_waitcnt lgkmcnt(0)
; #define MFMA(a, b, c) __builtin_amdgcn_mfma_f32_32x32x16_bf16((a), (b), (c), 0, 0, 0)
; DI float bf2f(u16 v) { return __uint_as_float(((unsigned)v) << 16); }
; DI int crow(int i, int h) { return (i & 3) + 8 * (i >> 2) + 4 * h; }
; DI void lru_item(const Params& p, int l, int b, int chunk, int blk, bool fin, char* smem, int tid) {
;     ...
;       const u16* wa = p.WtA + (((size_t)l * 2 + dir) * 4 + blk) * 4096 + (size_t)chn * 64 + h * 8;
;       const u16* wx = p.WtX + (((size_t)l * 2 + dir) * 4 + blk) * 4096 + (size_t)chn * 64 + h * 8;
; #pragma unroll
;       for (int ks = 0; ks < 4; ks++) {
;         bf16x8 a = *(const bf16x8*)&xcb[tb * 32 + r][ks * 16 + h * 8];
;         bf16x8 ba = *(const bf16x8*)(wa + ks * 16), bx = *(const bf16x8*)(wx + ks * 16);
;         ga = MFMA(a, ba, ga); gx = MFMA(a, bx, gx);
;       }
;       const int pi = (l * 2 + dir) * 256 + c0 + chn;
;       const float b_a = p.ba[pi], b_x = p.bx[pi], lam = p.lam[pi];
;       const float sp = log1pf(__expf(-lam));
; #pragma unroll
;       for (int i = 0; i < 16; i++) {
;         const int tok = tb * 32 + crow(i, h);
;         const float rr = __builtin_amdgcn_rcpf(1.f + __expf(-(ga[i] + b_a))), ii = __builtin_amdgcn_rcpf(1.f + __expf(-(gx[i] + b_x)));
;         const float la = -8.f * rr * sp;
;         const float a = __expf(la);
;         const float x2 = 2.f * la;
;         const float ser = -x2 * (1.f + x2 * (0.5f + x2 * (0.16666667f + x2 * (0.041666668f + x2 * 0.0083333338f))));
;         const float om = (x2 > -0.25f) ? ser : (1.f - a * a);
;         const float u = __builtin_amdgcn_sqrtf(fmaxf(om, 0.f)) * ii * bf2f(xcb[tok][chn]);
;         au[(dir * 64 + tok) * 64 + chn] = make_float2(a, u);
	v_lshlrev_b32_e32 v8, 16, v2
	v_add_f32_e32 v2, v33, v51
	v_mul_f32_e32 v2, 0xbfb8aa3b, v2
	v_exp_f32_e32 v2, v2
	s_nop 0
	v_add_f32_e32 v2, 1.0, v2
	v_rcp_f32_e32 v2, v2
	s_nop 0
	v_pk_mul_f32 v[2:3], v[2:3], s[20:21] op_sel_hi:[1,0]
	s_nop 0
	v_pk_mul_f32 v[2:3], v[2:3], v[0:1] op_sel_hi:[1,0]
	s_nop 0
	v_mul_f32_e32 v0, 0x3fb8aa3b, v3
	v_pk_add_f32 v[6:7], v[2:3], v[2:3]
	v_exp_f32_e32 v4, v0
	v_fmamk_f32 v0, v7, 0x3c088889, v212
	v_fmaak_f32 v0, v7, v0, 0x3e2aaaab
	v_fma_f32 v0, v7, v0, 0.5
	v_fma_f32 v0, v7, v0, 1.0
	v_mul_f32_e64 v0, v0, -v7
	v_fma_f32 v3, -v4, v4, 1.0
	v_cmp_lt_f32_e64 s[8:9], s19, v7
	v_cmp_lt_f32_e64 s[6:7], s19, v6
	s_nop 0
	v_cndmask_b32_e64 v0, v3, v0, s[8:9]
	v_max_f32_e32 v0, 0, v0
	v_sqrt_f32_e32 v0, v0
	s_nop 0
	v_mul_f32_e32 v0, v5, v0
	v_mul_f32_e32 v5, v0, v8
	v_mul_f32_e32 v0, 0x3fb8aa3b, v2
	v_exp_f32_e32 v2, v0
	v_fmamk_f32 v0, v6, 0x3c088889, v212
	v_fmaak_f32 v0, v6, v0, 0x3e2aaaab
	v_fma_f32 v0, v6, v0, 0.5
	v_fma_f32 v0, v6, v0, 1.0
	v_mul_f32_e64 v0, v0, -v6
	v_fma_f32 v3, -v2, v2, 1.0
	ds_write_b64 v78, v[4:5] offset:9216
	v_cndmask_b32_e64 v0, v3, v0, s[6:7]
	v_max_f32_e32 v0, 0, v0
	ds_read_u16 v3, v37 offset:3888
	v_sqrt_f32_e32 v0, v0
	s_waitcnt lgkmcnt(0)
	v_lshlrev_b32_e32 v3, 16, v3
	v_mul_f32_e32 v0, v9, v0
	v_mul_f32_e32 v3, v0, v3
	ds_write_b64 v79, v[2:3] offset:9216
	global_load_dwordx4 v[2:5], v[94:95], off
	global_load_dwordx4 v[6:9], v[96:97], off
	ds_read_b128 v[10:13], v61
	ds_read_b128 v[82:85], v61 offset:32
	global_load_dwordx4 v[86:89], v[94:95], off offset:32
	global_load_dwordx4 v[90:93], v[96:97], off offset:32
	s_waitcnt vmcnt(3) lgkmcnt(1)
	v_mfma_f32_32x32x16_bf16 v[18:33], v[10:13], v[2:5], 0
	s_waitcnt vmcnt(2)
	v_mfma_f32_32x32x16_bf16 v[2:17], v[10:13], v[6:9], 0
	s_waitcnt vmcnt(1) lgkmcnt(0)
	v_mfma_f32_32x32x16_bf16 v[18:33], v[82:85], v[86:89], v[18:33]
	s_waitcnt vmcnt(0)
	v_mfma_f32_32x32x16_bf16 v[2:17], v[82:85], v[90:93], v[2:17]
	ds_read_b128 v[82:85], v61 offset:64
	global_load_dwordx4 v[86:89], v[94:95], off offset:64
	global_load_dwordx4 v[90:93], v[96:97], off offset:64
	s_waitcnt vmcnt(1) lgkmcnt(0)
	v_mfma_f32_32x32x16_bf16 v[18:33], v[82:85], v[86:89], v[18:33]
	s_waitcnt vmcnt(0)
	v_mfma_f32_32x32x16_bf16 v[2:17], v[82:85], v[90:93], v[2:17]
	ds_read_b128 v[82:85], v61 offset:96
	global_load_dwordx4 v[86:89], v[94:95], off offset:96
	global_load_dwordx4 v[90:93], v[96:97], off offset:96
	s_nop 0
	global_load_dword v56, v[56:57], off offset:1024
	s_nop 0
	global_load_dword v51, v[58:59], off offset:1024
	global_load_dword v0, v[54:55], off offset:1024
	s_waitcnt vmcnt(0)
	v_mul_f32_e32 v0, 0xbfb8aa3b, v0
	v_exp_f32_e32 v0, v0
	s_waitcnt lgkmcnt(0)
	v_mfma_f32_32x32x16_bf16 v[18:33], v[82:85], v[86:89], v[18:33]
	v_add_f32_e32 v57, 1.0, v0
	v_add_f32_e32 v54, -1.0, v57
	v_sub_f32_e32 v55, v54, v57
	v_add_f32_e32 v55, 1.0, v55
	v_sub_f32_e32 v54, v0, v54
	v_add_f32_e32 v58, v54, v55
	v_frexp_mant_f32_e32 v54, v57
	v_cmp_gt_f32_e64 s[6:7], s14, v54
	v_cvt_f64_f32_e32 v[54:55], v57
	v_frexp_exp_i32_f64_e32 v54, v[54:55]
	v_subbrev_co_u32_e64 v81, s[6:7], 0, v54, s[6:7]
	v_sub_u32_e32 v54, 0, v81
	v_ldexp_f32 v55, v57, v54
	v_add_f32_e32 v57, -1.0, v55
	v_add_f32_e32 v59, 1.0, v55
	v_mfma_f32_32x32x16_bf16 v[2:17], v[82:85], v[90:93], v[2:17]
	v_ldexp_f32 v54, v58, v54
	v_add_f32_e32 v58, 1.0, v57
	v_add_f32_e32 v82, -1.0, v59
	v_sub_f32_e32 v58, v55, v58
	v_sub_f32_e32 v55, v55, v82
	v_add_f32_e32 v58, v54, v58
	v_add_f32_e32 v54, v54, v55
	v_add_f32_e32 v86, v59, v54
	v_rcp_f32_e32 v88, v86
	v_sub_f32_e32 v55, v86, v59
	v_sub_f32_e32 v87, v54, v55
	v_add_f32_e32 v55, v57, v58
	v_sub_f32_e32 v54, v55, v57
	v_mul_f32_e32 v89, v55, v88
	v_sub_f32_e32 v57, v58, v54
	v_mul_f32_e32 v58, v86, v89
	v_fma_f32 v82, v89, v86, -v58
	v_fmac_f32_e32 v82, v89, v87
	v_add_f32_e32 v54, v58, v82
	v_sub_f32_e32 v59, v55, v54
	v_pk_add_f32 v[84:85], v[54:55], v[58:59] neg_lo:[0,1] neg_hi:[0,1]
	v_mov_b32_e32 v83, v54
	v_pk_add_f32 v[54:55], v[84:85], v[82:83] neg_lo:[0,1] neg_hi:[0,1]
	v_add_f32_e32 v2, v2, v51
	v_add_f32_e32 v55, v57, v55
	v_add_f32_e32 v54, v54, v55
	v_add_f32_e32 v55, v59, v54
	v_mul_f32_e32 v57, v88, v55
	v_mul_f32_e32 v58, v86, v57
	v_fma_f32 v82, v57, v86, -v58
	v_fmac_f32_e32 v82, v57, v87
	v_sub_f32_e32 v59, v59, v55
	v_add_f32_e32 v86, v54, v59
	v_add_f32_e32 v54, v58, v82
	v_sub_f32_e32 v59, v55, v54
	v_pk_add_f32 v[84:85], v[54:55], v[58:59] neg_lo:[0,1] neg_hi:[0,1]
	v_mov_b32_e32 v83, v54
	v_pk_add_f32 v[54:55], v[84:85], v[82:83] neg_lo:[0,1] neg_hi:[0,1]
	v_mul_f32_e32 v2, 0xbfb8aa3b, v2
	v_add_f32_e32 v55, v86, v55
	v_add_f32_e32 v54, v54, v55
	v_add_f32_e32 v55, v89, v57
	v_add_f32_e32 v54, v59, v54
	v_sub_f32_e32 v58, v55, v89
	v_mul_f32_e32 v54, v88, v54
	v_sub_f32_e32 v57, v57, v58
	v_add_f32_e32 v57, v57, v54
	v_add_f32_e32 v58, v55, v57
	v_mul_f32_e32 v82, v58, v58
	v_fmamk_f32 v54, v82, 0x3e9b6dac, v211
	v_fmaak_f32 v153, v82, v54, 0x3f2aaada
	v_cvt_f32_i32_e32 v54, v81
	v_sub_f32_e32 v55, v58, v55
	v_sub_f32_e32 v55, v57, v55
	v_ldexp_f32 v57, v55, 1
	v_mul_f32_e32 v55, v58, v82
	v_pk_mul_f32 v[82:83], v[54:55], v[152:153]
	v_ldexp_f32 v59, v58, 1
	v_fma_f32 v58, v54, s15, -v82
	v_fmac_f32_e32 v58, 0xb102e308, v54
	v_pk_add_f32 v[54:55], v[82:83], v[58:59]
	v_mov_b32_e32 v84, v82
	v_sub_f32_e32 v59, v55, v59
	v_sub_f32_e32 v59, v83, v59
	v_add_f32_e32 v85, v57, v59
	v_pk_add_f32 v[82:83], v[54:55], v[82:83] neg_lo:[0,1] neg_hi:[0,1]
	v_pk_add_f32 v[86:87], v[54:55], v[84:85]
	v_mov_b32_e32 v59, v54
	v_mov_b32_e32 v83, v87
	v_pk_add_f32 v[88:89], v[58:59], v[82:83] neg_lo:[0,1] neg_hi:[0,1]
	v_pk_add_f32 v[58:59], v[58:59], v[82:83]
	v_mov_b32_e32 v84, v85
	v_pk_add_f32 v[82:83], v[58:59], v[54:55] op_sel:[1,0] op_sel_hi:[0,1] neg_lo:[0,1] neg_hi:[0,1]
	v_pk_add_f32 v[90:91], v[86:87], v[82:83] op_sel_hi:[1,0] neg_lo:[0,1] neg_hi:[0,1]
	v_mov_b32_e32 v86, v87
	v_mov_b32_e32 v87, v59
	v_pk_mov_b32 v[82:83], v[54:55], v[82:83] op_sel:[1,0]
	v_mov_b32_e32 v85, v54
	v_pk_add_f32 v[82:83], v[86:87], v[82:83] neg_lo:[0,1] neg_hi:[0,1]
	v_mov_b32_e32 v90, v88
	v_pk_add_f32 v[54:55], v[84:85], v[82:83] neg_lo:[0,1] neg_hi:[0,1]
	v_mov_b32_e32 v89, v59
	v_pk_add_f32 v[82:83], v[90:91], v[54:55]
	v_exp_f32_e32 v2, v2
	v_pk_add_f32 v[84:85], v[82:83], v[82:83] op_sel:[0,1] op_sel_hi:[1,0]
	v_cmp_neq_f32_e64 s[6:7], s16, v0
	v_pk_add_f32 v[58:59], v[58:59], v[84:85] op_sel:[1,0] op_sel_hi:[0,1]
	v_mov_b32_e32 v83, v58
	v_pk_add_f32 v[86:87], v[82:83], v[88:89] neg_lo:[0,1] neg_hi:[0,1]
	v_mov_b32_e32 v55, v84
	v_sub_f32_e32 v57, v82, v86
	v_pk_add_f32 v[54:55], v[54:55], v[86:87] neg_lo:[0,1] neg_hi:[0,1]
	v_sub_f32_e32 v57, v88, v57
	v_add_f32_e32 v2, 1.0, v2
	v_add_f32_e32 v54, v54, v57
	v_rcp_f32_e32 v57, v2
	ds_read_u16 v2, v37
	v_add_f32_e32 v54, v54, v55
	v_add_f32_e32 v54, v58, v54
	v_add_f32_e32 v18, v18, v56
	v_cndmask_b32_e64 v54, v217, v54, s[6:7]
	s_waitcnt lgkmcnt(0)
; DI float bf2f(u16 v) { return __uint_as_float(((unsigned)v) << 16); }
; DI int crow(int i, int h) { return (i & 3) + 8 * (i >> 2) + 4 * h; }
; DI void lru_item(const Params& p, int l, int b, int chunk, int blk, bool fin, char* smem, int tid) {
;     ...
;       for (int i = 0; i < 16; i++) {
;         const int tok = tb * 32 + crow(i, h);
;         const float rr = __builtin_amdgcn_rcpf(1.f + __expf(-(ga[i] + b_a))), ii = __builtin_amdgcn_rcpf(1.f + __expf(-(gx[i] + b_x)));
;         const float la = -8.f * rr * sp;
;         const float a = __expf(la);
;         const float x2 = 2.f * la;
;         const float ser = -x2 * (1.f + x2 * (0.5f + x2 * (0.16666667f + x2 * (0.041666668f + x2 * 0.0083333338f))));
;         const float om = (x2 > -0.25f) ? ser : (1.f - a * a);
;         const float u = __builtin_amdgcn_sqrtf(fmaxf(om, 0.f)) * ii * bf2f(xcb[tok][chn]);
;         au[(dir * 64 + tok) * 64 + chn] = make_float2(a, u);
;       }
	v_lshlrev_b32_e32 v58, 16, v2
	v_add_f32_e32 v2, v19, v56
	v_mul_f32_e32 v2, 0xbfb8aa3b, v2
	v_exp_f32_e32 v2, v2
	v_cmp_ngt_f32_e64 s[6:7], -1.0, v0
	v_mul_f32_e32 v18, 0xbfb8aa3b, v18
	v_exp_f32_e32 v18, v18
	v_cndmask_b32_e64 v54, v218, v54, s[6:7]
	v_cmp_neq_f32_e64 s[6:7], -1.0, v0
	v_add_f32_e32 v2, 1.0, v2
	v_add_f32_e32 v18, 1.0, v18
	v_cndmask_b32_e64 v54, v219, v54, s[6:7]
	v_cmp_lt_f32_e64 s[6:7], |v0|, s17
	v_rcp_f32_e32 v55, v18
	s_nop 0
	v_cndmask_b32_e64 v0, v54, v0, s[6:7]
	v_rcp_f32_e32 v54, v2
	v_add_f32_e32 v2, v3, v51
	v_mul_f32_e32 v2, 0xbfb8aa3b, v2
	v_exp_f32_e32 v2, v2
	s_nop 0
	v_add_f32_e32 v2, 1.0, v2
	v_rcp_f32_e32 v59, v2
	v_pk_mul_f32 v[2:3], v[54:55], s[20:21] op_sel_hi:[1,0]
	s_nop 0
	v_pk_mul_f32 v[2:3], v[2:3], v[0:1] op_sel_hi:[1,0]
	s_nop 0
	v_mul_f32_e32 v18, 0x3fb8aa3b, v3
	v_pk_add_f32 v[54:55], v[2:3], v[2:3]
	v_exp_f32_e32 v18, v18
	v_fmamk_f32 v3, v55, 0x3c088889, v212
	v_fmaak_f32 v3, v55, v3, 0x3e2aaaab
	v_fma_f32 v3, v55, v3, 0.5
	v_fma_f32 v3, v55, v3, 1.0
	v_mul_f32_e64 v3, v3, -v55
	v_fma_f32 v19, -v18, v18, 1.0
	v_cmp_lt_f32_e64 s[8:9], s19, v55
	v_mul_f32_e32 v2, 0x3fb8aa3b, v2
	v_exp_f32_e32 v2, v2
	v_cndmask_b32_e64 v3, v19, v3, s[8:9]
	v_max_f32_e32 v3, 0, v3
	v_sqrt_f32_e32 v3, v3
	v_cmp_lt_f32_e64 s[6:7], s19, v54
	v_mul_f32_e32 v3, v57, v3
	v_mul_f32_e32 v19, v3, v58
	v_fmamk_f32 v3, v54, 0x3c088889, v212
	v_fmaak_f32 v3, v54, v3, 0x3e2aaaab
	v_fma_f32 v3, v54, v3, 0.5
	v_fma_f32 v3, v54, v3, 1.0
	ds_write_b64 v80, v[18:19] offset:41984
	v_mul_f32_e64 v3, v3, -v54
	v_fma_f32 v18, -v2, v2, 1.0
	v_cndmask_b32_e64 v3, v18, v3, s[6:7]
	v_max_f32_e32 v3, 0, v3
	ds_read_u16 v18, v37 offset:144
	v_sqrt_f32_e32 v3, v3
	s_waitcnt lgkmcnt(0)
	v_lshlrev_b32_e32 v18, 16, v18
	v_mul_f32_e32 v3, v59, v3
	v_mul_f32_e32 v3, v3, v18
	ds_write_b64 v49, v[2:3] offset:41984
	v_add_f32_e32 v2, v20, v56
	v_mul_f32_e32 v2, 0xbfb8aa3b, v2
	v_exp_f32_e32 v2, v2
	s_nop 0
	v_add_f32_e32 v2, 1.0, v2
	v_rcp_f32_e32 v3, v2
	v_add_f32_e32 v2, v4, v51
	v_mul_f32_e32 v2, 0xbfb8aa3b, v2
	v_exp_f32_e32 v2, v2
	v_add_f32_e32 v4, v5, v51
	v_mul_f32_e32 v4, 0xbfb8aa3b, v4
	v_exp_f32_e32 v4, v4
	v_add_f32_e32 v2, 1.0, v2
	v_rcp_f32_e32 v20, v2
	ds_read_u16 v2, v37 offset:288
	v_add_f32_e32 v4, 1.0, v4
	s_waitcnt lgkmcnt(0)
	v_lshlrev_b32_e32 v54, 16, v2
	v_add_f32_e32 v2, v21, v56
	v_mul_f32_e32 v2, 0xbfb8aa3b, v2
	v_exp_f32_e32 v2, v2
	v_rcp_f32_e32 v21, v4
	v_add_f32_e32 v2, 1.0, v2
	v_rcp_f32_e32 v2, v2
	s_nop 0
	v_pk_mul_f32 v[2:3], v[2:3], s[20:21] op_sel_hi:[1,0]
	s_nop 0
	v_pk_mul_f32 v[2:3], v[2:3], v[0:1] op_sel_hi:[1,0]
	s_nop 0
	v_mul_f32_e32 v4, 0x3fb8aa3b, v3
	v_pk_add_f32 v[18:19], v[2:3], v[2:3]
	v_exp_f32_e32 v4, v4
	v_fmamk_f32 v3, v19, 0x3c088889, v212
	v_fmaak_f32 v3, v19, v3, 0x3e2aaaab
	v_fma_f32 v3, v19, v3, 0.5
	v_fma_f32 v3, v19, v3, 1.0
	v_mul_f32_e64 v3, v3, -v19
	v_fma_f32 v5, -v4, v4, 1.0
	v_cmp_lt_f32_e64 s[8:9], s19, v19
	v_mul_f32_e32 v2, 0x3fb8aa3b, v2
	v_exp_f32_e32 v2, v2
	v_cndmask_b32_e64 v3, v5, v3, s[8:9]
	v_max_f32_e32 v3, 0, v3
	v_sqrt_f32_e32 v3, v3
	v_cmp_lt_f32_e64 s[6:7], s19, v18
	v_mul_f32_e32 v3, v20, v3
	v_mul_f32_e32 v5, v3, v54
	v_fmamk_f32 v3, v18, 0x3c088889, v212
	v_fmaak_f32 v3, v18, v3, 0x3e2aaaab
	v_fma_f32 v3, v18, v3, 0.5
	v_fma_f32 v3, v18, v3, 1.0
	ds_write_b64 v66, v[4:5] offset:41984
	v_mul_f32_e64 v3, v3, -v18
	v_fma_f32 v4, -v2, v2, 1.0
	v_cndmask_b32_e64 v3, v4, v3, s[6:7]
	v_max_f32_e32 v3, 0, v3
	ds_read_u16 v4, v37 offset:432
	v_sqrt_f32_e32 v3, v3
	s_waitcnt lgkmcnt(0)
	v_lshlrev_b32_e32 v4, 16, v4
	v_mul_f32_e32 v3, v21, v3
	v_mul_f32_e32 v3, v3, v4
	ds_write_b64 v67, v[2:3] offset:41984
	v_add_f32_e32 v2, v22, v56
	v_mul_f32_e32 v2, 0xbfb8aa3b, v2
	v_exp_f32_e32 v2, v2
	v_add_f32_e32 v4, v7, v51
	v_mul_f32_e32 v4, 0xbfb8aa3b, v4
	v_exp_f32_e32 v4, v4
	v_add_f32_e32 v2, 1.0, v2
	v_rcp_f32_e32 v3, v2
	v_add_f32_e32 v2, v6, v51
	v_mul_f32_e32 v2, 0xbfb8aa3b, v2
	v_exp_f32_e32 v2, v2
	v_add_f32_e32 v4, 1.0, v4
	v_rcp_f32_e32 v19, v4
	v_add_f32_e32 v2, 1.0, v2
	v_rcp_f32_e32 v5, v2
	ds_read_u16 v2, v37 offset:1152
	s_waitcnt lgkmcnt(0)
	v_lshlrev_b32_e32 v18, 16, v2
	v_add_f32_e32 v2, v23, v56
	v_mul_f32_e32 v2, 0xbfb8aa3b, v2
	v_exp_f32_e32 v2, v2
	s_nop 0
	v_add_f32_e32 v2, 1.0, v2
	v_rcp_f32_e32 v2, v2
	s_nop 0
	v_pk_mul_f32 v[2:3], v[2:3], s[20:21] op_sel_hi:[1,0]
	s_nop 0
	v_pk_mul_f32 v[2:3], v[2:3], v[0:1] op_sel_hi:[1,0]
	s_nop 0
	v_mul_f32_e32 v4, 0x3fb8aa3b, v3
	v_pk_add_f32 v[6:7], v[2:3], v[2:3]
	v_exp_f32_e32 v4, v4
	v_fmamk_f32 v3, v7, 0x3c088889, v212
	v_fmaak_f32 v3, v7, v3, 0x3e2aaaab
	v_fma_f32 v3, v7, v3, 0.5
	v_fma_f32 v3, v7, v3, 1.0
	v_mul_f32_e64 v3, v3, -v7
	v_fma_f32 v20, -v4, v4, 1.0
	v_cmp_lt_f32_e64 s[8:9], s19, v7
	v_mul_f32_e32 v2, 0x3fb8aa3b, v2
	v_exp_f32_e32 v2, v2
	v_cndmask_b32_e64 v3, v20, v3, s[8:9]
	v_max_f32_e32 v3, 0, v3
	v_sqrt_f32_e32 v3, v3
	v_cmp_lt_f32_e64 s[6:7], s19, v6
	v_mul_f32_e32 v3, v5, v3
	v_mul_f32_e32 v5, v3, v18
	v_fmamk_f32 v3, v6, 0x3c088889, v212
	v_fmaak_f32 v3, v6, v3, 0x3e2aaaab
	v_fma_f32 v3, v6, v3, 0.5
	v_fma_f32 v3, v6, v3, 1.0
	ds_write_b64 v68, v[4:5] offset:41984
	v_mul_f32_e64 v3, v3, -v6
	v_fma_f32 v4, -v2, v2, 1.0
	v_cndmask_b32_e64 v3, v4, v3, s[6:7]
	v_max_f32_e32 v3, 0, v3
	ds_read_u16 v4, v37 offset:1296
	v_sqrt_f32_e32 v3, v3
	s_waitcnt lgkmcnt(0)
	v_lshlrev_b32_e32 v4, 16, v4
	v_mul_f32_e32 v3, v19, v3
	v_mul_f32_e32 v3, v3, v4
	ds_write_b64 v69, v[2:3] offset:41984
	v_add_f32_e32 v2, v24, v56
	v_mul_f32_e32 v2, 0xbfb8aa3b, v2
	v_exp_f32_e32 v2, v2
	v_add_f32_e32 v4, v9, v51
	v_mul_f32_e32 v4, 0xbfb8aa3b, v4
	v_exp_f32_e32 v4, v4
	v_add_f32_e32 v2, 1.0, v2
	v_rcp_f32_e32 v3, v2
	v_add_f32_e32 v2, v8, v51
	v_mul_f32_e32 v2, 0xbfb8aa3b, v2
	v_exp_f32_e32 v2, v2
	v_add_f32_e32 v4, 1.0, v4
	v_rcp_f32_e32 v9, v4
	v_add_f32_e32 v2, 1.0, v2
	v_rcp_f32_e32 v5, v2
	ds_read_u16 v2, v37 offset:1440
	s_waitcnt lgkmcnt(0)
; DI float bf2f(u16 v) { return __uint_as_float(((unsigned)v) << 16); }
; DI int crow(int i, int h) { return (i & 3) + 8 * (i >> 2) + 4 * h; }
; DI void lru_item(const Params& p, int l, int b, int chunk, int blk, bool fin, char* smem, int tid) {
;     ...
;       for (int i = 0; i < 16; i++) {
;         const int tok = tb * 32 + crow(i, h);
;         const float rr = __builtin_amdgcn_rcpf(1.f + __expf(-(ga[i] + b_a))), ii = __builtin_amdgcn_rcpf(1.f + __expf(-(gx[i] + b_x)));
;         const float la = -8.f * rr * sp;
;         const float a = __expf(la);
;         const float x2 = 2.f * la;
;         const float ser = -x2 * (1.f + x2 * (0.5f + x2 * (0.16666667f + x2 * (0.041666668f + x2 * 0.0083333338f))));
;         const float om = (x2 > -0.25f) ? ser : (1.f - a * a);
;         const float u = __builtin_amdgcn_sqrtf(fmaxf(om, 0.f)) * ii * bf2f(xcb[tok][chn]);
;         au[(dir * 64 + tok) * 64 + chn] = make_float2(a, u);
;       }
	v_lshlrev_b32_e32 v8, 16, v2
	v_add_f32_e32 v2, v25, v56
	v_mul_f32_e32 v2, 0xbfb8aa3b, v2
	v_exp_f32_e32 v2, v2
	s_nop 0
	v_add_f32_e32 v2, 1.0, v2
	v_rcp_f32_e32 v2, v2
	s_nop 0
	v_pk_mul_f32 v[2:3], v[2:3], s[20:21] op_sel_hi:[1,0]
	s_nop 0
	v_pk_mul_f32 v[2:3], v[2:3], v[0:1] op_sel_hi:[1,0]
	s_nop 0
	v_mul_f32_e32 v4, 0x3fb8aa3b, v3
	v_pk_add_f32 v[6:7], v[2:3], v[2:3]
	v_exp_f32_e32 v4, v4
	v_fmamk_f32 v3, v7, 0x3c088889, v212
	v_fmaak_f32 v3, v7, v3, 0x3e2aaaab
	v_fma_f32 v3, v7, v3, 0.5
	v_fma_f32 v3, v7, v3, 1.0
	v_mul_f32_e64 v3, v3, -v7
	v_fma_f32 v18, -v4, v4, 1.0
	v_cmp_lt_f32_e64 s[8:9], s19, v7
	v_mul_f32_e32 v2, 0x3fb8aa3b, v2
	v_exp_f32_e32 v2, v2
	v_cndmask_b32_e64 v3, v18, v3, s[8:9]
	v_max_f32_e32 v3, 0, v3
	v_sqrt_f32_e32 v3, v3
	v_cmp_lt_f32_e64 s[6:7], s19, v6
	v_mul_f32_e32 v3, v5, v3
	v_mul_f32_e32 v5, v3, v8
	v_fmamk_f32 v3, v6, 0x3c088889, v212
	v_fmaak_f32 v3, v6, v3, 0x3e2aaaab
	v_fma_f32 v3, v6, v3, 0.5
	v_fma_f32 v3, v6, v3, 1.0
	ds_write_b64 v70, v[4:5] offset:41984
	v_mul_f32_e64 v3, v3, -v6
	v_fma_f32 v4, -v2, v2, 1.0
	v_cndmask_b32_e64 v3, v4, v3, s[6:7]
	v_max_f32_e32 v3, 0, v3
	ds_read_u16 v4, v37 offset:1584
	v_sqrt_f32_e32 v3, v3
	s_waitcnt lgkmcnt(0)
	v_lshlrev_b32_e32 v4, 16, v4
	v_mul_f32_e32 v3, v9, v3
	v_mul_f32_e32 v3, v3, v4
	ds_write_b64 v71, v[2:3] offset:41984
	v_add_f32_e32 v2, v26, v56
	v_mul_f32_e32 v2, 0xbfb8aa3b, v2
	v_exp_f32_e32 v2, v2
	v_add_f32_e32 v4, v11, v51
	v_mul_f32_e32 v4, 0xbfb8aa3b, v4
	v_exp_f32_e32 v4, v4
	v_add_f32_e32 v2, 1.0, v2
	v_rcp_f32_e32 v3, v2
	v_add_f32_e32 v2, v10, v51
	v_mul_f32_e32 v2, 0xbfb8aa3b, v2
	v_exp_f32_e32 v2, v2
	v_add_f32_e32 v4, 1.0, v4
	v_rcp_f32_e32 v9, v4
	v_add_f32_e32 v2, 1.0, v2
	v_rcp_f32_e32 v5, v2
	ds_read_u16 v2, v37 offset:2304
	s_waitcnt lgkmcnt(0)
	v_lshlrev_b32_e32 v8, 16, v2
	v_add_f32_e32 v2, v27, v56
	v_mul_f32_e32 v2, 0xbfb8aa3b, v2
	v_exp_f32_e32 v2, v2
	s_nop 0
	v_add_f32_e32 v2, 1.0, v2
	v_rcp_f32_e32 v2, v2
	s_nop 0
	v_pk_mul_f32 v[2:3], v[2:3], s[20:21] op_sel_hi:[1,0]
	s_nop 0
	v_pk_mul_f32 v[2:3], v[2:3], v[0:1] op_sel_hi:[1,0]
	s_nop 0
	v_mul_f32_e32 v4, 0x3fb8aa3b, v3
	v_pk_add_f32 v[6:7], v[2:3], v[2:3]
	v_exp_f32_e32 v4, v4
	v_fmamk_f32 v3, v7, 0x3c088889, v212
	v_fmaak_f32 v3, v7, v3, 0x3e2aaaab
	v_fma_f32 v3, v7, v3, 0.5
	v_fma_f32 v3, v7, v3, 1.0
	v_mul_f32_e64 v3, v3, -v7
	v_fma_f32 v10, -v4, v4, 1.0
	v_cmp_lt_f32_e64 s[8:9], s19, v7
	v_mul_f32_e32 v2, 0x3fb8aa3b, v2
	v_exp_f32_e32 v2, v2
	v_cndmask_b32_e64 v3, v10, v3, s[8:9]
	v_max_f32_e32 v3, 0, v3
	v_sqrt_f32_e32 v3, v3
	v_cmp_lt_f32_e64 s[6:7], s19, v6
	v_mul_f32_e32 v3, v5, v3
	v_mul_f32_e32 v5, v3, v8
	v_fmamk_f32 v3, v6, 0x3c088889, v212
	v_fmaak_f32 v3, v6, v3, 0x3e2aaaab
	v_fma_f32 v3, v6, v3, 0.5
	v_fma_f32 v3, v6, v3, 1.0
	ds_write_b64 v72, v[4:5] offset:41984
	v_mul_f32_e64 v3, v3, -v6
	v_fma_f32 v4, -v2, v2, 1.0
	v_cndmask_b32_e64 v3, v4, v3, s[6:7]
	v_max_f32_e32 v3, 0, v3
	ds_read_u16 v4, v37 offset:2448
	v_sqrt_f32_e32 v3, v3
	s_waitcnt lgkmcnt(0)
	v_lshlrev_b32_e32 v4, 16, v4
	v_mul_f32_e32 v3, v9, v3
	v_mul_f32_e32 v3, v3, v4
	ds_write_b64 v73, v[2:3] offset:41984
	v_add_f32_e32 v2, v28, v56
	v_mul_f32_e32 v2, 0xbfb8aa3b, v2
	v_exp_f32_e32 v2, v2
	v_add_f32_e32 v4, v13, v51
	v_mul_f32_e32 v4, 0xbfb8aa3b, v4
	v_exp_f32_e32 v4, v4
	v_add_f32_e32 v2, 1.0, v2
	v_rcp_f32_e32 v3, v2
	v_add_f32_e32 v2, v12, v51
	v_mul_f32_e32 v2, 0xbfb8aa3b, v2
	v_exp_f32_e32 v2, v2
	v_add_f32_e32 v4, 1.0, v4
	v_rcp_f32_e32 v9, v4
	v_add_f32_e32 v2, 1.0, v2
	v_rcp_f32_e32 v5, v2
	ds_read_u16 v2, v37 offset:2592
	s_waitcnt lgkmcnt(0)
	v_lshlrev_b32_e32 v8, 16, v2
	v_add_f32_e32 v2, v29, v56
	v_mul_f32_e32 v2, 0xbfb8aa3b, v2
	v_exp_f32_e32 v2, v2
	s_nop 0
	v_add_f32_e32 v2, 1.0, v2
	v_rcp_f32_e32 v2, v2
	s_nop 0
	v_pk_mul_f32 v[2:3], v[2:3], s[20:21] op_sel_hi:[1,0]
	s_nop 0
	v_pk_mul_f32 v[2:3], v[2:3], v[0:1] op_sel_hi:[1,0]
	s_nop 0
	v_mul_f32_e32 v4, 0x3fb8aa3b, v3
	v_pk_add_f32 v[6:7], v[2:3], v[2:3]
	v_exp_f32_e32 v4, v4
	v_fmamk_f32 v3, v7, 0x3c088889, v212
	v_fmaak_f32 v3, v7, v3, 0x3e2aaaab
	v_fma_f32 v3, v7, v3, 0.5
	v_fma_f32 v3, v7, v3, 1.0
	v_mul_f32_e64 v3, v3, -v7
	v_fma_f32 v10, -v4, v4, 1.0
	v_cmp_lt_f32_e64 s[8:9], s19, v7
	v_mul_f32_e32 v2, 0x3fb8aa3b, v2
	v_exp_f32_e32 v2, v2
	v_cndmask_b32_e64 v3, v10, v3, s[8:9]
	v_max_f32_e32 v3, 0, v3
	v_sqrt_f32_e32 v3, v3
	v_cmp_lt_f32_e64 s[6:7], s19, v6
	v_mul_f32_e32 v3, v5, v3
	v_mul_f32_e32 v5, v3, v8
	v_fmamk_f32 v3, v6, 0x3c088889, v212
	v_fmaak_f32 v3, v6, v3, 0x3e2aaaab
	v_fma_f32 v3, v6, v3, 0.5
	v_fma_f32 v3, v6, v3, 1.0
	ds_write_b64 v74, v[4:5] offset:41984
	v_mul_f32_e64 v3, v3, -v6
	v_fma_f32 v4, -v2, v2, 1.0
	v_cndmask_b32_e64 v3, v4, v3, s[6:7]
	v_max_f32_e32 v3, 0, v3
	ds_read_u16 v4, v37 offset:2736
	v_sqrt_f32_e32 v3, v3
	s_waitcnt lgkmcnt(0)
	v_lshlrev_b32_e32 v4, 16, v4
	v_mul_f32_e32 v3, v9, v3
	v_mul_f32_e32 v3, v3, v4
	ds_write_b64 v75, v[2:3] offset:41984
	v_add_f32_e32 v2, v30, v56
	v_mul_f32_e32 v2, 0xbfb8aa3b, v2
	v_exp_f32_e32 v2, v2
	v_add_f32_e32 v4, v15, v51
	v_mul_f32_e32 v4, 0xbfb8aa3b, v4
	v_exp_f32_e32 v4, v4
	v_add_f32_e32 v2, 1.0, v2
	v_rcp_f32_e32 v3, v2
	v_add_f32_e32 v2, v14, v51
	v_mul_f32_e32 v2, 0xbfb8aa3b, v2
	v_exp_f32_e32 v2, v2
	v_add_f32_e32 v4, 1.0, v4
	v_rcp_f32_e32 v9, v4
	v_add_f32_e32 v2, 1.0, v2
	v_rcp_f32_e32 v5, v2
	ds_read_u16 v2, v37 offset:3456
	s_waitcnt lgkmcnt(0)
; DI float bf2f(u16 v) { return __uint_as_float(((unsigned)v) << 16); }
; DI int crow(int i, int h) { return (i & 3) + 8 * (i >> 2) + 4 * h; }
; DI void lru_item(const Params& p, int l, int b, int chunk, int blk, bool fin, char* smem, int tid) {
;     ...
;       for (int i = 0; i < 16; i++) {
;         const int tok = tb * 32 + crow(i, h);
;         const float rr = __builtin_amdgcn_rcpf(1.f + __expf(-(ga[i] + b_a))), ii = __builtin_amdgcn_rcpf(1.f + __expf(-(gx[i] + b_x)));
;         const float la = -8.f * rr * sp;
;         const float a = __expf(la);
;         const float x2 = 2.f * la;
;         const float ser = -x2 * (1.f + x2 * (0.5f + x2 * (0.16666667f + x2 * (0.041666668f + x2 * 0.0083333338f))));
;         const float om = (x2 > -0.25f) ? ser : (1.f - a * a);
;         const float u = __builtin_amdgcn_sqrtf(fmaxf(om, 0.f)) * ii * bf2f(xcb[tok][chn]);
;         au[(dir * 64 + tok) * 64 + chn] = make_float2(a, u);
;       }
;     }
;   }
;   __syncthreads();
;   float2* agg = (float2*)p.agg;
;   if (w < 2) {
;     const int dir = w, ch = lane;
;     float hst = 0.f;
;     if (!fin) {
;       float Ap = 1.f;
; #pragma unroll 8
;       for (int s2 = 0; s2 < 64; s2++) { const int t = dir ? 63 - s2 : s2; float2 v = au[(dir * 64 + t) * 64 + ch]; hst = v.x * hst + v.y; Ap *= v.x; }
;       agg[(((size_t)b * 68 + chunk) * 2 + dir) * 256 + c0 + ch] = make_float2(Ap, hst);
	v_lshlrev_b32_e32 v8, 16, v2
	v_add_f32_e32 v2, v31, v56
	v_mul_f32_e32 v2, 0xbfb8aa3b, v2
	v_exp_f32_e32 v2, v2
	s_nop 0
	v_add_f32_e32 v2, 1.0, v2
	v_rcp_f32_e32 v2, v2
	s_nop 0
	v_pk_mul_f32 v[2:3], v[2:3], s[20:21] op_sel_hi:[1,0]
	s_nop 0
	v_pk_mul_f32 v[2:3], v[2:3], v[0:1] op_sel_hi:[1,0]
	s_nop 0
	v_mul_f32_e32 v4, 0x3fb8aa3b, v3
	v_pk_add_f32 v[6:7], v[2:3], v[2:3]
	v_exp_f32_e32 v4, v4
	v_fmamk_f32 v3, v7, 0x3c088889, v212
	v_fmaak_f32 v3, v7, v3, 0x3e2aaaab
	v_fma_f32 v3, v7, v3, 0.5
	v_fma_f32 v3, v7, v3, 1.0
	v_mul_f32_e64 v3, v3, -v7
	v_fma_f32 v10, -v4, v4, 1.0
	v_cmp_lt_f32_e64 s[8:9], s19, v7
	v_mul_f32_e32 v2, 0x3fb8aa3b, v2
	v_exp_f32_e32 v2, v2
	v_cndmask_b32_e64 v3, v10, v3, s[8:9]
	v_max_f32_e32 v3, 0, v3
	v_sqrt_f32_e32 v3, v3
	v_cmp_lt_f32_e64 s[6:7], s19, v6
	v_mul_f32_e32 v3, v5, v3
	v_mul_f32_e32 v5, v3, v8
	v_fmamk_f32 v3, v6, 0x3c088889, v212
	v_fmaak_f32 v3, v6, v3, 0x3e2aaaab
	v_fma_f32 v3, v6, v3, 0.5
	v_fma_f32 v3, v6, v3, 1.0
	ds_write_b64 v76, v[4:5] offset:41984
	v_mul_f32_e64 v3, v3, -v6
	v_fma_f32 v4, -v2, v2, 1.0
	v_cndmask_b32_e64 v3, v4, v3, s[6:7]
	v_max_f32_e32 v3, 0, v3
	ds_read_u16 v4, v37 offset:3600
	v_sqrt_f32_e32 v3, v3
	s_waitcnt lgkmcnt(0)
	v_lshlrev_b32_e32 v4, 16, v4
	v_mul_f32_e32 v3, v9, v3
	v_mul_f32_e32 v3, v3, v4
	ds_write_b64 v77, v[2:3] offset:41984
	v_add_f32_e32 v2, v32, v56
	v_mul_f32_e32 v2, 0xbfb8aa3b, v2
	v_exp_f32_e32 v2, v2
	v_add_f32_e32 v4, v17, v51
	v_mul_f32_e32 v4, 0xbfb8aa3b, v4
	v_exp_f32_e32 v4, v4
	v_add_f32_e32 v2, 1.0, v2
	v_rcp_f32_e32 v3, v2
	v_add_f32_e32 v2, v16, v51
	v_mul_f32_e32 v2, 0xbfb8aa3b, v2
	v_exp_f32_e32 v2, v2
	v_add_f32_e32 v4, 1.0, v4
	v_rcp_f32_e32 v9, v4
	v_add_f32_e32 v2, 1.0, v2
	v_rcp_f32_e32 v5, v2
	ds_read_u16 v2, v37 offset:3744
	s_waitcnt lgkmcnt(0)
	v_lshlrev_b32_e32 v8, 16, v2
	v_add_f32_e32 v2, v33, v56
	v_mul_f32_e32 v2, 0xbfb8aa3b, v2
	v_exp_f32_e32 v2, v2
	s_nop 0
	v_add_f32_e32 v2, 1.0, v2
	v_rcp_f32_e32 v2, v2
	s_nop 0
	v_pk_mul_f32 v[2:3], v[2:3], s[20:21] op_sel_hi:[1,0]
	s_nop 0
	v_pk_mul_f32 v[2:3], v[2:3], v[0:1] op_sel_hi:[1,0]
	s_nop 0
	v_mul_f32_e32 v0, 0x3fb8aa3b, v3
	v_pk_add_f32 v[6:7], v[2:3], v[2:3]
	v_exp_f32_e32 v4, v0
	v_fmamk_f32 v0, v7, 0x3c088889, v212
	v_fmaak_f32 v0, v7, v0, 0x3e2aaaab
	v_fma_f32 v0, v7, v0, 0.5
	v_fma_f32 v0, v7, v0, 1.0
	v_mul_f32_e64 v0, v0, -v7
	v_fma_f32 v3, -v4, v4, 1.0
	v_cmp_lt_f32_e64 s[8:9], s19, v7
	v_cmp_lt_f32_e64 s[6:7], s19, v6
	s_nop 0
	v_cndmask_b32_e64 v0, v3, v0, s[8:9]
	v_max_f32_e32 v0, 0, v0
	v_sqrt_f32_e32 v0, v0
	s_nop 0
	v_mul_f32_e32 v0, v5, v0
	v_mul_f32_e32 v5, v0, v8
	v_mul_f32_e32 v0, 0x3fb8aa3b, v2
	v_exp_f32_e32 v2, v0
	v_fmamk_f32 v0, v6, 0x3c088889, v212
	v_fmaak_f32 v0, v6, v0, 0x3e2aaaab
	v_fma_f32 v0, v6, v0, 0.5
	v_fma_f32 v0, v6, v0, 1.0
	v_mul_f32_e64 v0, v0, -v6
	v_fma_f32 v3, -v2, v2, 1.0
	ds_write_b64 v78, v[4:5] offset:41984
	v_cndmask_b32_e64 v0, v3, v0, s[6:7]
	v_max_f32_e32 v0, 0, v0
	ds_read_u16 v3, v37 offset:3888
	v_sqrt_f32_e32 v0, v0
	s_waitcnt lgkmcnt(0)
	v_lshlrev_b32_e32 v3, 16, v3
	v_mul_f32_e32 v0, v9, v0
	v_mul_f32_e32 v3, v0, v3
	ds_write_b64 v79, v[2:3] offset:41984
	s_waitcnt lgkmcnt(0)
	s_barrier
	s_and_saveexec_b64 s[6:7], s[0:1]
	s_cbranch_execz .LBB0_783
	v_lshrrev_b32_e32 v0, 6, v206
	v_and_b32_e32 v2, 63, v206
	v_mov_b32_e32 v4, 1.0
	v_readfirstlane_b32 s8, v0
	v_lshlrev_b32_e32 v2, 3, v2
	v_mov_b32_e32 v3, 0
	s_lshl_b32 s9, s8, 15
	s_nop 0
	v_add_u32_e32 v2, s9, v2
	s_cmp_eq_u32 s8, 0
	s_cbranch_scc0 .Llp_scan1
	ds_read_b64 v[8:9], v2 offset:9216
	ds_read_b64 v[10:11], v2 offset:9728
	ds_read_b64 v[12:13], v2 offset:10240
	ds_read_b64 v[14:15], v2 offset:10752
	ds_read_b64 v[16:17], v2 offset:11264
	ds_read_b64 v[18:19], v2 offset:11776
	ds_read_b64 v[20:21], v2 offset:12288
	ds_read_b64 v[22:23], v2 offset:12800
	s_waitcnt lgkmcnt(7)
	v_fma_f32 v3, v8, v3, v9
	v_mul_f32_e32 v4, v4, v8
	s_waitcnt lgkmcnt(6)
	v_fma_f32 v3, v10, v3, v11
	v_mul_f32_e32 v4, v4, v10
	s_waitcnt lgkmcnt(5)
	v_fma_f32 v3, v12, v3, v13
	v_mul_f32_e32 v4, v4, v12
	s_waitcnt lgkmcnt(4)
	v_fma_f32 v3, v14, v3, v15
	v_mul_f32_e32 v4, v4, v14
	s_waitcnt lgkmcnt(3)
	v_fma_f32 v3, v16, v3, v17
	v_mul_f32_e32 v4, v4, v16
	s_waitcnt lgkmcnt(2)
	v_fma_f32 v3, v18, v3, v19
	v_mul_f32_e32 v4, v4, v18
	s_waitcnt lgkmcnt(1)
	v_fma_f32 v3, v20, v3, v21
	v_mul_f32_e32 v4, v4, v20
	s_waitcnt lgkmcnt(0)
	v_fma_f32 v3, v22, v3, v23
	v_mul_f32_e32 v4, v4, v22
	ds_read_b64 v[8:9], v2 offset:13312
	ds_read_b64 v[10:11], v2 offset:13824
	ds_read_b64 v[12:13], v2 offset:14336
	ds_read_b64 v[14:15], v2 offset:14848
	ds_read_b64 v[16:17], v2 offset:15360
	ds_read_b64 v[18:19], v2 offset:15872
	ds_read_b64 v[20:21], v2 offset:16384
	ds_read_b64 v[22:23], v2 offset:16896
	s_waitcnt lgkmcnt(7)
	v_fma_f32 v3, v8, v3, v9
	v_mul_f32_e32 v4, v4, v8
	s_waitcnt lgkmcnt(6)
	v_fma_f32 v3, v10, v3, v11
	v_mul_f32_e32 v4, v4, v10
	s_waitcnt lgkmcnt(5)
	v_fma_f32 v3, v12, v3, v13
	v_mul_f32_e32 v4, v4, v12
	s_waitcnt lgkmcnt(4)
	v_fma_f32 v3, v14, v3, v15
	v_mul_f32_e32 v4, v4, v14
	s_waitcnt lgkmcnt(3)
	v_fma_f32 v3, v16, v3, v17
	v_mul_f32_e32 v4, v4, v16
	s_waitcnt lgkmcnt(2)
	v_fma_f32 v3, v18, v3, v19
	v_mul_f32_e32 v4, v4, v18
	s_waitcnt lgkmcnt(1)
	v_fma_f32 v3, v20, v3, v21
	v_mul_f32_e32 v4, v4, v20
	s_waitcnt lgkmcnt(0)
	v_fma_f32 v3, v22, v3, v23
	v_mul_f32_e32 v4, v4, v22
	ds_read_b64 v[8:9], v2 offset:17408
	ds_read_b64 v[10:11], v2 offset:17920
	ds_read_b64 v[12:13], v2 offset:18432
	ds_read_b64 v[14:15], v2 offset:18944
	ds_read_b64 v[16:17], v2 offset:19456
	ds_read_b64 v[18:19], v2 offset:19968
	ds_read_b64 v[20:21], v2 offset:20480
	ds_read_b64 v[22:23], v2 offset:20992
	s_waitcnt lgkmcnt(7)
; DI void lru_item(const Params& p, int l, int b, int chunk, int blk, bool fin, char* smem, int tid) {
;     ...
;       for (int s2 = 0; s2 < 64; s2++) { const int t = dir ? 63 - s2 : s2; float2 v = au[(dir * 64 + t) * 64 + ch]; hst = v.x * hst + v.y; Ap *= v.x; }
	v_fma_f32 v3, v8, v3, v9
	v_mul_f32_e32 v4, v4, v8
	s_waitcnt lgkmcnt(6)
	v_fma_f32 v3, v10, v3, v11
	v_mul_f32_e32 v4, v4, v10
	s_waitcnt lgkmcnt(5)
	v_fma_f32 v3, v12, v3, v13
	v_mul_f32_e32 v4, v4, v12
	s_waitcnt lgkmcnt(4)
	v_fma_f32 v3, v14, v3, v15
	v_mul_f32_e32 v4, v4, v14
	s_waitcnt lgkmcnt(3)
	v_fma_f32 v3, v16, v3, v17
	v_mul_f32_e32 v4, v4, v16
	s_waitcnt lgkmcnt(2)
	v_fma_f32 v3, v18, v3, v19
	v_mul_f32_e32 v4, v4, v18
	s_waitcnt lgkmcnt(1)
	v_fma_f32 v3, v20, v3, v21
	v_mul_f32_e32 v4, v4, v20
	s_waitcnt lgkmcnt(0)
	v_fma_f32 v3, v22, v3, v23
	v_mul_f32_e32 v4, v4, v22
	ds_read_b64 v[8:9], v2 offset:21504
	ds_read_b64 v[10:11], v2 offset:22016
	ds_read_b64 v[12:13], v2 offset:22528
	ds_read_b64 v[14:15], v2 offset:23040
	ds_read_b64 v[16:17], v2 offset:23552
	ds_read_b64 v[18:19], v2 offset:24064
	ds_read_b64 v[20:21], v2 offset:24576
	ds_read_b64 v[22:23], v2 offset:25088
	s_waitcnt lgkmcnt(7)
	v_fma_f32 v3, v8, v3, v9
	v_mul_f32_e32 v4, v4, v8
	s_waitcnt lgkmcnt(6)
	v_fma_f32 v3, v10, v3, v11
	v_mul_f32_e32 v4, v4, v10
	s_waitcnt lgkmcnt(5)
	v_fma_f32 v3, v12, v3, v13
	v_mul_f32_e32 v4, v4, v12
	s_waitcnt lgkmcnt(4)
	v_fma_f32 v3, v14, v3, v15
	v_mul_f32_e32 v4, v4, v14
	s_waitcnt lgkmcnt(3)
	v_fma_f32 v3, v16, v3, v17
	v_mul_f32_e32 v4, v4, v16
	s_waitcnt lgkmcnt(2)
	v_fma_f32 v3, v18, v3, v19
	v_mul_f32_e32 v4, v4, v18
	s_waitcnt lgkmcnt(1)
	v_fma_f32 v3, v20, v3, v21
	v_mul_f32_e32 v4, v4, v20
	s_waitcnt lgkmcnt(0)
	v_fma_f32 v3, v22, v3, v23
	v_mul_f32_e32 v4, v4, v22
	ds_read_b64 v[8:9], v2 offset:25600
	ds_read_b64 v[10:11], v2 offset:26112
	ds_read_b64 v[12:13], v2 offset:26624
	ds_read_b64 v[14:15], v2 offset:27136
	ds_read_b64 v[16:17], v2 offset:27648
	ds_read_b64 v[18:19], v2 offset:28160
	ds_read_b64 v[20:21], v2 offset:28672
	ds_read_b64 v[22:23], v2 offset:29184
	s_waitcnt lgkmcnt(7)
	v_fma_f32 v3, v8, v3, v9
	v_mul_f32_e32 v4, v4, v8
	s_waitcnt lgkmcnt(6)
	v_fma_f32 v3, v10, v3, v11
	v_mul_f32_e32 v4, v4, v10
	s_waitcnt lgkmcnt(5)
	v_fma_f32 v3, v12, v3, v13
	v_mul_f32_e32 v4, v4, v12
	s_waitcnt lgkmcnt(4)
	v_fma_f32 v3, v14, v3, v15
	v_mul_f32_e32 v4, v4, v14
	s_waitcnt lgkmcnt(3)
	v_fma_f32 v3, v16, v3, v17
	v_mul_f32_e32 v4, v4, v16
	s_waitcnt lgkmcnt(2)
	v_fma_f32 v3, v18, v3, v19
	v_mul_f32_e32 v4, v4, v18
	s_waitcnt lgkmcnt(1)
	v_fma_f32 v3, v20, v3, v21
	v_mul_f32_e32 v4, v4, v20
	s_waitcnt lgkmcnt(0)
	v_fma_f32 v3, v22, v3, v23
	v_mul_f32_e32 v4, v4, v22
	ds_read_b64 v[8:9], v2 offset:29696
	ds_read_b64 v[10:11], v2 offset:30208
	ds_read_b64 v[12:13], v2 offset:30720
	ds_read_b64 v[14:15], v2 offset:31232
	ds_read_b64 v[16:17], v2 offset:31744
	ds_read_b64 v[18:19], v2 offset:32256
	ds_read_b64 v[20:21], v2 offset:32768
	ds_read_b64 v[22:23], v2 offset:33280
	s_waitcnt lgkmcnt(7)
	v_fma_f32 v3, v8, v3, v9
	v_mul_f32_e32 v4, v4, v8
	s_waitcnt lgkmcnt(6)
	v_fma_f32 v3, v10, v3, v11
	v_mul_f32_e32 v4, v4, v10
	s_waitcnt lgkmcnt(5)
	v_fma_f32 v3, v12, v3, v13
	v_mul_f32_e32 v4, v4, v12
	s_waitcnt lgkmcnt(4)
	v_fma_f32 v3, v14, v3, v15
	v_mul_f32_e32 v4, v4, v14
	s_waitcnt lgkmcnt(3)
	v_fma_f32 v3, v16, v3, v17
	v_mul_f32_e32 v4, v4, v16
	s_waitcnt lgkmcnt(2)
	v_fma_f32 v3, v18, v3, v19
	v_mul_f32_e32 v4, v4, v18
	s_waitcnt lgkmcnt(1)
	v_fma_f32 v3, v20, v3, v21
	v_mul_f32_e32 v4, v4, v20
	s_waitcnt lgkmcnt(0)
	v_fma_f32 v3, v22, v3, v23
	v_mul_f32_e32 v4, v4, v22
	ds_read_b64 v[8:9], v2 offset:33792
	ds_read_b64 v[10:11], v2 offset:34304
	ds_read_b64 v[12:13], v2 offset:34816
	ds_read_b64 v[14:15], v2 offset:35328
	ds_read_b64 v[16:17], v2 offset:35840
	ds_read_b64 v[18:19], v2 offset:36352
	ds_read_b64 v[20:21], v2 offset:36864
	ds_read_b64 v[22:23], v2 offset:37376
	s_waitcnt lgkmcnt(7)
	v_fma_f32 v3, v8, v3, v9
	v_mul_f32_e32 v4, v4, v8
	s_waitcnt lgkmcnt(6)
	v_fma_f32 v3, v10, v3, v11
	v_mul_f32_e32 v4, v4, v10
	s_waitcnt lgkmcnt(5)
	v_fma_f32 v3, v12, v3, v13
	v_mul_f32_e32 v4, v4, v12
	s_waitcnt lgkmcnt(4)
	v_fma_f32 v3, v14, v3, v15
	v_mul_f32_e32 v4, v4, v14
	s_waitcnt lgkmcnt(3)
	v_fma_f32 v3, v16, v3, v17
	v_mul_f32_e32 v4, v4, v16
	s_waitcnt lgkmcnt(2)
	v_fma_f32 v3, v18, v3, v19
	v_mul_f32_e32 v4, v4, v18
	s_waitcnt lgkmcnt(1)
	v_fma_f32 v3, v20, v3, v21
	v_mul_f32_e32 v4, v4, v20
	s_waitcnt lgkmcnt(0)
	v_fma_f32 v3, v22, v3, v23
	v_mul_f32_e32 v4, v4, v22
	ds_read_b64 v[8:9], v2 offset:37888
	ds_read_b64 v[10:11], v2 offset:38400
	ds_read_b64 v[12:13], v2 offset:38912
	ds_read_b64 v[14:15], v2 offset:39424
	ds_read_b64 v[16:17], v2 offset:39936
	ds_read_b64 v[18:19], v2 offset:40448
	ds_read_b64 v[20:21], v2 offset:40960
	ds_read_b64 v[22:23], v2 offset:41472
	s_waitcnt lgkmcnt(7)
	v_fma_f32 v3, v8, v3, v9
	v_mul_f32_e32 v4, v4, v8
	s_waitcnt lgkmcnt(6)
	v_fma_f32 v3, v10, v3, v11
	v_mul_f32_e32 v4, v4, v10
	s_waitcnt lgkmcnt(5)
	v_fma_f32 v3, v12, v3, v13
	v_mul_f32_e32 v4, v4, v12
	s_waitcnt lgkmcnt(4)
	v_fma_f32 v3, v14, v3, v15
	v_mul_f32_e32 v4, v4, v14
	s_waitcnt lgkmcnt(3)
	v_fma_f32 v3, v16, v3, v17
	v_mul_f32_e32 v4, v4, v16
	s_waitcnt lgkmcnt(2)
	v_fma_f32 v3, v18, v3, v19
	v_mul_f32_e32 v4, v4, v18
	s_waitcnt lgkmcnt(1)
	v_fma_f32 v3, v20, v3, v21
	v_mul_f32_e32 v4, v4, v20
	s_waitcnt lgkmcnt(0)
	v_fma_f32 v3, v22, v3, v23
	v_mul_f32_e32 v4, v4, v22
	s_branch .Llp_done
; DI void lru_item(const Params& p, int l, int b, int chunk, int blk, bool fin, char* smem, int tid) {
;     ...
;       for (int s2 = 0; s2 < 64; s2++) { const int t = dir ? 63 - s2 : s2; float2 v = au[(dir * 64 + t) * 64 + ch]; hst = v.x * hst + v.y; Ap *= v.x; }
.Llp_scan1:
	ds_read_b64 v[8:9], v2 offset:41472
	ds_read_b64 v[10:11], v2 offset:40960
	ds_read_b64 v[12:13], v2 offset:40448
	ds_read_b64 v[14:15], v2 offset:39936
	ds_read_b64 v[16:17], v2 offset:39424
	ds_read_b64 v[18:19], v2 offset:38912
	ds_read_b64 v[20:21], v2 offset:38400
	ds_read_b64 v[22:23], v2 offset:37888
	s_waitcnt lgkmcnt(7)
	v_fma_f32 v3, v8, v3, v9
	v_mul_f32_e32 v4, v4, v8
	s_waitcnt lgkmcnt(6)
	v_fma_f32 v3, v10, v3, v11
	v_mul_f32_e32 v4, v4, v10
	s_waitcnt lgkmcnt(5)
	v_fma_f32 v3, v12, v3, v13
	v_mul_f32_e32 v4, v4, v12
	s_waitcnt lgkmcnt(4)
	v_fma_f32 v3, v14, v3, v15
	v_mul_f32_e32 v4, v4, v14
	s_waitcnt lgkmcnt(3)
	v_fma_f32 v3, v16, v3, v17
	v_mul_f32_e32 v4, v4, v16
	s_waitcnt lgkmcnt(2)
	v_fma_f32 v3, v18, v3, v19
	v_mul_f32_e32 v4, v4, v18
	s_waitcnt lgkmcnt(1)
	v_fma_f32 v3, v20, v3, v21
	v_mul_f32_e32 v4, v4, v20
	s_waitcnt lgkmcnt(0)
	v_fma_f32 v3, v22, v3, v23
	v_mul_f32_e32 v4, v4, v22
	ds_read_b64 v[8:9], v2 offset:37376
	ds_read_b64 v[10:11], v2 offset:36864
	ds_read_b64 v[12:13], v2 offset:36352
	ds_read_b64 v[14:15], v2 offset:35840
	ds_read_b64 v[16:17], v2 offset:35328
	ds_read_b64 v[18:19], v2 offset:34816
	ds_read_b64 v[20:21], v2 offset:34304
	ds_read_b64 v[22:23], v2 offset:33792
	s_waitcnt lgkmcnt(7)
	v_fma_f32 v3, v8, v3, v9
	v_mul_f32_e32 v4, v4, v8
	s_waitcnt lgkmcnt(6)
	v_fma_f32 v3, v10, v3, v11
	v_mul_f32_e32 v4, v4, v10
	s_waitcnt lgkmcnt(5)
	v_fma_f32 v3, v12, v3, v13
	v_mul_f32_e32 v4, v4, v12
	s_waitcnt lgkmcnt(4)
	v_fma_f32 v3, v14, v3, v15
	v_mul_f32_e32 v4, v4, v14
	s_waitcnt lgkmcnt(3)
	v_fma_f32 v3, v16, v3, v17
	v_mul_f32_e32 v4, v4, v16
	s_waitcnt lgkmcnt(2)
	v_fma_f32 v3, v18, v3, v19
	v_mul_f32_e32 v4, v4, v18
	s_waitcnt lgkmcnt(1)
	v_fma_f32 v3, v20, v3, v21
	v_mul_f32_e32 v4, v4, v20
	s_waitcnt lgkmcnt(0)
	v_fma_f32 v3, v22, v3, v23
	v_mul_f32_e32 v4, v4, v22
	ds_read_b64 v[8:9], v2 offset:33280
	ds_read_b64 v[10:11], v2 offset:32768
	ds_read_b64 v[12:13], v2 offset:32256
	ds_read_b64 v[14:15], v2 offset:31744
	ds_read_b64 v[16:17], v2 offset:31232
	ds_read_b64 v[18:19], v2 offset:30720
	ds_read_b64 v[20:21], v2 offset:30208
	ds_read_b64 v[22:23], v2 offset:29696
	s_waitcnt lgkmcnt(7)
	v_fma_f32 v3, v8, v3, v9
	v_mul_f32_e32 v4, v4, v8
	s_waitcnt lgkmcnt(6)
	v_fma_f32 v3, v10, v3, v11
	v_mul_f32_e32 v4, v4, v10
	s_waitcnt lgkmcnt(5)
	v_fma_f32 v3, v12, v3, v13
	v_mul_f32_e32 v4, v4, v12
	s_waitcnt lgkmcnt(4)
	v_fma_f32 v3, v14, v3, v15
	v_mul_f32_e32 v4, v4, v14
	s_waitcnt lgkmcnt(3)
	v_fma_f32 v3, v16, v3, v17
	v_mul_f32_e32 v4, v4, v16
	s_waitcnt lgkmcnt(2)
	v_fma_f32 v3, v18, v3, v19
	v_mul_f32_e32 v4, v4, v18
	s_waitcnt lgkmcnt(1)
	v_fma_f32 v3, v20, v3, v21
	v_mul_f32_e32 v4, v4, v20
	s_waitcnt lgkmcnt(0)
	v_fma_f32 v3, v22, v3, v23
	v_mul_f32_e32 v4, v4, v22
	ds_read_b64 v[8:9], v2 offset:29184
	ds_read_b64 v[10:11], v2 offset:28672
	ds_read_b64 v[12:13], v2 offset:28160
	ds_read_b64 v[14:15], v2 offset:27648
	ds_read_b64 v[16:17], v2 offset:27136
	ds_read_b64 v[18:19], v2 offset:26624
	ds_read_b64 v[20:21], v2 offset:26112
	ds_read_b64 v[22:23], v2 offset:25600
	s_waitcnt lgkmcnt(7)
	v_fma_f32 v3, v8, v3, v9
	v_mul_f32_e32 v4, v4, v8
	s_waitcnt lgkmcnt(6)
	v_fma_f32 v3, v10, v3, v11
	v_mul_f32_e32 v4, v4, v10
	s_waitcnt lgkmcnt(5)
	v_fma_f32 v3, v12, v3, v13
	v_mul_f32_e32 v4, v4, v12
	s_waitcnt lgkmcnt(4)
	v_fma_f32 v3, v14, v3, v15
	v_mul_f32_e32 v4, v4, v14
	s_waitcnt lgkmcnt(3)
	v_fma_f32 v3, v16, v3, v17
	v_mul_f32_e32 v4, v4, v16
	s_waitcnt lgkmcnt(2)
	v_fma_f32 v3, v18, v3, v19
	v_mul_f32_e32 v4, v4, v18
	s_waitcnt lgkmcnt(1)
	v_fma_f32 v3, v20, v3, v21
	v_mul_f32_e32 v4, v4, v20
	s_waitcnt lgkmcnt(0)
	v_fma_f32 v3, v22, v3, v23
	v_mul_f32_e32 v4, v4, v22
	ds_read_b64 v[8:9], v2 offset:25088
	ds_read_b64 v[10:11], v2 offset:24576
	ds_read_b64 v[12:13], v2 offset:24064
	ds_read_b64 v[14:15], v2 offset:23552
	ds_read_b64 v[16:17], v2 offset:23040
	ds_read_b64 v[18:19], v2 offset:22528
	ds_read_b64 v[20:21], v2 offset:22016
	ds_read_b64 v[22:23], v2 offset:21504
	s_waitcnt lgkmcnt(7)
; DI void lru_item(const Params& p, int l, int b, int chunk, int blk, bool fin, char* smem, int tid) {
;     ...
;       for (int s2 = 0; s2 < 64; s2++) { const int t = dir ? 63 - s2 : s2; float2 v = au[(dir * 64 + t) * 64 + ch]; hst = v.x * hst + v.y; Ap *= v.x; }
;       agg[(((size_t)b * 68 + chunk) * 2 + dir) * 256 + c0 + ch] = make_float2(Ap, hst);
	v_fma_f32 v3, v8, v3, v9
	v_mul_f32_e32 v4, v4, v8
	s_waitcnt lgkmcnt(6)
	v_fma_f32 v3, v10, v3, v11
	v_mul_f32_e32 v4, v4, v10
	s_waitcnt lgkmcnt(5)
	v_fma_f32 v3, v12, v3, v13
	v_mul_f32_e32 v4, v4, v12
	s_waitcnt lgkmcnt(4)
	v_fma_f32 v3, v14, v3, v15
	v_mul_f32_e32 v4, v4, v14
	s_waitcnt lgkmcnt(3)
	v_fma_f32 v3, v16, v3, v17
	v_mul_f32_e32 v4, v4, v16
	s_waitcnt lgkmcnt(2)
	v_fma_f32 v3, v18, v3, v19
	v_mul_f32_e32 v4, v4, v18
	s_waitcnt lgkmcnt(1)
	v_fma_f32 v3, v20, v3, v21
	v_mul_f32_e32 v4, v4, v20
	s_waitcnt lgkmcnt(0)
	v_fma_f32 v3, v22, v3, v23
	v_mul_f32_e32 v4, v4, v22
	ds_read_b64 v[8:9], v2 offset:20992
	ds_read_b64 v[10:11], v2 offset:20480
	ds_read_b64 v[12:13], v2 offset:19968
	ds_read_b64 v[14:15], v2 offset:19456
	ds_read_b64 v[16:17], v2 offset:18944
	ds_read_b64 v[18:19], v2 offset:18432
	ds_read_b64 v[20:21], v2 offset:17920
	ds_read_b64 v[22:23], v2 offset:17408
	s_waitcnt lgkmcnt(7)
	v_fma_f32 v3, v8, v3, v9
	v_mul_f32_e32 v4, v4, v8
	s_waitcnt lgkmcnt(6)
	v_fma_f32 v3, v10, v3, v11
	v_mul_f32_e32 v4, v4, v10
	s_waitcnt lgkmcnt(5)
	v_fma_f32 v3, v12, v3, v13
	v_mul_f32_e32 v4, v4, v12
	s_waitcnt lgkmcnt(4)
	v_fma_f32 v3, v14, v3, v15
	v_mul_f32_e32 v4, v4, v14
	s_waitcnt lgkmcnt(3)
	v_fma_f32 v3, v16, v3, v17
	v_mul_f32_e32 v4, v4, v16
	s_waitcnt lgkmcnt(2)
	v_fma_f32 v3, v18, v3, v19
	v_mul_f32_e32 v4, v4, v18
	s_waitcnt lgkmcnt(1)
	v_fma_f32 v3, v20, v3, v21
	v_mul_f32_e32 v4, v4, v20
	s_waitcnt lgkmcnt(0)
	v_fma_f32 v3, v22, v3, v23
	v_mul_f32_e32 v4, v4, v22
	ds_read_b64 v[8:9], v2 offset:16896
	ds_read_b64 v[10:11], v2 offset:16384
	ds_read_b64 v[12:13], v2 offset:15872
	ds_read_b64 v[14:15], v2 offset:15360
	ds_read_b64 v[16:17], v2 offset:14848
	ds_read_b64 v[18:19], v2 offset:14336
	ds_read_b64 v[20:21], v2 offset:13824
	ds_read_b64 v[22:23], v2 offset:13312
	s_waitcnt lgkmcnt(7)
	v_fma_f32 v3, v8, v3, v9
	v_mul_f32_e32 v4, v4, v8
	s_waitcnt lgkmcnt(6)
	v_fma_f32 v3, v10, v3, v11
	v_mul_f32_e32 v4, v4, v10
	s_waitcnt lgkmcnt(5)
	v_fma_f32 v3, v12, v3, v13
	v_mul_f32_e32 v4, v4, v12
	s_waitcnt lgkmcnt(4)
	v_fma_f32 v3, v14, v3, v15
	v_mul_f32_e32 v4, v4, v14
	s_waitcnt lgkmcnt(3)
	v_fma_f32 v3, v16, v3, v17
	v_mul_f32_e32 v4, v4, v16
	s_waitcnt lgkmcnt(2)
	v_fma_f32 v3, v18, v3, v19
	v_mul_f32_e32 v4, v4, v18
	s_waitcnt lgkmcnt(1)
	v_fma_f32 v3, v20, v3, v21
	v_mul_f32_e32 v4, v4, v20
	s_waitcnt lgkmcnt(0)
	v_fma_f32 v3, v22, v3, v23
	v_mul_f32_e32 v4, v4, v22
	ds_read_b64 v[8:9], v2 offset:12800
	ds_read_b64 v[10:11], v2 offset:12288
	ds_read_b64 v[12:13], v2 offset:11776
	ds_read_b64 v[14:15], v2 offset:11264
	ds_read_b64 v[16:17], v2 offset:10752
	ds_read_b64 v[18:19], v2 offset:10240
	ds_read_b64 v[20:21], v2 offset:9728
	ds_read_b64 v[22:23], v2 offset:9216
	s_waitcnt lgkmcnt(7)
	v_fma_f32 v3, v8, v3, v9
	v_mul_f32_e32 v4, v4, v8
	s_waitcnt lgkmcnt(6)
	v_fma_f32 v3, v10, v3, v11
	v_mul_f32_e32 v4, v4, v10
	s_waitcnt lgkmcnt(5)
	v_fma_f32 v3, v12, v3, v13
	v_mul_f32_e32 v4, v4, v12
	s_waitcnt lgkmcnt(4)
	v_fma_f32 v3, v14, v3, v15
	v_mul_f32_e32 v4, v4, v14
	s_waitcnt lgkmcnt(3)
	v_fma_f32 v3, v16, v3, v17
	v_mul_f32_e32 v4, v4, v16
	s_waitcnt lgkmcnt(2)
	v_fma_f32 v3, v18, v3, v19
	v_mul_f32_e32 v4, v4, v18
	s_waitcnt lgkmcnt(1)
	v_fma_f32 v3, v20, v3, v21
	v_mul_f32_e32 v4, v4, v20
	s_waitcnt lgkmcnt(0)
	v_fma_f32 v3, v22, v3, v23
	v_mul_f32_e32 v4, v4, v22
.Llp_done:
	s_ashr_i32 s8, s2, 31
	s_ashr_i32 s9, s3, 31
	s_add_u32 s2, s2, s3
	s_addc_u32 s3, s8, s9
	s_lshl_b64 s[2:3], s[2:3], 12
	v_lshl_add_u64 v[6:7], v[44:45], 0, s[2:3]
	v_lshl_add_u64 v[6:7], v[52:53], 3, v[6:7]
	v_mov_b32_e32 v51, v1
	v_lshl_add_u64 v[6:7], v[6:7], 0, v[50:51]
	v_mov_b32_e32 v5, v3
	global_store_dwordx2 v[6:7], v[4:5], off
	s_branch .LBB0_783

; #define MFMA(a, b, c) __builtin_amdgcn_mfma_f32_32x32x16_bf16((a), (b), (c), 0, 0, 0)
; DI u16 f2bf(float x) { return (u16)(pack2(x, 0.f) & 0xffffu); }
; DI float bf2f(u16 v) { return __uint_as_float(((unsigned)v) << 16); }
; DI void lru_item(const Params& p, int l, int b, int chunk, int blk, bool fin, char* smem, int tid) {
;     ...
;     const int ch = tid & 63;
;     const float* cw = p.cw + (size_t)l * 4 * 256 + c0 + ch;
;     const float w0 = cw[0], w1 = cw[256], w2 = cw[512], w3 = cw[768], bias = p.cb[l * 256 + c0 + ch];
; #pragma unroll 4
;     for (int e = 0; e < 16; e++) {
;       const int t = (tid >> 6) + 4 * e;
;       float v = w0 * bf2f(xr[t * 64 + ch]) + w1 * bf2f(xr[(t + 1) * 64 + ch]) + w2 * bf2f(xr[(t + 2) * 64 + ch]) + w3 * bf2f(xr[(t + 3) * 64 + ch]) + bias;
;       xcb[t][ch] = f2bf(v);
;     }
;   }
;   __syncthreads();
;   {
;     const int tb = w & 1, ob = w >> 1;
;     const int chn = ob * 32 + r;
; #pragma unroll
;     for (int dir = 0; dir < 2; dir++) {
;       f32x16 ga, gx;
; #pragma unroll
;       for (int i = 0; i < 16; i++) { ga[i] = 0.f; gx[i] = 0.f; }
;       const u16* wa = p.WtA + (((size_t)l * 2 + dir) * 4 + blk) * 4096 + (size_t)chn * 64 + h * 8;
;       const u16* wx = p.WtX + (((size_t)l * 2 + dir) * 4 + blk) * 4096 + (size_t)chn * 64 + h * 8;
; #pragma unroll
;       for (int ks = 0; ks < 4; ks++) {
;         bf16x8 a = *(const bf16x8*)&xcb[tb * 32 + r][ks * 16 + h * 8];
;         bf16x8 ba = *(const bf16x8*)(wa + ks * 16), bx = *(const bf16x8*)(wx + ks * 16);
;         ga = MFMA(a, ba, ga); gx = MFMA(a, bx, gx);
;       }
;       const int pi = (l * 2 + dir) * 256 + c0 + chn;
;       const float b_a = p.ba[pi], b_x = p.bx[pi], lam = p.lam[pi];
.LBB0_1049:
	ds_read_u16 v7, v6 offset:9216
	ds_read_u16 v8, v6 offset:9344
	ds_read_u16 v11, v6 offset:9472
	ds_read_u16 v12, v6 offset:9600
	v_add_u32_e32 v14, s0, v60
	s_addk_i32 s0, 0x900
	s_waitcnt lgkmcnt(2)
	v_lshlrev_b32_e32 v9, 16, v8
	v_lshlrev_b32_e32 v8, 16, v7
	s_waitcnt lgkmcnt(0)
	v_lshlrev_b32_e32 v13, 16, v12
	v_lshlrev_b32_e32 v12, 16, v11
	s_waitcnt vmcnt(3)
	v_pk_mul_f32 v[8:9], v[2:3], v[8:9]
	s_waitcnt vmcnt(1)
	v_pk_mul_f32 v[12:13], v[4:5], v[12:13]
	v_add_f32_e32 v7, v8, v9
	v_add_f32_e32 v7, v7, v12
	v_add_f32_e32 v7, v7, v13
	s_waitcnt vmcnt(0)
	v_add_f32_e32 v7, v0, v7
	v_cvt_pk_bf16_f32 v7, v7, s0
	ds_write_b16 v14, v7
	ds_read_u16 v7, v6 offset:9856
	ds_read_u16 v11, v6 offset:9984
	ds_read_u16 v8, v6 offset:9728
	ds_read_u16 v12, v6 offset:10112
	s_cmpk_eq_i32 s0, 0x2400
	s_waitcnt lgkmcnt(3)
	v_lshlrev_b32_e32 v9, 16, v7
	s_waitcnt lgkmcnt(1)
	v_lshlrev_b32_e32 v8, 16, v8
	s_waitcnt lgkmcnt(0)
	v_lshlrev_b32_e32 v13, 16, v12
	v_lshlrev_b32_e32 v12, 16, v11
	v_pk_mul_f32 v[8:9], v[2:3], v[8:9]
	v_pk_mul_f32 v[12:13], v[4:5], v[12:13]
	v_add_f32_e32 v7, v8, v9
	v_add_f32_e32 v7, v7, v12
	v_add_f32_e32 v7, v7, v13
	v_add_f32_e32 v7, v0, v7
	v_cvt_pk_bf16_f32 v7, v7, s0
	ds_write_b16 v14, v7 offset:576
	ds_read_u16 v7, v6 offset:10368
	ds_read_u16 v11, v6 offset:10496
	ds_read_u16 v8, v6 offset:10240
	ds_read_u16 v12, v6 offset:10624
	s_waitcnt lgkmcnt(3)
	v_lshlrev_b32_e32 v9, 16, v7
	s_waitcnt lgkmcnt(1)
	v_lshlrev_b32_e32 v8, 16, v8
	s_waitcnt lgkmcnt(0)
	v_lshlrev_b32_e32 v13, 16, v12
	v_lshlrev_b32_e32 v12, 16, v11
	v_pk_mul_f32 v[8:9], v[2:3], v[8:9]
	v_pk_mul_f32 v[12:13], v[4:5], v[12:13]
	v_add_f32_e32 v7, v8, v9
	v_add_f32_e32 v7, v7, v12
	v_add_f32_e32 v7, v7, v13
	v_add_f32_e32 v7, v0, v7
	v_cvt_pk_bf16_f32 v7, v7, s0
	ds_write_b16 v14, v7 offset:1152
	ds_read_u16 v7, v6 offset:10880
	ds_read_u16 v11, v6 offset:11008
	ds_read_u16 v8, v6 offset:10752
	ds_read_u16 v12, v6 offset:11136
	v_add_u32_e32 v6, 0x800, v6
	s_waitcnt lgkmcnt(3)
	v_lshlrev_b32_e32 v9, 16, v7
	s_waitcnt lgkmcnt(1)
	v_lshlrev_b32_e32 v8, 16, v8
	s_waitcnt lgkmcnt(0)
	v_lshlrev_b32_e32 v13, 16, v12
	v_lshlrev_b32_e32 v12, 16, v11
	v_pk_mul_f32 v[8:9], v[2:3], v[8:9]
	v_pk_mul_f32 v[12:13], v[4:5], v[12:13]
	v_add_f32_e32 v7, v8, v9
	v_add_f32_e32 v7, v7, v12
	v_add_f32_e32 v7, v7, v13
	v_add_f32_e32 v7, v0, v7
	v_cvt_pk_bf16_f32 v7, v7, s0
	ds_write_b16 v14, v7 offset:1728
	s_cbranch_scc0 .LBB0_1049
	v_lshl_or_b32 v2, v10, 12, s16
	v_mov_b32_e32 v3, s17
	v_lshlrev_b64 v[80:81], 1, v[2:3]
	v_lshl_add_u64 v[114:115], v[54:55], 0, v[80:81]
	s_waitcnt lgkmcnt(0)
	s_barrier
	v_lshl_add_u64 v[116:117], v[56:57], 0, v[80:81]
	global_load_dwordx4 v[2:5], v[114:115], off
	global_load_dwordx4 v[6:9], v[116:117], off
	ds_read_b128 v[10:13], v87
	ds_read_b128 v[82:85], v87 offset:32
	global_load_dwordx4 v[106:109], v[114:115], off offset:32
	global_load_dwordx4 v[110:113], v[116:117], off offset:32
	v_or_b32_e32 v0, s94, v74
	v_add_u32_e32 v78, v0, v38
	v_ashrrev_i32_e32 v79, 31, v78
	v_readlane_b32 s52, v252, 16
	v_lshlrev_b64 v[78:79], 2, v[78:79]
	v_readlane_b32 s53, v252, 17
	v_readlane_b32 s54, v252, 18
	v_readlane_b32 s55, v252, 19
	v_readlane_b32 s56, v252, 20
	v_readlane_b32 s57, v252, 21
	v_readlane_b32 s58, v252, 22
	v_readlane_b32 s59, v252, 23
	v_readlane_b32 s60, v252, 24
	v_readlane_b32 s61, v252, 25
	v_readlane_b32 s62, v252, 26
	v_readlane_b32 s63, v252, 27
	v_readlane_b32 s64, v252, 28
	v_readlane_b32 s65, v252, 29
	v_readlane_b32 s66, v252, 30
	v_readlane_b32 s67, v252, 31
	s_mov_b32 s2, 0x3f2aaaab
	s_mov_b32 s3, 0x3f317218
	s_mov_b32 s20, 0x7f800000
	s_mov_b32 s21, 0x33800000
	s_mov_b32 s24, 0xc1000000
	s_mov_b32 s22, 0xbe800000
	v_or_b32_e32 v80, 0x8000, v80
	s_waitcnt vmcnt(3) lgkmcnt(1)
	v_mfma_f32_32x32x16_bf16 v[18:33], v[10:13], v[2:5], 0
	s_waitcnt vmcnt(2)
	v_mfma_f32_32x32x16_bf16 v[2:17], v[10:13], v[6:9], 0
	s_waitcnt vmcnt(1) lgkmcnt(0)
	v_mfma_f32_32x32x16_bf16 v[18:33], v[82:85], v[106:109], v[18:33]
	s_waitcnt vmcnt(0)
	v_mfma_f32_32x32x16_bf16 v[2:17], v[82:85], v[110:113], v[2:17]
	ds_read_b128 v[82:85], v87 offset:64
	global_load_dwordx4 v[106:109], v[114:115], off offset:64
	global_load_dwordx4 v[110:113], v[116:117], off offset:64
	s_waitcnt vmcnt(1) lgkmcnt(0)
	v_mfma_f32_32x32x16_bf16 v[18:33], v[82:85], v[106:109], v[18:33]
	s_waitcnt vmcnt(0)
	v_mfma_f32_32x32x16_bf16 v[2:17], v[82:85], v[110:113], v[2:17]
	ds_read_b128 v[82:85], v87 offset:96
	global_load_dwordx4 v[106:109], v[114:115], off offset:96
	global_load_dwordx4 v[110:113], v[116:117], off offset:96
	s_waitcnt vmcnt(1) lgkmcnt(0)
	v_mfma_f32_32x32x16_bf16 v[18:33], v[82:85], v[106:109], v[18:33]
	s_waitcnt vmcnt(0)
	v_mfma_f32_32x32x16_bf16 v[2:17], v[82:85], v[110:113], v[2:17]
	v_lshl_add_u64 v[82:83], s[66:67], 0, v[78:79]
	v_readlane_b32 s52, v252, 32
	v_readlane_b32 s54, v252, 34
	v_readlane_b32 s55, v252, 35
	v_readlane_b32 s56, v252, 36
	v_readlane_b32 s57, v252, 37
	v_lshl_add_u64 v[84:85], s[54:55], 0, v[78:79]
	global_load_dword v107, v[84:85], off
	v_lshl_add_u64 v[78:79], s[56:57], 0, v[78:79]
	global_load_dword v0, v[78:79], off
	global_load_dword v71, v[82:83], off
	v_readlane_b32 s53, v252, 33
	v_readlane_b32 s58, v252, 38
	v_readlane_b32 s59, v252, 39
	v_readlane_b32 s60, v252, 40
	v_readlane_b32 s61, v252, 41
	v_readlane_b32 s62, v252, 42
	v_readlane_b32 s63, v252, 43
	v_readlane_b32 s64, v252, 44
	v_readlane_b32 s65, v252, 45
	v_readlane_b32 s66, v252, 46
	v_readlane_b32 s67, v252, 47
	s_waitcnt vmcnt(2)
	v_add_f32_e32 v2, v2, v107
	v_mul_f32_e32 v2, 0xbfb8aa3b, v2
	s_waitcnt vmcnt(1)
; DI float bf2f(u16 v) { return __uint_as_float(((unsigned)v) << 16); }
; DI int crow(int i, int h) { return (i & 3) + 8 * (i >> 2) + 4 * h; }
; DI void lru_item(const Params& p, int l, int b, int chunk, int blk, bool fin, char* smem, int tid) {
;     ...
;       const float sp = log1pf(__expf(-lam));
; #pragma unroll
;       for (int i = 0; i < 16; i++) {
;         const int tok = tb * 32 + crow(i, h);
;         const float rr = __builtin_amdgcn_rcpf(1.f + __expf(-(ga[i] + b_a))), ii = __builtin_amdgcn_rcpf(1.f + __expf(-(gx[i] + b_x)));
;         const float la = -8.f * rr * sp;
;         const float a = __expf(la);
;         const float x2 = 2.f * la;
;         const float ser = -x2 * (1.f + x2 * (0.5f + x2 * (0.16666667f + x2 * (0.041666668f + x2 * 0.0083333338f))));
;         const float om = (x2 > -0.25f) ? ser : (1.f - a * a);
;         const float u = __builtin_amdgcn_sqrtf(fmaxf(om, 0.f)) * ii * bf2f(xcb[tok][chn]);
;         au[(dir * 64 + tok) * 64 + chn] = make_float2(a, u);
	v_mul_f32_e32 v0, 0xbfb8aa3b, v0
	v_exp_f32_e32 v0, v0
	v_exp_f32_e32 v2, v2
	s_waitcnt vmcnt(0)
	v_add_f32_e32 v18, v18, v71
	v_mul_f32_e32 v18, 0xbfb8aa3b, v18
	v_add_f32_e32 v106, 1.0, v0
	v_add_f32_e32 v108, -1.0, v106
	v_sub_f32_e32 v109, v108, v106
	v_add_f32_e32 v109, 1.0, v109
	v_sub_f32_e32 v108, v0, v108
	v_add_f32_e32 v110, v108, v109
	v_frexp_mant_f32_e32 v108, v106
	v_cmp_gt_f32_e64 s[0:1], s2, v108
	v_cvt_f64_f32_e32 v[108:109], v106
	v_frexp_exp_i32_f64_e32 v108, v[108:109]
	v_subbrev_co_u32_e64 v116, s[0:1], 0, v108, s[0:1]
	v_sub_u32_e32 v108, 0, v116
	v_ldexp_f32 v106, v106, v108
	v_ldexp_f32 v108, v110, v108
	v_add_f32_e32 v110, -1.0, v106
	v_add_f32_e32 v109, 1.0, v110
	v_sub_f32_e32 v109, v106, v109
	v_add_f32_e32 v111, v108, v109
	v_add_f32_e32 v109, 1.0, v106
	v_add_f32_e32 v112, -1.0, v109
	v_sub_f32_e32 v106, v106, v112
	v_add_f32_e32 v106, v108, v106
	v_add_f32_e32 v117, v109, v106
	v_rcp_f32_e32 v118, v117
	v_sub_f32_e32 v108, v117, v109
	v_add_f32_e32 v109, v110, v111
	v_sub_f32_e32 v106, v106, v108
	v_mul_f32_e32 v120, v109, v118
	v_sub_f32_e32 v108, v109, v110
	v_mul_f32_e32 v110, v117, v120
	v_fma_f32 v112, v120, v117, -v110
	v_fmac_f32_e32 v112, v120, v106
	v_sub_f32_e32 v119, v111, v108
	v_add_f32_e32 v108, v110, v112
	v_sub_f32_e32 v111, v109, v108
	v_pk_add_f32 v[114:115], v[108:109], v[110:111] neg_lo:[0,1] neg_hi:[0,1]
	v_mov_b32_e32 v113, v108
	v_pk_add_f32 v[108:109], v[114:115], v[112:113] neg_lo:[0,1] neg_hi:[0,1]
	v_cmp_neq_f32_e64 s[0:1], s20, v0
	v_add_f32_e32 v109, v119, v109
	v_add_f32_e32 v108, v108, v109
	v_add_f32_e32 v109, v111, v108
	v_mul_f32_e32 v119, v118, v109
	v_mul_f32_e32 v110, v117, v119
	v_fma_f32 v112, v119, v117, -v110
	v_fmac_f32_e32 v112, v119, v106
	v_sub_f32_e32 v106, v111, v109
	v_add_f32_e32 v106, v108, v106
	v_add_f32_e32 v108, v110, v112
	v_sub_f32_e32 v111, v109, v108
	v_pk_add_f32 v[114:115], v[108:109], v[110:111] neg_lo:[0,1] neg_hi:[0,1]
	v_mov_b32_e32 v113, v108
	v_pk_add_f32 v[108:109], v[114:115], v[112:113] neg_lo:[0,1] neg_hi:[0,1]
	v_add_f32_e32 v2, 1.0, v2
	v_add_f32_e32 v106, v106, v109
	v_add_f32_e32 v106, v108, v106
	v_add_f32_e32 v109, v120, v119
	v_add_f32_e32 v106, v111, v106
	v_sub_f32_e32 v108, v109, v120
	v_mul_f32_e32 v106, v118, v106
	v_sub_f32_e32 v108, v119, v108
	v_add_f32_e32 v106, v108, v106
	v_add_f32_e32 v110, v109, v106
	v_mul_f32_e32 v112, v110, v110
	v_fmamk_f32 v108, v112, 0x3e9b6dac, v211
	v_fmaak_f32 v153, v112, v108, 0x3f2aaada
	v_cvt_f32_i32_e32 v108, v116
	v_sub_f32_e32 v109, v110, v109
	v_sub_f32_e32 v106, v106, v109
	v_mul_f32_e32 v109, v110, v112
	v_pk_mul_f32 v[112:113], v[108:109], v[152:153]
	v_ldexp_f32 v111, v110, 1
	v_fma_f32 v110, v108, s3, -v112
	v_fmac_f32_e32 v110, 0xb102e308, v108
	v_pk_add_f32 v[108:109], v[112:113], v[110:111]
	v_ldexp_f32 v106, v106, 1
	v_sub_f32_e32 v111, v109, v111
	v_sub_f32_e32 v111, v113, v111
	v_add_f32_e32 v115, v106, v111
	v_mov_b32_e32 v114, v112
	v_pk_add_f32 v[112:113], v[108:109], v[112:113] neg_lo:[0,1] neg_hi:[0,1]
	v_pk_add_f32 v[116:117], v[108:109], v[114:115]
	v_mov_b32_e32 v111, v108
	v_mov_b32_e32 v113, v117
	v_pk_add_f32 v[118:119], v[110:111], v[112:113] neg_lo:[0,1] neg_hi:[0,1]
	v_pk_add_f32 v[110:111], v[110:111], v[112:113]
	v_mov_b32_e32 v114, v115
	v_pk_add_f32 v[112:113], v[110:111], v[108:109] op_sel:[1,0] op_sel_hi:[0,1] neg_lo:[0,1] neg_hi:[0,1]
	v_pk_add_f32 v[120:121], v[116:117], v[112:113] op_sel_hi:[1,0] neg_lo:[0,1] neg_hi:[0,1]
	v_mov_b32_e32 v116, v117
	v_mov_b32_e32 v117, v111
	v_pk_mov_b32 v[112:113], v[108:109], v[112:113] op_sel:[1,0]
	v_mov_b32_e32 v115, v108
	v_pk_add_f32 v[112:113], v[116:117], v[112:113] neg_lo:[0,1] neg_hi:[0,1]
	v_mov_b32_e32 v120, v118
	v_pk_add_f32 v[108:109], v[114:115], v[112:113] neg_lo:[0,1] neg_hi:[0,1]
	v_mov_b32_e32 v119, v111
	v_pk_add_f32 v[112:113], v[120:121], v[108:109]
	v_exp_f32_e32 v18, v18
	v_pk_add_f32 v[114:115], v[112:113], v[112:113] op_sel:[0,1] op_sel_hi:[1,0]
	v_lshl_add_u64 v[120:121], v[54:55], 0, v[80:81]
	v_pk_add_f32 v[110:111], v[110:111], v[114:115] op_sel:[1,0] op_sel_hi:[0,1]
	v_mov_b32_e32 v113, v110
	v_pk_add_f32 v[116:117], v[112:113], v[118:119] neg_lo:[0,1] neg_hi:[0,1]
	v_mov_b32_e32 v109, v114
	v_sub_f32_e32 v106, v112, v116
	v_pk_add_f32 v[108:109], v[108:109], v[116:117] neg_lo:[0,1] neg_hi:[0,1]
	v_sub_f32_e32 v106, v118, v106
	v_add_f32_e32 v106, v108, v106
	v_add_f32_e32 v106, v106, v109
	v_add_f32_e32 v106, v110, v106
	v_cndmask_b32_e64 v106, v217, v106, s[0:1]
	v_cmp_ngt_f32_e64 s[0:1], -1.0, v0
	v_add_f32_e32 v18, 1.0, v18
	v_rcp_f32_e32 v109, v18
	v_cndmask_b32_e64 v106, v218, v106, s[0:1]
	v_cmp_neq_f32_e64 s[0:1], -1.0, v0
	v_lshl_add_u64 v[80:81], v[56:57], 0, v[80:81]
	s_nop 0
	v_cndmask_b32_e64 v106, v219, v106, s[0:1]
	v_cmp_lt_f32_e64 s[0:1], |v0|, s21
	s_nop 1
	v_cndmask_b32_e64 v0, v106, v0, s[0:1]
	v_rcp_f32_e32 v106, v2
	ds_read_u16 v2, v41
	s_waitcnt lgkmcnt(0)
	v_lshlrev_b32_e32 v110, 16, v2
	v_add_f32_e32 v2, v19, v71
	v_mul_f32_e32 v2, 0xbfb8aa3b, v2
	v_exp_f32_e32 v2, v2
	s_nop 0
	v_add_f32_e32 v2, 1.0, v2
	v_rcp_f32_e32 v108, v2
	v_add_f32_e32 v2, v3, v107
	v_mul_f32_e32 v2, 0xbfb8aa3b, v2
	v_exp_f32_e32 v2, v2
	s_nop 0
	v_add_f32_e32 v2, 1.0, v2
	v_rcp_f32_e32 v111, v2
	v_pk_mul_f32 v[2:3], v[108:109], s[24:25] op_sel_hi:[1,0]
	s_nop 0
	v_pk_mul_f32 v[2:3], v[2:3], v[0:1] op_sel_hi:[1,0]
	s_nop 0
	v_mul_f32_e32 v18, 0x3fb8aa3b, v3
	v_pk_add_f32 v[108:109], v[2:3], v[2:3]
	v_exp_f32_e32 v18, v18
	v_fmamk_f32 v3, v109, 0x3c088889, v212
	v_fmaak_f32 v3, v109, v3, 0x3e2aaaab
	v_fma_f32 v3, v109, v3, 0.5
	v_fma_f32 v3, v109, v3, 1.0
	v_mul_f32_e64 v3, v3, -v109
	v_fma_f32 v19, -v18, v18, 1.0
	v_cmp_lt_f32_e64 s[12:13], s22, v109
	v_mul_f32_e32 v2, 0x3fb8aa3b, v2
	v_exp_f32_e32 v2, v2
	v_cndmask_b32_e64 v3, v19, v3, s[12:13]
	v_max_f32_e32 v3, 0, v3
	v_sqrt_f32_e32 v3, v3
	v_cmp_lt_f32_e64 s[0:1], s22, v108
	v_mul_f32_e32 v3, v106, v3
	v_mul_f32_e32 v19, v3, v110
	v_fmamk_f32 v3, v108, 0x3c088889, v212
	v_fmaak_f32 v3, v108, v3, 0x3e2aaaab
	v_fma_f32 v3, v108, v3, 0.5
	v_add_u32_e32 v106, v40, v88
	v_fma_f32 v3, v108, v3, 1.0
	ds_write_b64 v106, v[18:19] offset:9216
	v_mul_f32_e64 v3, v3, -v108
	v_fma_f32 v18, -v2, v2, 1.0
	v_cndmask_b32_e64 v3, v18, v3, s[0:1]
	v_max_f32_e32 v3, 0, v3
	ds_read_u16 v18, v41 offset:144
	v_sqrt_f32_e32 v3, v3
	s_waitcnt lgkmcnt(0)
; DI float bf2f(u16 v) { return __uint_as_float(((unsigned)v) << 16); }
; DI int crow(int i, int h) { return (i & 3) + 8 * (i >> 2) + 4 * h; }
; DI void lru_item(const Params& p, int l, int b, int chunk, int blk, bool fin, char* smem, int tid) {
;     ...
;       for (int i = 0; i < 16; i++) {
;         const int tok = tb * 32 + crow(i, h);
;         const float rr = __builtin_amdgcn_rcpf(1.f + __expf(-(ga[i] + b_a))), ii = __builtin_amdgcn_rcpf(1.f + __expf(-(gx[i] + b_x)));
;         const float la = -8.f * rr * sp;
;         const float a = __expf(la);
;         const float x2 = 2.f * la;
;         const float ser = -x2 * (1.f + x2 * (0.5f + x2 * (0.16666667f + x2 * (0.041666668f + x2 * 0.0083333338f))));
;         const float om = (x2 > -0.25f) ? ser : (1.f - a * a);
;         const float u = __builtin_amdgcn_sqrtf(fmaxf(om, 0.f)) * ii * bf2f(xcb[tok][chn]);
;         au[(dir * 64 + tok) * 64 + chn] = make_float2(a, u);
;       }
	v_lshlrev_b32_e32 v18, 16, v18
	v_mul_f32_e32 v3, v111, v3
	v_mul_f32_e32 v3, v3, v18
	ds_write_b64 v39, v[2:3] offset:9216
	v_add_f32_e32 v2, v20, v71
	v_mul_f32_e32 v2, 0xbfb8aa3b, v2
	v_exp_f32_e32 v2, v2
	s_nop 0
	v_add_f32_e32 v2, 1.0, v2
	v_rcp_f32_e32 v3, v2
	v_add_f32_e32 v2, v4, v107
	v_mul_f32_e32 v2, 0xbfb8aa3b, v2
	v_exp_f32_e32 v2, v2
	v_add_f32_e32 v4, v5, v107
	v_mul_f32_e32 v4, 0xbfb8aa3b, v4
	v_exp_f32_e32 v4, v4
	v_add_f32_e32 v2, 1.0, v2
	v_rcp_f32_e32 v20, v2
	ds_read_u16 v2, v41 offset:288
	v_add_f32_e32 v4, 1.0, v4
	s_waitcnt lgkmcnt(0)
	v_lshlrev_b32_e32 v108, 16, v2
	v_add_f32_e32 v2, v21, v71
	v_mul_f32_e32 v2, 0xbfb8aa3b, v2
	v_exp_f32_e32 v2, v2
	v_rcp_f32_e32 v21, v4
	v_add_f32_e32 v2, 1.0, v2
	v_rcp_f32_e32 v2, v2
	s_nop 0
	v_pk_mul_f32 v[2:3], v[2:3], s[24:25] op_sel_hi:[1,0]
	s_nop 0
	v_pk_mul_f32 v[2:3], v[2:3], v[0:1] op_sel_hi:[1,0]
	s_nop 0
	v_mul_f32_e32 v4, 0x3fb8aa3b, v3
	v_pk_add_f32 v[18:19], v[2:3], v[2:3]
	v_exp_f32_e32 v4, v4
	v_fmamk_f32 v3, v19, 0x3c088889, v212
	v_fmaak_f32 v3, v19, v3, 0x3e2aaaab
	v_fma_f32 v3, v19, v3, 0.5
	v_fma_f32 v3, v19, v3, 1.0
	v_mul_f32_e64 v3, v3, -v19
	v_fma_f32 v5, -v4, v4, 1.0
	v_cmp_lt_f32_e64 s[12:13], s22, v19
	v_mul_f32_e32 v2, 0x3fb8aa3b, v2
	v_exp_f32_e32 v2, v2
	v_cndmask_b32_e64 v3, v5, v3, s[12:13]
	v_max_f32_e32 v3, 0, v3
	v_sqrt_f32_e32 v3, v3
	v_cmp_lt_f32_e64 s[0:1], s22, v18
	v_mul_f32_e32 v3, v20, v3
	v_mul_f32_e32 v5, v3, v108
	v_fmamk_f32 v3, v18, 0x3c088889, v212
	v_fmaak_f32 v3, v18, v3, 0x3e2aaaab
	v_fma_f32 v3, v18, v3, 0.5
	v_fma_f32 v3, v18, v3, 1.0
	ds_write_b64 v43, v[4:5] offset:9216
	v_mul_f32_e64 v3, v3, -v18
	v_fma_f32 v4, -v2, v2, 1.0
	v_cndmask_b32_e64 v3, v4, v3, s[0:1]
	v_max_f32_e32 v3, 0, v3
	ds_read_u16 v4, v41 offset:432
	v_sqrt_f32_e32 v3, v3
	s_waitcnt lgkmcnt(0)
	v_lshlrev_b32_e32 v4, 16, v4
	v_mul_f32_e32 v3, v21, v3
	v_mul_f32_e32 v3, v3, v4
	ds_write_b64 v61, v[2:3] offset:9216
	v_add_f32_e32 v2, v22, v71
	v_mul_f32_e32 v2, 0xbfb8aa3b, v2
	v_exp_f32_e32 v2, v2
	v_add_f32_e32 v4, v7, v107
	v_mul_f32_e32 v4, 0xbfb8aa3b, v4
	v_exp_f32_e32 v4, v4
	v_add_f32_e32 v2, 1.0, v2
	v_rcp_f32_e32 v3, v2
	v_add_f32_e32 v2, v6, v107
	v_mul_f32_e32 v2, 0xbfb8aa3b, v2
	v_exp_f32_e32 v2, v2
	v_add_f32_e32 v4, 1.0, v4
	v_rcp_f32_e32 v19, v4
	v_add_f32_e32 v2, 1.0, v2
	v_rcp_f32_e32 v5, v2
	ds_read_u16 v2, v41 offset:1152
	s_waitcnt lgkmcnt(0)
	v_lshlrev_b32_e32 v18, 16, v2
	v_add_f32_e32 v2, v23, v71
	v_mul_f32_e32 v2, 0xbfb8aa3b, v2
	v_exp_f32_e32 v2, v2
	s_nop 0
	v_add_f32_e32 v2, 1.0, v2
	v_rcp_f32_e32 v2, v2
	s_nop 0
	v_pk_mul_f32 v[2:3], v[2:3], s[24:25] op_sel_hi:[1,0]
	s_nop 0
	v_pk_mul_f32 v[2:3], v[2:3], v[0:1] op_sel_hi:[1,0]
	s_nop 0
	v_mul_f32_e32 v4, 0x3fb8aa3b, v3
	v_pk_add_f32 v[6:7], v[2:3], v[2:3]
	v_exp_f32_e32 v4, v4
	v_fmamk_f32 v3, v7, 0x3c088889, v212
	v_fmaak_f32 v3, v7, v3, 0x3e2aaaab
	v_fma_f32 v3, v7, v3, 0.5
	v_fma_f32 v3, v7, v3, 1.0
	v_mul_f32_e64 v3, v3, -v7
	v_fma_f32 v20, -v4, v4, 1.0
	v_cmp_lt_f32_e64 s[12:13], s22, v7
	v_mul_f32_e32 v2, 0x3fb8aa3b, v2
	v_exp_f32_e32 v2, v2
	v_cndmask_b32_e64 v3, v20, v3, s[12:13]
	v_max_f32_e32 v3, 0, v3
	v_sqrt_f32_e32 v3, v3
	v_cmp_lt_f32_e64 s[0:1], s22, v6
	v_mul_f32_e32 v3, v5, v3
	v_mul_f32_e32 v5, v3, v18
	v_fmamk_f32 v3, v6, 0x3c088889, v212
	v_fmaak_f32 v3, v6, v3, 0x3e2aaaab
	v_fma_f32 v3, v6, v3, 0.5
	v_fma_f32 v3, v6, v3, 1.0
	ds_write_b64 v94, v[4:5] offset:9216
	v_mul_f32_e64 v3, v3, -v6
	v_fma_f32 v4, -v2, v2, 1.0
	v_cndmask_b32_e64 v3, v4, v3, s[0:1]
	v_max_f32_e32 v3, 0, v3
	ds_read_u16 v4, v41 offset:1296
	v_sqrt_f32_e32 v3, v3
	s_waitcnt lgkmcnt(0)
	v_lshlrev_b32_e32 v4, 16, v4
	v_mul_f32_e32 v3, v19, v3
	v_mul_f32_e32 v3, v3, v4
	ds_write_b64 v95, v[2:3] offset:9216
	v_add_f32_e32 v2, v24, v71
	v_mul_f32_e32 v2, 0xbfb8aa3b, v2
	v_exp_f32_e32 v2, v2
	v_add_f32_e32 v4, v9, v107
	v_mul_f32_e32 v4, 0xbfb8aa3b, v4
	v_exp_f32_e32 v4, v4
	v_add_f32_e32 v2, 1.0, v2
	v_rcp_f32_e32 v3, v2
	v_add_f32_e32 v2, v8, v107
	v_mul_f32_e32 v2, 0xbfb8aa3b, v2
	v_exp_f32_e32 v2, v2
	v_add_f32_e32 v4, 1.0, v4
	v_rcp_f32_e32 v9, v4
	v_add_f32_e32 v2, 1.0, v2
	v_rcp_f32_e32 v5, v2
	ds_read_u16 v2, v41 offset:1440
	s_waitcnt lgkmcnt(0)
	v_lshlrev_b32_e32 v8, 16, v2
	v_add_f32_e32 v2, v25, v71
	v_mul_f32_e32 v2, 0xbfb8aa3b, v2
	v_exp_f32_e32 v2, v2
	s_nop 0
	v_add_f32_e32 v2, 1.0, v2
	v_rcp_f32_e32 v2, v2
	s_nop 0
	v_pk_mul_f32 v[2:3], v[2:3], s[24:25] op_sel_hi:[1,0]
	s_nop 0
	v_pk_mul_f32 v[2:3], v[2:3], v[0:1] op_sel_hi:[1,0]
	s_nop 0
	v_mul_f32_e32 v4, 0x3fb8aa3b, v3
	v_pk_add_f32 v[6:7], v[2:3], v[2:3]
	v_exp_f32_e32 v4, v4
	v_fmamk_f32 v3, v7, 0x3c088889, v212
	v_fmaak_f32 v3, v7, v3, 0x3e2aaaab
	v_fma_f32 v3, v7, v3, 0.5
	v_fma_f32 v3, v7, v3, 1.0
	v_mul_f32_e64 v3, v3, -v7
	v_fma_f32 v18, -v4, v4, 1.0
	v_cmp_lt_f32_e64 s[12:13], s22, v7
	v_mul_f32_e32 v2, 0x3fb8aa3b, v2
	v_exp_f32_e32 v2, v2
	v_cndmask_b32_e64 v3, v18, v3, s[12:13]
	v_max_f32_e32 v3, 0, v3
	v_sqrt_f32_e32 v3, v3
	v_cmp_lt_f32_e64 s[0:1], s22, v6
	v_mul_f32_e32 v3, v5, v3
	v_mul_f32_e32 v5, v3, v8
	v_fmamk_f32 v3, v6, 0x3c088889, v212
	v_fmaak_f32 v3, v6, v3, 0x3e2aaaab
	v_fma_f32 v3, v6, v3, 0.5
	v_fma_f32 v3, v6, v3, 1.0
	ds_write_b64 v96, v[4:5] offset:9216
	v_mul_f32_e64 v3, v3, -v6
	v_fma_f32 v4, -v2, v2, 1.0
	v_cndmask_b32_e64 v3, v4, v3, s[0:1]
	v_max_f32_e32 v3, 0, v3
	ds_read_u16 v4, v41 offset:1584
	v_sqrt_f32_e32 v3, v3
	s_waitcnt lgkmcnt(0)
; DI float bf2f(u16 v) { return __uint_as_float(((unsigned)v) << 16); }
; DI int crow(int i, int h) { return (i & 3) + 8 * (i >> 2) + 4 * h; }
; DI void lru_item(const Params& p, int l, int b, int chunk, int blk, bool fin, char* smem, int tid) {
;     ...
;       for (int i = 0; i < 16; i++) {
;         const int tok = tb * 32 + crow(i, h);
;         const float rr = __builtin_amdgcn_rcpf(1.f + __expf(-(ga[i] + b_a))), ii = __builtin_amdgcn_rcpf(1.f + __expf(-(gx[i] + b_x)));
;         const float la = -8.f * rr * sp;
;         const float a = __expf(la);
;         const float x2 = 2.f * la;
;         const float ser = -x2 * (1.f + x2 * (0.5f + x2 * (0.16666667f + x2 * (0.041666668f + x2 * 0.0083333338f))));
;         const float om = (x2 > -0.25f) ? ser : (1.f - a * a);
;         const float u = __builtin_amdgcn_sqrtf(fmaxf(om, 0.f)) * ii * bf2f(xcb[tok][chn]);
;         au[(dir * 64 + tok) * 64 + chn] = make_float2(a, u);
;       }
	v_lshlrev_b32_e32 v4, 16, v4
	v_mul_f32_e32 v3, v9, v3
	v_mul_f32_e32 v3, v3, v4
	ds_write_b64 v97, v[2:3] offset:9216
	v_add_f32_e32 v2, v26, v71
	v_mul_f32_e32 v2, 0xbfb8aa3b, v2
	v_exp_f32_e32 v2, v2
	v_add_f32_e32 v4, v11, v107
	v_mul_f32_e32 v4, 0xbfb8aa3b, v4
	v_exp_f32_e32 v4, v4
	v_add_f32_e32 v2, 1.0, v2
	v_rcp_f32_e32 v3, v2
	v_add_f32_e32 v2, v10, v107
	v_mul_f32_e32 v2, 0xbfb8aa3b, v2
	v_exp_f32_e32 v2, v2
	v_add_f32_e32 v4, 1.0, v4
	v_rcp_f32_e32 v9, v4
	v_add_f32_e32 v2, 1.0, v2
	v_rcp_f32_e32 v5, v2
	ds_read_u16 v2, v41 offset:2304
	s_waitcnt lgkmcnt(0)
	v_lshlrev_b32_e32 v8, 16, v2
	v_add_f32_e32 v2, v27, v71
	v_mul_f32_e32 v2, 0xbfb8aa3b, v2
	v_exp_f32_e32 v2, v2
	s_nop 0
	v_add_f32_e32 v2, 1.0, v2
	v_rcp_f32_e32 v2, v2
	s_nop 0
	v_pk_mul_f32 v[2:3], v[2:3], s[24:25] op_sel_hi:[1,0]
	s_nop 0
	v_pk_mul_f32 v[2:3], v[2:3], v[0:1] op_sel_hi:[1,0]
	s_nop 0
	v_mul_f32_e32 v4, 0x3fb8aa3b, v3
	v_pk_add_f32 v[6:7], v[2:3], v[2:3]
	v_exp_f32_e32 v4, v4
	v_fmamk_f32 v3, v7, 0x3c088889, v212
	v_fmaak_f32 v3, v7, v3, 0x3e2aaaab
	v_fma_f32 v3, v7, v3, 0.5
	v_fma_f32 v3, v7, v3, 1.0
	v_mul_f32_e64 v3, v3, -v7
	v_fma_f32 v10, -v4, v4, 1.0
	v_cmp_lt_f32_e64 s[12:13], s22, v7
	v_mul_f32_e32 v2, 0x3fb8aa3b, v2
	v_exp_f32_e32 v2, v2
	v_cndmask_b32_e64 v3, v10, v3, s[12:13]
	v_max_f32_e32 v3, 0, v3
	v_sqrt_f32_e32 v3, v3
	v_cmp_lt_f32_e64 s[0:1], s22, v6
	v_mul_f32_e32 v3, v5, v3
	v_mul_f32_e32 v5, v3, v8
	v_fmamk_f32 v3, v6, 0x3c088889, v212
	v_fmaak_f32 v3, v6, v3, 0x3e2aaaab
	v_fma_f32 v3, v6, v3, 0.5
	v_fma_f32 v3, v6, v3, 1.0
	ds_write_b64 v98, v[4:5] offset:9216
	v_mul_f32_e64 v3, v3, -v6
	v_fma_f32 v4, -v2, v2, 1.0
	v_cndmask_b32_e64 v3, v4, v3, s[0:1]
	v_max_f32_e32 v3, 0, v3
	ds_read_u16 v4, v41 offset:2448
	v_sqrt_f32_e32 v3, v3
	s_waitcnt lgkmcnt(0)
	v_lshlrev_b32_e32 v4, 16, v4
	v_mul_f32_e32 v3, v9, v3
	v_mul_f32_e32 v3, v3, v4
	ds_write_b64 v99, v[2:3] offset:9216
	v_add_f32_e32 v2, v28, v71
	v_mul_f32_e32 v2, 0xbfb8aa3b, v2
	v_exp_f32_e32 v2, v2
	v_add_f32_e32 v4, v13, v107
	v_mul_f32_e32 v4, 0xbfb8aa3b, v4
	v_exp_f32_e32 v4, v4
	v_add_f32_e32 v2, 1.0, v2
	v_rcp_f32_e32 v3, v2
	v_add_f32_e32 v2, v12, v107
	v_mul_f32_e32 v2, 0xbfb8aa3b, v2
	v_exp_f32_e32 v2, v2
	v_add_f32_e32 v4, 1.0, v4
	v_rcp_f32_e32 v9, v4
	v_add_f32_e32 v2, 1.0, v2
	v_rcp_f32_e32 v5, v2
	ds_read_u16 v2, v41 offset:2592
	s_waitcnt lgkmcnt(0)
	v_lshlrev_b32_e32 v8, 16, v2
	v_add_f32_e32 v2, v29, v71
	v_mul_f32_e32 v2, 0xbfb8aa3b, v2
	v_exp_f32_e32 v2, v2
	s_nop 0
	v_add_f32_e32 v2, 1.0, v2
	v_rcp_f32_e32 v2, v2
	s_nop 0
	v_pk_mul_f32 v[2:3], v[2:3], s[24:25] op_sel_hi:[1,0]
	s_nop 0
	v_pk_mul_f32 v[2:3], v[2:3], v[0:1] op_sel_hi:[1,0]
	s_nop 0
	v_mul_f32_e32 v4, 0x3fb8aa3b, v3
	v_pk_add_f32 v[6:7], v[2:3], v[2:3]
	v_exp_f32_e32 v4, v4
	v_fmamk_f32 v3, v7, 0x3c088889, v212
	v_fmaak_f32 v3, v7, v3, 0x3e2aaaab
	v_fma_f32 v3, v7, v3, 0.5
	v_fma_f32 v3, v7, v3, 1.0
	v_mul_f32_e64 v3, v3, -v7
	v_fma_f32 v10, -v4, v4, 1.0
	v_cmp_lt_f32_e64 s[12:13], s22, v7
	v_mul_f32_e32 v2, 0x3fb8aa3b, v2
	v_exp_f32_e32 v2, v2
	v_cndmask_b32_e64 v3, v10, v3, s[12:13]
	v_max_f32_e32 v3, 0, v3
	v_sqrt_f32_e32 v3, v3
	v_cmp_lt_f32_e64 s[0:1], s22, v6
	v_mul_f32_e32 v3, v5, v3
	v_mul_f32_e32 v5, v3, v8
	v_fmamk_f32 v3, v6, 0x3c088889, v212
	v_fmaak_f32 v3, v6, v3, 0x3e2aaaab
	v_fma_f32 v3, v6, v3, 0.5
	v_fma_f32 v3, v6, v3, 1.0
	ds_write_b64 v100, v[4:5] offset:9216
	v_mul_f32_e64 v3, v3, -v6
	v_fma_f32 v4, -v2, v2, 1.0
	v_cndmask_b32_e64 v3, v4, v3, s[0:1]
	v_max_f32_e32 v3, 0, v3
	ds_read_u16 v4, v41 offset:2736
	v_sqrt_f32_e32 v3, v3
	s_waitcnt lgkmcnt(0)
	v_lshlrev_b32_e32 v4, 16, v4
	v_mul_f32_e32 v3, v9, v3
	v_mul_f32_e32 v3, v3, v4
	ds_write_b64 v101, v[2:3] offset:9216
	v_add_f32_e32 v2, v30, v71
	v_mul_f32_e32 v2, 0xbfb8aa3b, v2
	v_exp_f32_e32 v2, v2
	v_add_f32_e32 v4, v15, v107
	v_mul_f32_e32 v4, 0xbfb8aa3b, v4
	v_exp_f32_e32 v4, v4
	v_add_f32_e32 v2, 1.0, v2
	v_rcp_f32_e32 v3, v2
	v_add_f32_e32 v2, v14, v107
	v_mul_f32_e32 v2, 0xbfb8aa3b, v2
	v_exp_f32_e32 v2, v2
	v_add_f32_e32 v4, 1.0, v4
	v_rcp_f32_e32 v9, v4
	v_add_f32_e32 v2, 1.0, v2
	v_rcp_f32_e32 v5, v2
	ds_read_u16 v2, v41 offset:3456
	s_waitcnt lgkmcnt(0)
	v_lshlrev_b32_e32 v8, 16, v2
	v_add_f32_e32 v2, v31, v71
	v_mul_f32_e32 v2, 0xbfb8aa3b, v2
	v_exp_f32_e32 v2, v2
	s_nop 0
	v_add_f32_e32 v2, 1.0, v2
	v_rcp_f32_e32 v2, v2
	s_nop 0
	v_pk_mul_f32 v[2:3], v[2:3], s[24:25] op_sel_hi:[1,0]
	s_nop 0
	v_pk_mul_f32 v[2:3], v[2:3], v[0:1] op_sel_hi:[1,0]
	s_nop 0
	v_mul_f32_e32 v4, 0x3fb8aa3b, v3
	v_pk_add_f32 v[6:7], v[2:3], v[2:3]
	v_exp_f32_e32 v4, v4
	v_fmamk_f32 v3, v7, 0x3c088889, v212
	v_fmaak_f32 v3, v7, v3, 0x3e2aaaab
	v_fma_f32 v3, v7, v3, 0.5
	v_fma_f32 v3, v7, v3, 1.0
	v_mul_f32_e64 v3, v3, -v7
	v_fma_f32 v10, -v4, v4, 1.0
	v_cmp_lt_f32_e64 s[12:13], s22, v7
	v_mul_f32_e32 v2, 0x3fb8aa3b, v2
	v_exp_f32_e32 v2, v2
	v_cndmask_b32_e64 v3, v10, v3, s[12:13]
	v_max_f32_e32 v3, 0, v3
	v_sqrt_f32_e32 v3, v3
	v_cmp_lt_f32_e64 s[0:1], s22, v6
	v_mul_f32_e32 v3, v5, v3
	v_mul_f32_e32 v5, v3, v8
	v_fmamk_f32 v3, v6, 0x3c088889, v212
	v_fmaak_f32 v3, v6, v3, 0x3e2aaaab
	v_fma_f32 v3, v6, v3, 0.5
	v_fma_f32 v3, v6, v3, 1.0
	ds_write_b64 v102, v[4:5] offset:9216
	v_mul_f32_e64 v3, v3, -v6
	v_fma_f32 v4, -v2, v2, 1.0
	v_cndmask_b32_e64 v3, v4, v3, s[0:1]
	v_max_f32_e32 v3, 0, v3
	ds_read_u16 v4, v41 offset:3600
	v_sqrt_f32_e32 v3, v3
	s_waitcnt lgkmcnt(0)
; #define MFMA(a, b, c) __builtin_amdgcn_mfma_f32_32x32x16_bf16((a), (b), (c), 0, 0, 0)
; DI int crow(int i, int h) { return (i & 3) + 8 * (i >> 2) + 4 * h; }
; DI void lru_item(const Params& p, int l, int b, int chunk, int blk, bool fin, char* smem, int tid) {
;     ...
;       const u16* wa = p.WtA + (((size_t)l * 2 + dir) * 4 + blk) * 4096 + (size_t)chn * 64 + h * 8;
;       const u16* wx = p.WtX + (((size_t)l * 2 + dir) * 4 + blk) * 4096 + (size_t)chn * 64 + h * 8;
; #pragma unroll
;       for (int ks = 0; ks < 4; ks++) {
;         bf16x8 a = *(const bf16x8*)&xcb[tb * 32 + r][ks * 16 + h * 8];
;         bf16x8 ba = *(const bf16x8*)(wa + ks * 16), bx = *(const bf16x8*)(wx + ks * 16);
;         ga = MFMA(a, ba, ga); gx = MFMA(a, bx, gx);
;       }
;       const int pi = (l * 2 + dir) * 256 + c0 + chn;
;       const float b_a = p.ba[pi], b_x = p.bx[pi], lam = p.lam[pi];
;       const float sp = log1pf(__expf(-lam));
; #pragma unroll
;       for (int i = 0; i < 16; i++) {
;         const int tok = tb * 32 + crow(i, h);
;         const float rr = __builtin_amdgcn_rcpf(1.f + __expf(-(ga[i] + b_a))), ii = __builtin_amdgcn_rcpf(1.f + __expf(-(gx[i] + b_x)));
	v_lshlrev_b32_e32 v4, 16, v4
	v_mul_f32_e32 v3, v9, v3
	v_mul_f32_e32 v3, v3, v4
	ds_write_b64 v103, v[2:3] offset:9216
	v_add_f32_e32 v2, v32, v71
	v_mul_f32_e32 v2, 0xbfb8aa3b, v2
	v_exp_f32_e32 v2, v2
	v_add_f32_e32 v4, v17, v107
	v_mul_f32_e32 v4, 0xbfb8aa3b, v4
	v_exp_f32_e32 v4, v4
	v_add_f32_e32 v2, 1.0, v2
	v_rcp_f32_e32 v3, v2
	v_add_f32_e32 v2, v16, v107
	v_mul_f32_e32 v2, 0xbfb8aa3b, v2
	v_exp_f32_e32 v2, v2
	v_add_f32_e32 v4, 1.0, v4
	v_rcp_f32_e32 v9, v4
	v_add_f32_e32 v2, 1.0, v2
	v_rcp_f32_e32 v5, v2
	ds_read_u16 v2, v41 offset:3744
	s_waitcnt lgkmcnt(0)
	v_lshlrev_b32_e32 v8, 16, v2
	v_add_f32_e32 v2, v33, v71
	v_mul_f32_e32 v2, 0xbfb8aa3b, v2
	v_exp_f32_e32 v2, v2
	s_nop 0
	v_add_f32_e32 v2, 1.0, v2
	v_rcp_f32_e32 v2, v2
	s_nop 0
	v_pk_mul_f32 v[2:3], v[2:3], s[24:25] op_sel_hi:[1,0]
	s_nop 0
	v_pk_mul_f32 v[2:3], v[2:3], v[0:1] op_sel_hi:[1,0]
	s_nop 0
	v_mul_f32_e32 v0, 0x3fb8aa3b, v3
	v_pk_add_f32 v[6:7], v[2:3], v[2:3]
	v_exp_f32_e32 v4, v0
	v_fmamk_f32 v0, v7, 0x3c088889, v212
	v_fmaak_f32 v0, v7, v0, 0x3e2aaaab
	v_fma_f32 v0, v7, v0, 0.5
	v_fma_f32 v0, v7, v0, 1.0
	v_mul_f32_e64 v0, v0, -v7
	v_fma_f32 v3, -v4, v4, 1.0
	v_cmp_lt_f32_e64 s[12:13], s22, v7
	v_cmp_lt_f32_e64 s[0:1], s22, v6
	s_nop 0
	v_cndmask_b32_e64 v0, v3, v0, s[12:13]
	v_max_f32_e32 v0, 0, v0
	v_sqrt_f32_e32 v0, v0
	s_nop 0
	v_mul_f32_e32 v0, v5, v0
	v_mul_f32_e32 v5, v0, v8
	v_mul_f32_e32 v0, 0x3fb8aa3b, v2
	v_exp_f32_e32 v2, v0
	v_fmamk_f32 v0, v6, 0x3c088889, v212
	v_fmaak_f32 v0, v6, v0, 0x3e2aaaab
	v_fma_f32 v0, v6, v0, 0.5
	v_fma_f32 v0, v6, v0, 1.0
	v_mul_f32_e64 v0, v0, -v6
	v_fma_f32 v3, -v2, v2, 1.0
	ds_write_b64 v104, v[4:5] offset:9216
	v_cndmask_b32_e64 v0, v3, v0, s[0:1]
	v_max_f32_e32 v0, 0, v0
	ds_read_u16 v3, v41 offset:3888
	v_sqrt_f32_e32 v0, v0
	s_waitcnt lgkmcnt(0)
	v_lshlrev_b32_e32 v3, 16, v3
	v_mul_f32_e32 v0, v9, v0
	v_mul_f32_e32 v3, v0, v3
	ds_write_b64 v105, v[2:3] offset:9216
	global_load_dwordx4 v[2:5], v[120:121], off
	global_load_dwordx4 v[6:9], v[80:81], off
	ds_read_b128 v[10:13], v87
	ds_read_b128 v[108:111], v87 offset:32
	global_load_dwordx4 v[112:115], v[120:121], off offset:32
	global_load_dwordx4 v[116:119], v[80:81], off offset:32
	s_waitcnt vmcnt(3) lgkmcnt(1)
	v_mfma_f32_32x32x16_bf16 v[18:33], v[10:13], v[2:5], 0
	s_waitcnt vmcnt(2)
	v_mfma_f32_32x32x16_bf16 v[2:17], v[10:13], v[6:9], 0
	s_waitcnt vmcnt(1) lgkmcnt(0)
	v_mfma_f32_32x32x16_bf16 v[18:33], v[108:111], v[112:115], v[18:33]
	s_waitcnt vmcnt(0)
	v_mfma_f32_32x32x16_bf16 v[2:17], v[108:111], v[116:119], v[2:17]
	ds_read_b128 v[108:111], v87 offset:64
	global_load_dwordx4 v[112:115], v[120:121], off offset:64
	global_load_dwordx4 v[116:119], v[80:81], off offset:64
	s_waitcnt vmcnt(1) lgkmcnt(0)
	v_mfma_f32_32x32x16_bf16 v[18:33], v[108:111], v[112:115], v[18:33]
	s_waitcnt vmcnt(0)
	v_mfma_f32_32x32x16_bf16 v[2:17], v[108:111], v[116:119], v[2:17]
	ds_read_b128 v[108:111], v87 offset:96
	global_load_dwordx4 v[112:115], v[120:121], off offset:96
	global_load_dwordx4 v[116:119], v[80:81], off offset:96
	s_nop 0
	global_load_dword v80, v[82:83], off offset:1024
	global_load_dword v71, v[84:85], off offset:1024
	global_load_dword v0, v[78:79], off offset:1024
	s_waitcnt vmcnt(0)
	v_mul_f32_e32 v0, 0xbfb8aa3b, v0
	v_exp_f32_e32 v0, v0
	s_waitcnt lgkmcnt(0)
	v_mfma_f32_32x32x16_bf16 v[18:33], v[108:111], v[112:115], v[18:33]
	v_add_f32_e32 v81, 1.0, v0
	v_add_f32_e32 v78, -1.0, v81
	v_sub_f32_e32 v79, v78, v81
	v_add_f32_e32 v79, 1.0, v79
	v_sub_f32_e32 v78, v0, v78
	v_add_f32_e32 v82, v78, v79
	v_frexp_mant_f32_e32 v78, v81
	v_cmp_gt_f32_e64 s[0:1], s2, v78
	v_cvt_f64_f32_e32 v[78:79], v81
	v_frexp_exp_i32_f64_e32 v78, v[78:79]
	v_subbrev_co_u32_e64 v107, s[0:1], 0, v78, s[0:1]
	v_sub_u32_e32 v78, 0, v107
	v_ldexp_f32 v79, v81, v78
	v_add_f32_e32 v81, -1.0, v79
	v_add_f32_e32 v83, 1.0, v79
	v_ldexp_f32 v78, v82, v78
	v_add_f32_e32 v82, 1.0, v81
	v_add_f32_e32 v84, -1.0, v83
	v_sub_f32_e32 v82, v79, v82
	v_sub_f32_e32 v79, v79, v84
	v_add_f32_e32 v82, v78, v82
	v_add_f32_e32 v78, v78, v79
	v_mfma_f32_32x32x16_bf16 v[2:17], v[108:111], v[116:119], v[2:17]
	v_add_f32_e32 v110, v83, v78
	v_rcp_f32_e32 v112, v110
	v_sub_f32_e32 v79, v110, v83
	v_sub_f32_e32 v111, v78, v79
	v_add_f32_e32 v79, v81, v82
	v_sub_f32_e32 v78, v79, v81
	v_mul_f32_e32 v113, v79, v112
	v_sub_f32_e32 v81, v82, v78
	v_mul_f32_e32 v82, v110, v113
	v_fma_f32 v84, v113, v110, -v82
	v_fmac_f32_e32 v84, v113, v111
	v_add_f32_e32 v78, v82, v84
	v_sub_f32_e32 v83, v79, v78
	v_pk_add_f32 v[108:109], v[78:79], v[82:83] neg_lo:[0,1] neg_hi:[0,1]
	v_mov_b32_e32 v85, v78
	v_pk_add_f32 v[78:79], v[108:109], v[84:85] neg_lo:[0,1] neg_hi:[0,1]
	v_add_f32_e32 v2, v2, v71
	v_add_f32_e32 v79, v81, v79
	v_add_f32_e32 v78, v78, v79
	v_add_f32_e32 v79, v83, v78
	v_mul_f32_e32 v81, v112, v79
	v_mul_f32_e32 v82, v110, v81
	v_fma_f32 v84, v81, v110, -v82
	v_fmac_f32_e32 v84, v81, v111
	v_sub_f32_e32 v83, v83, v79
	v_add_f32_e32 v110, v78, v83
	v_add_f32_e32 v78, v82, v84
	v_sub_f32_e32 v83, v79, v78
	v_pk_add_f32 v[108:109], v[78:79], v[82:83] neg_lo:[0,1] neg_hi:[0,1]
	v_mov_b32_e32 v85, v78
	v_pk_add_f32 v[78:79], v[108:109], v[84:85] neg_lo:[0,1] neg_hi:[0,1]
	v_mul_f32_e32 v2, 0xbfb8aa3b, v2
	v_add_f32_e32 v79, v110, v79
	v_add_f32_e32 v78, v78, v79
	v_add_f32_e32 v79, v113, v81
	v_add_f32_e32 v78, v83, v78
	v_sub_f32_e32 v82, v79, v113
	v_mul_f32_e32 v78, v112, v78
	v_sub_f32_e32 v81, v81, v82
	v_add_f32_e32 v81, v81, v78
	v_add_f32_e32 v82, v79, v81
	v_mul_f32_e32 v84, v82, v82
	v_fmamk_f32 v78, v84, 0x3e9b6dac, v211
	v_fmaak_f32 v153, v84, v78, 0x3f2aaada
	v_cvt_f32_i32_e32 v78, v107
; DI float bf2f(u16 v) { return __uint_as_float(((unsigned)v) << 16); }
; DI int crow(int i, int h) { return (i & 3) + 8 * (i >> 2) + 4 * h; }
; DI void lru_item(const Params& p, int l, int b, int chunk, int blk, bool fin, char* smem, int tid) {
;     ...
;       const float sp = log1pf(__expf(-lam));
; #pragma unroll
;       for (int i = 0; i < 16; i++) {
;         const int tok = tb * 32 + crow(i, h);
;         const float rr = __builtin_amdgcn_rcpf(1.f + __expf(-(ga[i] + b_a))), ii = __builtin_amdgcn_rcpf(1.f + __expf(-(gx[i] + b_x)));
;         const float la = -8.f * rr * sp;
;         const float a = __expf(la);
;         const float x2 = 2.f * la;
;         const float ser = -x2 * (1.f + x2 * (0.5f + x2 * (0.16666667f + x2 * (0.041666668f + x2 * 0.0083333338f))));
;         const float om = (x2 > -0.25f) ? ser : (1.f - a * a);
;         const float u = __builtin_amdgcn_sqrtf(fmaxf(om, 0.f)) * ii * bf2f(xcb[tok][chn]);
;         au[(dir * 64 + tok) * 64 + chn] = make_float2(a, u);
;       }
	v_sub_f32_e32 v79, v82, v79
	v_sub_f32_e32 v79, v81, v79
	v_ldexp_f32 v81, v79, 1
	v_mul_f32_e32 v79, v82, v84
	v_pk_mul_f32 v[84:85], v[78:79], v[152:153]
	v_ldexp_f32 v83, v82, 1
	v_fma_f32 v82, v78, s3, -v84
	v_fmac_f32_e32 v82, 0xb102e308, v78
	v_pk_add_f32 v[78:79], v[84:85], v[82:83]
	v_mov_b32_e32 v108, v84
	v_sub_f32_e32 v83, v79, v83
	v_sub_f32_e32 v83, v85, v83
	v_add_f32_e32 v109, v81, v83
	v_pk_add_f32 v[84:85], v[78:79], v[84:85] neg_lo:[0,1] neg_hi:[0,1]
	v_pk_add_f32 v[110:111], v[78:79], v[108:109]
	v_mov_b32_e32 v83, v78
	v_mov_b32_e32 v85, v111
	v_pk_add_f32 v[112:113], v[82:83], v[84:85] neg_lo:[0,1] neg_hi:[0,1]
	v_pk_add_f32 v[82:83], v[82:83], v[84:85]
	v_mov_b32_e32 v108, v109
	v_pk_add_f32 v[84:85], v[82:83], v[78:79] op_sel:[1,0] op_sel_hi:[0,1] neg_lo:[0,1] neg_hi:[0,1]
	v_pk_add_f32 v[114:115], v[110:111], v[84:85] op_sel_hi:[1,0] neg_lo:[0,1] neg_hi:[0,1]
	v_mov_b32_e32 v110, v111
	v_mov_b32_e32 v111, v83
	v_pk_mov_b32 v[84:85], v[78:79], v[84:85] op_sel:[1,0]
	v_mov_b32_e32 v109, v78
	v_pk_add_f32 v[84:85], v[110:111], v[84:85] neg_lo:[0,1] neg_hi:[0,1]
	v_mov_b32_e32 v114, v112
	v_pk_add_f32 v[78:79], v[108:109], v[84:85] neg_lo:[0,1] neg_hi:[0,1]
	v_mov_b32_e32 v113, v83
	v_pk_add_f32 v[84:85], v[114:115], v[78:79]
	v_exp_f32_e32 v2, v2
	v_pk_add_f32 v[108:109], v[84:85], v[84:85] op_sel:[0,1] op_sel_hi:[1,0]
	v_cmp_neq_f32_e64 s[0:1], s20, v0
	v_pk_add_f32 v[82:83], v[82:83], v[108:109] op_sel:[1,0] op_sel_hi:[0,1]
	v_mov_b32_e32 v85, v82
	v_pk_add_f32 v[110:111], v[84:85], v[112:113] neg_lo:[0,1] neg_hi:[0,1]
	v_mov_b32_e32 v79, v108
	v_sub_f32_e32 v81, v84, v110
	v_pk_add_f32 v[78:79], v[78:79], v[110:111] neg_lo:[0,1] neg_hi:[0,1]
	v_sub_f32_e32 v81, v112, v81
	v_add_f32_e32 v2, 1.0, v2
	v_add_f32_e32 v78, v78, v81
	v_rcp_f32_e32 v81, v2
	ds_read_u16 v2, v41
	v_add_f32_e32 v78, v78, v79
	v_add_f32_e32 v78, v82, v78
	v_add_f32_e32 v18, v18, v80
	v_cndmask_b32_e64 v78, v217, v78, s[0:1]
	s_waitcnt lgkmcnt(0)
	v_lshlrev_b32_e32 v82, 16, v2
	v_add_f32_e32 v2, v19, v80
	v_mul_f32_e32 v2, 0xbfb8aa3b, v2
	v_exp_f32_e32 v2, v2
	v_cmp_ngt_f32_e64 s[0:1], -1.0, v0
	v_mul_f32_e32 v18, 0xbfb8aa3b, v18
	v_exp_f32_e32 v18, v18
	v_cndmask_b32_e64 v78, v218, v78, s[0:1]
	v_cmp_neq_f32_e64 s[0:1], -1.0, v0
	v_add_f32_e32 v2, 1.0, v2
	v_add_f32_e32 v18, 1.0, v18
	v_cndmask_b32_e64 v78, v219, v78, s[0:1]
	v_cmp_lt_f32_e64 s[0:1], |v0|, s21
	v_rcp_f32_e32 v79, v18
	s_nop 0
	v_cndmask_b32_e64 v0, v78, v0, s[0:1]
	v_rcp_f32_e32 v78, v2
	v_add_f32_e32 v2, v3, v71
	v_mul_f32_e32 v2, 0xbfb8aa3b, v2
	v_exp_f32_e32 v2, v2
	s_nop 0
	v_add_f32_e32 v2, 1.0, v2
	v_rcp_f32_e32 v83, v2
	v_pk_mul_f32 v[2:3], v[78:79], s[24:25] op_sel_hi:[1,0]
	s_nop 0
	v_pk_mul_f32 v[2:3], v[2:3], v[0:1] op_sel_hi:[1,0]
	s_nop 0
	v_mul_f32_e32 v18, 0x3fb8aa3b, v3
	v_pk_add_f32 v[78:79], v[2:3], v[2:3]
	v_exp_f32_e32 v18, v18
	v_fmamk_f32 v3, v79, 0x3c088889, v212
	v_fmaak_f32 v3, v79, v3, 0x3e2aaaab
	v_fma_f32 v3, v79, v3, 0.5
	v_fma_f32 v3, v79, v3, 1.0
	v_mul_f32_e64 v3, v3, -v79
	v_fma_f32 v19, -v18, v18, 1.0
	v_cmp_lt_f32_e64 s[12:13], s22, v79
	v_mul_f32_e32 v2, 0x3fb8aa3b, v2
	v_exp_f32_e32 v2, v2
	v_cndmask_b32_e64 v3, v19, v3, s[12:13]
	v_max_f32_e32 v3, 0, v3
	v_sqrt_f32_e32 v3, v3
	v_cmp_lt_f32_e64 s[0:1], s22, v78
	v_mul_f32_e32 v3, v81, v3
	v_mul_f32_e32 v19, v3, v82
	v_fmamk_f32 v3, v78, 0x3c088889, v212
	v_fmaak_f32 v3, v78, v3, 0x3e2aaaab
	v_fma_f32 v3, v78, v3, 0.5
	v_fma_f32 v3, v78, v3, 1.0
	ds_write_b64 v106, v[18:19] offset:41984
	v_mul_f32_e64 v3, v3, -v78
	v_fma_f32 v18, -v2, v2, 1.0
	v_cndmask_b32_e64 v3, v18, v3, s[0:1]
	v_max_f32_e32 v3, 0, v3
	ds_read_u16 v18, v41 offset:144
	v_sqrt_f32_e32 v3, v3
	s_waitcnt lgkmcnt(0)
	v_lshlrev_b32_e32 v18, 16, v18
	v_mul_f32_e32 v3, v83, v3
	v_mul_f32_e32 v3, v3, v18
	ds_write_b64 v39, v[2:3] offset:41984
	v_add_f32_e32 v2, v20, v80
	v_mul_f32_e32 v2, 0xbfb8aa3b, v2
	v_exp_f32_e32 v2, v2
	s_nop 0
	v_add_f32_e32 v2, 1.0, v2
	v_rcp_f32_e32 v3, v2
	v_add_f32_e32 v2, v4, v71
	v_mul_f32_e32 v2, 0xbfb8aa3b, v2
	v_exp_f32_e32 v2, v2
	v_add_f32_e32 v4, v5, v71
	v_mul_f32_e32 v4, 0xbfb8aa3b, v4
	v_exp_f32_e32 v4, v4
	v_add_f32_e32 v2, 1.0, v2
	v_rcp_f32_e32 v20, v2
	ds_read_u16 v2, v41 offset:288
	v_add_f32_e32 v4, 1.0, v4
	s_waitcnt lgkmcnt(0)
	v_lshlrev_b32_e32 v78, 16, v2
	v_add_f32_e32 v2, v21, v80
	v_mul_f32_e32 v2, 0xbfb8aa3b, v2
	v_exp_f32_e32 v2, v2
	v_rcp_f32_e32 v21, v4
	v_add_f32_e32 v2, 1.0, v2
	v_rcp_f32_e32 v2, v2
	s_nop 0
	v_pk_mul_f32 v[2:3], v[2:3], s[24:25] op_sel_hi:[1,0]
	s_nop 0
	v_pk_mul_f32 v[2:3], v[2:3], v[0:1] op_sel_hi:[1,0]
	s_nop 0
	v_mul_f32_e32 v4, 0x3fb8aa3b, v3
	v_pk_add_f32 v[18:19], v[2:3], v[2:3]
	v_exp_f32_e32 v4, v4
	v_fmamk_f32 v3, v19, 0x3c088889, v212
	v_fmaak_f32 v3, v19, v3, 0x3e2aaaab
	v_fma_f32 v3, v19, v3, 0.5
	v_fma_f32 v3, v19, v3, 1.0
	v_mul_f32_e64 v3, v3, -v19
	v_fma_f32 v5, -v4, v4, 1.0
	v_cmp_lt_f32_e64 s[12:13], s22, v19
	v_mul_f32_e32 v2, 0x3fb8aa3b, v2
	v_exp_f32_e32 v2, v2
	v_cndmask_b32_e64 v3, v5, v3, s[12:13]
	v_max_f32_e32 v3, 0, v3
	v_sqrt_f32_e32 v3, v3
	v_cmp_lt_f32_e64 s[0:1], s22, v18
	v_mul_f32_e32 v3, v20, v3
	v_mul_f32_e32 v5, v3, v78
	v_fmamk_f32 v3, v18, 0x3c088889, v212
	v_fmaak_f32 v3, v18, v3, 0x3e2aaaab
	v_fma_f32 v3, v18, v3, 0.5
	v_fma_f32 v3, v18, v3, 1.0
	ds_write_b64 v43, v[4:5] offset:41984
	v_mul_f32_e64 v3, v3, -v18
	v_fma_f32 v4, -v2, v2, 1.0
	v_cndmask_b32_e64 v3, v4, v3, s[0:1]
	v_max_f32_e32 v3, 0, v3
	ds_read_u16 v4, v41 offset:432
	v_sqrt_f32_e32 v3, v3
	s_waitcnt lgkmcnt(0)
; DI float bf2f(u16 v) { return __uint_as_float(((unsigned)v) << 16); }
; DI int crow(int i, int h) { return (i & 3) + 8 * (i >> 2) + 4 * h; }
; DI void lru_item(const Params& p, int l, int b, int chunk, int blk, bool fin, char* smem, int tid) {
;     ...
;       for (int i = 0; i < 16; i++) {
;         const int tok = tb * 32 + crow(i, h);
;         const float rr = __builtin_amdgcn_rcpf(1.f + __expf(-(ga[i] + b_a))), ii = __builtin_amdgcn_rcpf(1.f + __expf(-(gx[i] + b_x)));
;         const float la = -8.f * rr * sp;
;         const float a = __expf(la);
;         const float x2 = 2.f * la;
;         const float ser = -x2 * (1.f + x2 * (0.5f + x2 * (0.16666667f + x2 * (0.041666668f + x2 * 0.0083333338f))));
;         const float om = (x2 > -0.25f) ? ser : (1.f - a * a);
;         const float u = __builtin_amdgcn_sqrtf(fmaxf(om, 0.f)) * ii * bf2f(xcb[tok][chn]);
;         au[(dir * 64 + tok) * 64 + chn] = make_float2(a, u);
;       }
	v_lshlrev_b32_e32 v4, 16, v4
	v_mul_f32_e32 v3, v21, v3
	v_mul_f32_e32 v3, v3, v4
	ds_write_b64 v61, v[2:3] offset:41984
	v_add_f32_e32 v2, v22, v80
	v_mul_f32_e32 v2, 0xbfb8aa3b, v2
	v_exp_f32_e32 v2, v2
	v_add_f32_e32 v4, v7, v71
	v_mul_f32_e32 v4, 0xbfb8aa3b, v4
	v_exp_f32_e32 v4, v4
	v_add_f32_e32 v2, 1.0, v2
	v_rcp_f32_e32 v3, v2
	v_add_f32_e32 v2, v6, v71
	v_mul_f32_e32 v2, 0xbfb8aa3b, v2
	v_exp_f32_e32 v2, v2
	v_add_f32_e32 v4, 1.0, v4
	v_rcp_f32_e32 v19, v4
	v_add_f32_e32 v2, 1.0, v2
	v_rcp_f32_e32 v5, v2
	ds_read_u16 v2, v41 offset:1152
	s_waitcnt lgkmcnt(0)
	v_lshlrev_b32_e32 v18, 16, v2
	v_add_f32_e32 v2, v23, v80
	v_mul_f32_e32 v2, 0xbfb8aa3b, v2
	v_exp_f32_e32 v2, v2
	s_nop 0
	v_add_f32_e32 v2, 1.0, v2
	v_rcp_f32_e32 v2, v2
	s_nop 0
	v_pk_mul_f32 v[2:3], v[2:3], s[24:25] op_sel_hi:[1,0]
	s_nop 0
	v_pk_mul_f32 v[2:3], v[2:3], v[0:1] op_sel_hi:[1,0]
	s_nop 0
	v_mul_f32_e32 v4, 0x3fb8aa3b, v3
	v_pk_add_f32 v[6:7], v[2:3], v[2:3]
	v_exp_f32_e32 v4, v4
	v_fmamk_f32 v3, v7, 0x3c088889, v212
	v_fmaak_f32 v3, v7, v3, 0x3e2aaaab
	v_fma_f32 v3, v7, v3, 0.5
	v_fma_f32 v3, v7, v3, 1.0
	v_mul_f32_e64 v3, v3, -v7
	v_fma_f32 v20, -v4, v4, 1.0
	v_cmp_lt_f32_e64 s[12:13], s22, v7
	v_mul_f32_e32 v2, 0x3fb8aa3b, v2
	v_exp_f32_e32 v2, v2
	v_cndmask_b32_e64 v3, v20, v3, s[12:13]
	v_max_f32_e32 v3, 0, v3
	v_sqrt_f32_e32 v3, v3
	v_cmp_lt_f32_e64 s[0:1], s22, v6
	v_mul_f32_e32 v3, v5, v3
	v_mul_f32_e32 v5, v3, v18
	v_fmamk_f32 v3, v6, 0x3c088889, v212
	v_fmaak_f32 v3, v6, v3, 0x3e2aaaab
	v_fma_f32 v3, v6, v3, 0.5
	v_fma_f32 v3, v6, v3, 1.0
	ds_write_b64 v94, v[4:5] offset:41984
	v_mul_f32_e64 v3, v3, -v6
	v_fma_f32 v4, -v2, v2, 1.0
	v_cndmask_b32_e64 v3, v4, v3, s[0:1]
	v_max_f32_e32 v3, 0, v3
	ds_read_u16 v4, v41 offset:1296
	v_sqrt_f32_e32 v3, v3
	s_waitcnt lgkmcnt(0)
	v_lshlrev_b32_e32 v4, 16, v4
	v_mul_f32_e32 v3, v19, v3
	v_mul_f32_e32 v3, v3, v4
	ds_write_b64 v95, v[2:3] offset:41984
	v_add_f32_e32 v2, v24, v80
	v_mul_f32_e32 v2, 0xbfb8aa3b, v2
	v_exp_f32_e32 v2, v2
	v_add_f32_e32 v4, v9, v71
	v_mul_f32_e32 v4, 0xbfb8aa3b, v4
	v_exp_f32_e32 v4, v4
	v_add_f32_e32 v2, 1.0, v2
	v_rcp_f32_e32 v3, v2
	v_add_f32_e32 v2, v8, v71
	v_mul_f32_e32 v2, 0xbfb8aa3b, v2
	v_exp_f32_e32 v2, v2
	v_add_f32_e32 v4, 1.0, v4
	v_rcp_f32_e32 v9, v4
	v_add_f32_e32 v2, 1.0, v2
	v_rcp_f32_e32 v5, v2
	ds_read_u16 v2, v41 offset:1440
	s_waitcnt lgkmcnt(0)
	v_lshlrev_b32_e32 v8, 16, v2
	v_add_f32_e32 v2, v25, v80
	v_mul_f32_e32 v2, 0xbfb8aa3b, v2
	v_exp_f32_e32 v2, v2
	s_nop 0
	v_add_f32_e32 v2, 1.0, v2
	v_rcp_f32_e32 v2, v2
	s_nop 0
	v_pk_mul_f32 v[2:3], v[2:3], s[24:25] op_sel_hi:[1,0]
	s_nop 0
	v_pk_mul_f32 v[2:3], v[2:3], v[0:1] op_sel_hi:[1,0]
	s_nop 0
	v_mul_f32_e32 v4, 0x3fb8aa3b, v3
	v_pk_add_f32 v[6:7], v[2:3], v[2:3]
	v_exp_f32_e32 v4, v4
	v_fmamk_f32 v3, v7, 0x3c088889, v212
	v_fmaak_f32 v3, v7, v3, 0x3e2aaaab
	v_fma_f32 v3, v7, v3, 0.5
	v_fma_f32 v3, v7, v3, 1.0
	v_mul_f32_e64 v3, v3, -v7
	v_fma_f32 v18, -v4, v4, 1.0
	v_cmp_lt_f32_e64 s[12:13], s22, v7
	v_mul_f32_e32 v2, 0x3fb8aa3b, v2
	v_exp_f32_e32 v2, v2
	v_cndmask_b32_e64 v3, v18, v3, s[12:13]
	v_max_f32_e32 v3, 0, v3
	v_sqrt_f32_e32 v3, v3
	v_cmp_lt_f32_e64 s[0:1], s22, v6
	v_mul_f32_e32 v3, v5, v3
	v_mul_f32_e32 v5, v3, v8
	v_fmamk_f32 v3, v6, 0x3c088889, v212
	v_fmaak_f32 v3, v6, v3, 0x3e2aaaab
	v_fma_f32 v3, v6, v3, 0.5
	v_fma_f32 v3, v6, v3, 1.0
	ds_write_b64 v96, v[4:5] offset:41984
	v_mul_f32_e64 v3, v3, -v6
	v_fma_f32 v4, -v2, v2, 1.0
	v_cndmask_b32_e64 v3, v4, v3, s[0:1]
	v_max_f32_e32 v3, 0, v3
	ds_read_u16 v4, v41 offset:1584
	v_sqrt_f32_e32 v3, v3
	s_waitcnt lgkmcnt(0)
	v_lshlrev_b32_e32 v4, 16, v4
	v_mul_f32_e32 v3, v9, v3
	v_mul_f32_e32 v3, v3, v4
	ds_write_b64 v97, v[2:3] offset:41984
	v_add_f32_e32 v2, v26, v80
	v_mul_f32_e32 v2, 0xbfb8aa3b, v2
	v_exp_f32_e32 v2, v2
	v_add_f32_e32 v4, v11, v71
	v_mul_f32_e32 v4, 0xbfb8aa3b, v4
	v_exp_f32_e32 v4, v4
	v_add_f32_e32 v2, 1.0, v2
	v_rcp_f32_e32 v3, v2
	v_add_f32_e32 v2, v10, v71
	v_mul_f32_e32 v2, 0xbfb8aa3b, v2
	v_exp_f32_e32 v2, v2
	v_add_f32_e32 v4, 1.0, v4
	v_rcp_f32_e32 v9, v4
	v_add_f32_e32 v2, 1.0, v2
	v_rcp_f32_e32 v5, v2
	ds_read_u16 v2, v41 offset:2304
	s_waitcnt lgkmcnt(0)
	v_lshlrev_b32_e32 v8, 16, v2
	v_add_f32_e32 v2, v27, v80
	v_mul_f32_e32 v2, 0xbfb8aa3b, v2
	v_exp_f32_e32 v2, v2
	s_nop 0
	v_add_f32_e32 v2, 1.0, v2
	v_rcp_f32_e32 v2, v2
	s_nop 0
	v_pk_mul_f32 v[2:3], v[2:3], s[24:25] op_sel_hi:[1,0]
	s_nop 0
	v_pk_mul_f32 v[2:3], v[2:3], v[0:1] op_sel_hi:[1,0]
	s_nop 0
	v_mul_f32_e32 v4, 0x3fb8aa3b, v3
	v_pk_add_f32 v[6:7], v[2:3], v[2:3]
	v_exp_f32_e32 v4, v4
	v_fmamk_f32 v3, v7, 0x3c088889, v212
	v_fmaak_f32 v3, v7, v3, 0x3e2aaaab
	v_fma_f32 v3, v7, v3, 0.5
	v_fma_f32 v3, v7, v3, 1.0
	v_mul_f32_e64 v3, v3, -v7
	v_fma_f32 v10, -v4, v4, 1.0
	v_cmp_lt_f32_e64 s[12:13], s22, v7
	v_mul_f32_e32 v2, 0x3fb8aa3b, v2
	v_exp_f32_e32 v2, v2
	v_cndmask_b32_e64 v3, v10, v3, s[12:13]
	v_max_f32_e32 v3, 0, v3
	v_sqrt_f32_e32 v3, v3
	v_cmp_lt_f32_e64 s[0:1], s22, v6
	v_mul_f32_e32 v3, v5, v3
	v_mul_f32_e32 v5, v3, v8
	v_fmamk_f32 v3, v6, 0x3c088889, v212
	v_fmaak_f32 v3, v6, v3, 0x3e2aaaab
	v_fma_f32 v3, v6, v3, 0.5
	v_fma_f32 v3, v6, v3, 1.0
	ds_write_b64 v98, v[4:5] offset:41984
	v_mul_f32_e64 v3, v3, -v6
	v_fma_f32 v4, -v2, v2, 1.0
	v_cndmask_b32_e64 v3, v4, v3, s[0:1]
	v_max_f32_e32 v3, 0, v3
	ds_read_u16 v4, v41 offset:2448
	v_sqrt_f32_e32 v3, v3
	s_waitcnt lgkmcnt(0)
; DI float bf2f(u16 v) { return __uint_as_float(((unsigned)v) << 16); }
; DI int crow(int i, int h) { return (i & 3) + 8 * (i >> 2) + 4 * h; }
; DI void lru_item(const Params& p, int l, int b, int chunk, int blk, bool fin, char* smem, int tid) {
;     ...
;       const float b_a = p.ba[pi], b_x = p.bx[pi], lam = p.lam[pi];
;       const float sp = log1pf(__expf(-lam));
; #pragma unroll
;       for (int i = 0; i < 16; i++) {
;         const int tok = tb * 32 + crow(i, h);
;         const float rr = __builtin_amdgcn_rcpf(1.f + __expf(-(ga[i] + b_a))), ii = __builtin_amdgcn_rcpf(1.f + __expf(-(gx[i] + b_x)));
;         const float la = -8.f * rr * sp;
;         const float a = __expf(la);
;         const float x2 = 2.f * la;
;         const float ser = -x2 * (1.f + x2 * (0.5f + x2 * (0.16666667f + x2 * (0.041666668f + x2 * 0.0083333338f))));
;         const float om = (x2 > -0.25f) ? ser : (1.f - a * a);
;         const float u = __builtin_amdgcn_sqrtf(fmaxf(om, 0.f)) * ii * bf2f(xcb[tok][chn]);
;         au[(dir * 64 + tok) * 64 + chn] = make_float2(a, u);
;     ...
;     } else {
;       const float2* ag = agg + ((size_t)b * 68 * 2 + dir) * 256 + c0 + ch;
;       if (dir == 0) {
; #pragma unroll 8
;         for (int cc = 0; cc < chunk; cc++) { float2 v = ag[(size_t)cc * 512]; hst = v.x * hst + v.y; }
;       } else {
;         if (chunk < 4) { for (int cc = 3; cc > chunk; cc--) { float2 v = ag[(size_t)cc * 512]; hst = v.x * hst + v.y; } }
;         else {
;           for (int cc = 3; cc >= 0; cc--) { float2 v = ag[(size_t)cc * 512]; hst = v.x * hst + v.y; }
; #pragma unroll 8
;           for (int cc = 67; cc > chunk; cc--) { float2 v = ag[(size_t)cc * 512]; hst = v.x * hst + v.y; }
;         }
;       }
	v_lshlrev_b32_e32 v4, 16, v4
	v_mul_f32_e32 v3, v9, v3
	v_mul_f32_e32 v3, v3, v4
	ds_write_b64 v99, v[2:3] offset:41984
	v_add_f32_e32 v2, v28, v80
	v_mul_f32_e32 v2, 0xbfb8aa3b, v2
	v_exp_f32_e32 v2, v2
	v_add_f32_e32 v4, v13, v71
	v_mul_f32_e32 v4, 0xbfb8aa3b, v4
	v_exp_f32_e32 v4, v4
	v_add_f32_e32 v2, 1.0, v2
	v_rcp_f32_e32 v3, v2
	v_add_f32_e32 v2, v12, v71
	v_mul_f32_e32 v2, 0xbfb8aa3b, v2
	v_exp_f32_e32 v2, v2
	v_add_f32_e32 v4, 1.0, v4
	v_rcp_f32_e32 v9, v4
	v_add_f32_e32 v2, 1.0, v2
	v_rcp_f32_e32 v5, v2
	ds_read_u16 v2, v41 offset:2592
	s_waitcnt lgkmcnt(0)
	v_lshlrev_b32_e32 v8, 16, v2
	v_add_f32_e32 v2, v29, v80
	v_mul_f32_e32 v2, 0xbfb8aa3b, v2
	v_exp_f32_e32 v2, v2
	s_nop 0
	v_add_f32_e32 v2, 1.0, v2
	v_rcp_f32_e32 v2, v2
	s_nop 0
	v_pk_mul_f32 v[2:3], v[2:3], s[24:25] op_sel_hi:[1,0]
	s_nop 0
	v_pk_mul_f32 v[2:3], v[2:3], v[0:1] op_sel_hi:[1,0]
	s_nop 0
	v_mul_f32_e32 v4, 0x3fb8aa3b, v3
	v_pk_add_f32 v[6:7], v[2:3], v[2:3]
	v_exp_f32_e32 v4, v4
	v_fmamk_f32 v3, v7, 0x3c088889, v212
	v_fmaak_f32 v3, v7, v3, 0x3e2aaaab
	v_fma_f32 v3, v7, v3, 0.5
	v_fma_f32 v3, v7, v3, 1.0
	v_mul_f32_e64 v3, v3, -v7
	v_fma_f32 v10, -v4, v4, 1.0
	v_cmp_lt_f32_e64 s[12:13], s22, v7
	v_mul_f32_e32 v2, 0x3fb8aa3b, v2
	v_exp_f32_e32 v2, v2
	v_cndmask_b32_e64 v3, v10, v3, s[12:13]
	v_max_f32_e32 v3, 0, v3
	v_sqrt_f32_e32 v3, v3
	v_cmp_lt_f32_e64 s[0:1], s22, v6
	v_mul_f32_e32 v3, v5, v3
	v_mul_f32_e32 v5, v3, v8
	v_fmamk_f32 v3, v6, 0x3c088889, v212
	v_fmaak_f32 v3, v6, v3, 0x3e2aaaab
	v_fma_f32 v3, v6, v3, 0.5
	v_fma_f32 v3, v6, v3, 1.0
	ds_write_b64 v100, v[4:5] offset:41984
	v_mul_f32_e64 v3, v3, -v6
	v_fma_f32 v4, -v2, v2, 1.0
	v_cndmask_b32_e64 v3, v4, v3, s[0:1]
	v_max_f32_e32 v3, 0, v3
	ds_read_u16 v4, v41 offset:2736
	v_sqrt_f32_e32 v3, v3
	s_waitcnt lgkmcnt(0)
	v_lshlrev_b32_e32 v4, 16, v4
	v_mul_f32_e32 v3, v9, v3
	v_mul_f32_e32 v3, v3, v4
	ds_write_b64 v101, v[2:3] offset:41984
	v_add_f32_e32 v2, v30, v80
	v_mul_f32_e32 v2, 0xbfb8aa3b, v2
	v_exp_f32_e32 v2, v2
	v_add_f32_e32 v4, v15, v71
	v_mul_f32_e32 v4, 0xbfb8aa3b, v4
	v_exp_f32_e32 v4, v4
	v_add_f32_e32 v2, 1.0, v2
	v_rcp_f32_e32 v3, v2
	v_add_f32_e32 v2, v14, v71
	v_mul_f32_e32 v2, 0xbfb8aa3b, v2
	v_exp_f32_e32 v2, v2
	v_add_f32_e32 v4, 1.0, v4
	v_rcp_f32_e32 v9, v4
	v_add_f32_e32 v2, 1.0, v2
	v_rcp_f32_e32 v5, v2
	ds_read_u16 v2, v41 offset:3456
	s_waitcnt lgkmcnt(0)
	v_lshlrev_b32_e32 v8, 16, v2
	v_add_f32_e32 v2, v31, v80
	v_mul_f32_e32 v2, 0xbfb8aa3b, v2
	v_exp_f32_e32 v2, v2
	s_nop 0
	v_add_f32_e32 v2, 1.0, v2
	v_rcp_f32_e32 v2, v2
	s_nop 0
	v_pk_mul_f32 v[2:3], v[2:3], s[24:25] op_sel_hi:[1,0]
	s_nop 0
	v_pk_mul_f32 v[2:3], v[2:3], v[0:1] op_sel_hi:[1,0]
	s_nop 0
	v_mul_f32_e32 v4, 0x3fb8aa3b, v3
	v_pk_add_f32 v[6:7], v[2:3], v[2:3]
	v_exp_f32_e32 v4, v4
	v_fmamk_f32 v3, v7, 0x3c088889, v212
	v_fmaak_f32 v3, v7, v3, 0x3e2aaaab
	v_fma_f32 v3, v7, v3, 0.5
	v_fma_f32 v3, v7, v3, 1.0
	v_mul_f32_e64 v3, v3, -v7
	v_fma_f32 v10, -v4, v4, 1.0
	v_cmp_lt_f32_e64 s[12:13], s22, v7
	v_mul_f32_e32 v2, 0x3fb8aa3b, v2
	v_exp_f32_e32 v2, v2
	v_cndmask_b32_e64 v3, v10, v3, s[12:13]
	v_max_f32_e32 v3, 0, v3
	v_sqrt_f32_e32 v3, v3
	v_cmp_lt_f32_e64 s[0:1], s22, v6
	v_mul_f32_e32 v3, v5, v3
	v_mul_f32_e32 v5, v3, v8
	v_fmamk_f32 v3, v6, 0x3c088889, v212
	v_fmaak_f32 v3, v6, v3, 0x3e2aaaab
	v_fma_f32 v3, v6, v3, 0.5
	v_fma_f32 v3, v6, v3, 1.0
	ds_write_b64 v102, v[4:5] offset:41984
	v_mul_f32_e64 v3, v3, -v6
	v_fma_f32 v4, -v2, v2, 1.0
	v_cndmask_b32_e64 v3, v4, v3, s[0:1]
	v_max_f32_e32 v3, 0, v3
	ds_read_u16 v4, v41 offset:3600
	v_sqrt_f32_e32 v3, v3
	s_waitcnt lgkmcnt(0)
	v_lshlrev_b32_e32 v4, 16, v4
	v_mul_f32_e32 v3, v9, v3
	v_mul_f32_e32 v3, v3, v4
	ds_write_b64 v103, v[2:3] offset:41984
	v_add_f32_e32 v2, v32, v80
	v_mul_f32_e32 v2, 0xbfb8aa3b, v2
	v_exp_f32_e32 v2, v2
	v_add_f32_e32 v4, v17, v71
	v_mul_f32_e32 v4, 0xbfb8aa3b, v4
	v_exp_f32_e32 v4, v4
	v_add_f32_e32 v2, 1.0, v2
	v_rcp_f32_e32 v3, v2
	v_add_f32_e32 v2, v16, v71
	v_mul_f32_e32 v2, 0xbfb8aa3b, v2
	v_exp_f32_e32 v2, v2
	v_add_f32_e32 v4, 1.0, v4
	v_rcp_f32_e32 v9, v4
	v_add_f32_e32 v2, 1.0, v2
	v_rcp_f32_e32 v5, v2
	ds_read_u16 v2, v41 offset:3744
	s_waitcnt lgkmcnt(0)
	v_lshlrev_b32_e32 v8, 16, v2
	v_add_f32_e32 v2, v33, v80
	v_mul_f32_e32 v2, 0xbfb8aa3b, v2
	v_exp_f32_e32 v2, v2
	s_nop 0
	v_add_f32_e32 v2, 1.0, v2
	v_rcp_f32_e32 v2, v2
	s_nop 0
	v_pk_mul_f32 v[2:3], v[2:3], s[24:25] op_sel_hi:[1,0]
	s_nop 0
	v_pk_mul_f32 v[2:3], v[2:3], v[0:1] op_sel_hi:[1,0]
	s_nop 0
	v_mul_f32_e32 v0, 0x3fb8aa3b, v3
	v_pk_add_f32 v[6:7], v[2:3], v[2:3]
	v_exp_f32_e32 v4, v0
	v_fmamk_f32 v0, v7, 0x3c088889, v212
	v_fmaak_f32 v0, v7, v0, 0x3e2aaaab
	v_fma_f32 v0, v7, v0, 0.5
	v_fma_f32 v0, v7, v0, 1.0
	v_mul_f32_e64 v0, v0, -v7
	v_fma_f32 v3, -v4, v4, 1.0
	v_cmp_lt_f32_e64 s[12:13], s22, v7
	v_cmp_lt_f32_e64 s[0:1], s22, v6
	s_nop 0
	v_cndmask_b32_e64 v0, v3, v0, s[12:13]
	v_max_f32_e32 v0, 0, v0
	v_sqrt_f32_e32 v0, v0
	s_nop 0
	v_mul_f32_e32 v0, v5, v0
	v_mul_f32_e32 v5, v0, v8
	v_mul_f32_e32 v0, 0x3fb8aa3b, v2
	v_exp_f32_e32 v2, v0
	v_fmamk_f32 v0, v6, 0x3c088889, v212
	v_fmaak_f32 v0, v6, v0, 0x3e2aaaab
	v_fma_f32 v0, v6, v0, 0.5
	v_fma_f32 v0, v6, v0, 1.0
	v_mul_f32_e64 v0, v0, -v6
	v_fma_f32 v3, -v2, v2, 1.0
	ds_write_b64 v104, v[4:5] offset:41984
	v_cndmask_b32_e64 v0, v3, v0, s[0:1]
	v_max_f32_e32 v0, 0, v0
	ds_read_u16 v3, v41 offset:3888
	v_sqrt_f32_e32 v0, v0
	s_waitcnt lgkmcnt(0)
	v_lshlrev_b32_e32 v3, 16, v3
	v_mul_f32_e32 v0, v9, v0
	v_mul_f32_e32 v3, v0, v3
	ds_write_b64 v105, v[2:3] offset:41984
	s_waitcnt lgkmcnt(0)
	s_barrier
	s_and_saveexec_b64 s[0:1], s[4:5]
	s_cbranch_execz .LBB0_1085
	v_lshrrev_b32_e32 v0, 6, v206
	v_and_b32_e32 v2, 63, v206
	v_readfirstlane_b32 s20, v77
	v_readfirstlane_b32 s21, v73
	v_readfirstlane_b32 s22, v74
	v_readfirstlane_b32 s23, v0
	v_lshlrev_b32_e32 v2, 3, v2
	v_readlane_b32 s2, v253, 44
	v_readlane_b32 s3, v253, 45
	s_mul_i32 s12, s21, 0x88
	s_add_u32 s12, s12, s23
	s_lshl_b32 s12, s12, 11
	s_lshl_b32 s13, s22, 3
	s_add_u32 s12, s12, s13
	s_add_u32 s2, s2, s12
	s_addc_u32 s3, s3, 0
	v_mov_b32_e32 v5, 0
	s_cmp_eq_u32 s23, 0
	s_cbranch_scc0 .Llf_dir1
	s_mov_b32 s24, 0x1000
	s_mov_b32 s25, 0
	s_mov_b32 s26, s2
	s_mov_b32 s27, s3
	s_mov_b32 s12, s20
	s_mov_b32 s13, 0
	s_branch .Llf_run
; DI void lru_item(const Params& p, int l, int b, int chunk, int blk, bool fin, char* smem, int tid) {
;     ...
;       const float2* ag = agg + ((size_t)b * 68 * 2 + dir) * 256 + c0 + ch;
;       if (dir == 0) {
; #pragma unroll 8
;         for (int cc = 0; cc < chunk; cc++) { float2 v = ag[(size_t)cc * 512]; hst = v.x * hst + v.y; }
;       } else {
;         if (chunk < 4) { for (int cc = 3; cc > chunk; cc--) { float2 v = ag[(size_t)cc * 512]; hst = v.x * hst + v.y; } }
;         else {
;           for (int cc = 3; cc >= 0; cc--) { float2 v = ag[(size_t)cc * 512]; hst = v.x * hst + v.y; }
; #pragma unroll 8
;           for (int cc = 67; cc > chunk; cc--) { float2 v = ag[(size_t)cc * 512]; hst = v.x * hst + v.y; }
;         }
;       }
; #pragma unroll 8
;       for (int s2 = 0; s2 < 64; s2++) { const int t = dir ? 63 - s2 : s2; float2 v = au[(dir * 64 + t) * 64 + ch]; hst = v.x * hst + v.y; au[(dir * 64 + t) * 64 + ch].y = hst; }
.Llf_dir1:
	s_mov_b32 s24, 0xfffff000
	s_mov_b32 s25, -1
	s_add_u32 s26, s2, 0x3000
	s_addc_u32 s27, s3, 0
	s_cmp_lt_u32 s20, 4
	s_cbranch_scc1 .Llf_ctx
	s_mov_b32 s12, 4
	s_sub_u32 s13, 0x43, s20
	s_branch .Llf_run
.Llf_ctx:
	s_sub_u32 s12, 3, s20
	s_mov_b32 s13, 0
.Llf_run:
	s_cmp_lt_i32 s12, 1
	s_cbranch_scc1 .Llf_next
	global_load_dwordx2 v[106:107], v2, s[26:27]
	s_add_u32 s26, s26, s24
	s_addc_u32 s27, s27, s25
	global_load_dwordx2 v[108:109], v2, s[26:27]
	s_add_u32 s26, s26, s24
	s_addc_u32 s27, s27, s25
	global_load_dwordx2 v[110:111], v2, s[26:27]
	s_add_u32 s26, s26, s24
	s_addc_u32 s27, s27, s25
	global_load_dwordx2 v[112:113], v2, s[26:27]
	s_add_u32 s26, s26, s24
	s_addc_u32 s27, s27, s25
	global_load_dwordx2 v[114:115], v2, s[26:27]
	s_add_u32 s26, s26, s24
	s_addc_u32 s27, s27, s25
	global_load_dwordx2 v[116:117], v2, s[26:27]
	s_add_u32 s26, s26, s24
	s_addc_u32 s27, s27, s25
	global_load_dwordx2 v[118:119], v2, s[26:27]
	s_add_u32 s26, s26, s24
	s_addc_u32 s27, s27, s25
	global_load_dwordx2 v[120:121], v2, s[26:27]
	s_add_u32 s26, s26, s24
	s_addc_u32 s27, s27, s25
	s_waitcnt vmcnt(0)
	v_fma_f32 v5, v5, v106, v107
	s_cmp_eq_u32 s12, 1
	s_cbranch_scc1 .Llf_next
	v_fma_f32 v5, v5, v108, v109
	s_cmp_eq_u32 s12, 2
	s_cbranch_scc1 .Llf_next
	v_fma_f32 v5, v5, v110, v111
	s_cmp_eq_u32 s12, 3
	s_cbranch_scc1 .Llf_next
	v_fma_f32 v5, v5, v112, v113
	s_cmp_eq_u32 s12, 4
	s_cbranch_scc1 .Llf_next
	v_fma_f32 v5, v5, v114, v115
	s_cmp_eq_u32 s12, 5
	s_cbranch_scc1 .Llf_next
	v_fma_f32 v5, v5, v116, v117
	s_cmp_eq_u32 s12, 6
	s_cbranch_scc1 .Llf_next
	v_fma_f32 v5, v5, v118, v119
	s_cmp_eq_u32 s12, 7
	s_cbranch_scc1 .Llf_next
	v_fma_f32 v5, v5, v120, v121
	s_sub_u32 s12, s12, 8
	s_branch .Llf_run
.Llf_next:
	s_cmp_lt_i32 s13, 1
	s_cbranch_scc1 .Llf_scan
	s_mov_b32 s12, s13
	s_mov_b32 s13, 0
	s_add_u32 s26, s2, 0x43000
	s_addc_u32 s27, s3, 0
	s_branch .Llf_run
.Llf_scan:
	s_lshl_b32 s12, s23, 15
	v_add_u32_e32 v3, s12, v2
	s_cmp_eq_u32 s23, 0
	s_cbranch_scc0 .Llf_scan1
	ds_read_b64 v[106:107], v3 offset:9216
	ds_read_b64 v[108:109], v3 offset:9728
	ds_read_b64 v[110:111], v3 offset:10240
	ds_read_b64 v[112:113], v3 offset:10752
	ds_read_b64 v[114:115], v3 offset:11264
	ds_read_b64 v[116:117], v3 offset:11776
	ds_read_b64 v[118:119], v3 offset:12288
	ds_read_b64 v[120:121], v3 offset:12800
	s_waitcnt lgkmcnt(7)
	v_fma_f32 v5, v106, v5, v107
	v_mov_b32_e32 v107, v5
	s_waitcnt lgkmcnt(6)
	v_fma_f32 v5, v108, v5, v109
	v_mov_b32_e32 v109, v5
	s_waitcnt lgkmcnt(5)
	v_fma_f32 v5, v110, v5, v111
	v_mov_b32_e32 v111, v5
	s_waitcnt lgkmcnt(4)
	v_fma_f32 v5, v112, v5, v113
	v_mov_b32_e32 v113, v5
	s_waitcnt lgkmcnt(3)
	v_fma_f32 v5, v114, v5, v115
	v_mov_b32_e32 v115, v5
	s_waitcnt lgkmcnt(2)
	v_fma_f32 v5, v116, v5, v117
	v_mov_b32_e32 v117, v5
	s_waitcnt lgkmcnt(1)
	v_fma_f32 v5, v118, v5, v119
	v_mov_b32_e32 v119, v5
	s_waitcnt lgkmcnt(0)
	v_fma_f32 v5, v120, v5, v121
	v_mov_b32_e32 v121, v5
	ds_write_b32 v3, v107 offset:9220
	ds_write_b32 v3, v109 offset:9732
	ds_write_b32 v3, v111 offset:10244
	ds_write_b32 v3, v113 offset:10756
	ds_write_b32 v3, v115 offset:11268
	ds_write_b32 v3, v117 offset:11780
	ds_write_b32 v3, v119 offset:12292
	ds_write_b32 v3, v121 offset:12804
	ds_read_b64 v[106:107], v3 offset:13312
	ds_read_b64 v[108:109], v3 offset:13824
	ds_read_b64 v[110:111], v3 offset:14336
	ds_read_b64 v[112:113], v3 offset:14848
	ds_read_b64 v[114:115], v3 offset:15360
	ds_read_b64 v[116:117], v3 offset:15872
	ds_read_b64 v[118:119], v3 offset:16384
	ds_read_b64 v[120:121], v3 offset:16896
	s_waitcnt lgkmcnt(7)
	v_fma_f32 v5, v106, v5, v107
	v_mov_b32_e32 v107, v5
	s_waitcnt lgkmcnt(6)
	v_fma_f32 v5, v108, v5, v109
	v_mov_b32_e32 v109, v5
	s_waitcnt lgkmcnt(5)
	v_fma_f32 v5, v110, v5, v111
	v_mov_b32_e32 v111, v5
	s_waitcnt lgkmcnt(4)
	v_fma_f32 v5, v112, v5, v113
	v_mov_b32_e32 v113, v5
	s_waitcnt lgkmcnt(3)
	v_fma_f32 v5, v114, v5, v115
	v_mov_b32_e32 v115, v5
	s_waitcnt lgkmcnt(2)
	v_fma_f32 v5, v116, v5, v117
	v_mov_b32_e32 v117, v5
	s_waitcnt lgkmcnt(1)
	v_fma_f32 v5, v118, v5, v119
	v_mov_b32_e32 v119, v5
	s_waitcnt lgkmcnt(0)
	v_fma_f32 v5, v120, v5, v121
	v_mov_b32_e32 v121, v5
	ds_write_b32 v3, v107 offset:13316
	ds_write_b32 v3, v109 offset:13828
	ds_write_b32 v3, v111 offset:14340
	ds_write_b32 v3, v113 offset:14852
	ds_write_b32 v3, v115 offset:15364
	ds_write_b32 v3, v117 offset:15876
	ds_write_b32 v3, v119 offset:16388
	ds_write_b32 v3, v121 offset:16900
	ds_read_b64 v[106:107], v3 offset:17408
	ds_read_b64 v[108:109], v3 offset:17920
	ds_read_b64 v[110:111], v3 offset:18432
	ds_read_b64 v[112:113], v3 offset:18944
	ds_read_b64 v[114:115], v3 offset:19456
	ds_read_b64 v[116:117], v3 offset:19968
	ds_read_b64 v[118:119], v3 offset:20480
	ds_read_b64 v[120:121], v3 offset:20992
	s_waitcnt lgkmcnt(7)
	v_fma_f32 v5, v106, v5, v107
	v_mov_b32_e32 v107, v5
	s_waitcnt lgkmcnt(6)
	v_fma_f32 v5, v108, v5, v109
	v_mov_b32_e32 v109, v5
	s_waitcnt lgkmcnt(5)
	v_fma_f32 v5, v110, v5, v111
	v_mov_b32_e32 v111, v5
	s_waitcnt lgkmcnt(4)
	v_fma_f32 v5, v112, v5, v113
	v_mov_b32_e32 v113, v5
	s_waitcnt lgkmcnt(3)
	v_fma_f32 v5, v114, v5, v115
	v_mov_b32_e32 v115, v5
	s_waitcnt lgkmcnt(2)
	v_fma_f32 v5, v116, v5, v117
	v_mov_b32_e32 v117, v5
	s_waitcnt lgkmcnt(1)
	v_fma_f32 v5, v118, v5, v119
	v_mov_b32_e32 v119, v5
	s_waitcnt lgkmcnt(0)
; DI void lru_item(const Params& p, int l, int b, int chunk, int blk, bool fin, char* smem, int tid) {
;     ...
;       for (int s2 = 0; s2 < 64; s2++) { const int t = dir ? 63 - s2 : s2; float2 v = au[(dir * 64 + t) * 64 + ch]; hst = v.x * hst + v.y; au[(dir * 64 + t) * 64 + ch].y = hst; }
	v_fma_f32 v5, v120, v5, v121
	v_mov_b32_e32 v121, v5
	ds_write_b32 v3, v107 offset:17412
	ds_write_b32 v3, v109 offset:17924
	ds_write_b32 v3, v111 offset:18436
	ds_write_b32 v3, v113 offset:18948
	ds_write_b32 v3, v115 offset:19460
	ds_write_b32 v3, v117 offset:19972
	ds_write_b32 v3, v119 offset:20484
	ds_write_b32 v3, v121 offset:20996
	ds_read_b64 v[106:107], v3 offset:21504
	ds_read_b64 v[108:109], v3 offset:22016
	ds_read_b64 v[110:111], v3 offset:22528
	ds_read_b64 v[112:113], v3 offset:23040
	ds_read_b64 v[114:115], v3 offset:23552
	ds_read_b64 v[116:117], v3 offset:24064
	ds_read_b64 v[118:119], v3 offset:24576
	ds_read_b64 v[120:121], v3 offset:25088
	s_waitcnt lgkmcnt(7)
	v_fma_f32 v5, v106, v5, v107
	v_mov_b32_e32 v107, v5
	s_waitcnt lgkmcnt(6)
	v_fma_f32 v5, v108, v5, v109
	v_mov_b32_e32 v109, v5
	s_waitcnt lgkmcnt(5)
	v_fma_f32 v5, v110, v5, v111
	v_mov_b32_e32 v111, v5
	s_waitcnt lgkmcnt(4)
	v_fma_f32 v5, v112, v5, v113
	v_mov_b32_e32 v113, v5
	s_waitcnt lgkmcnt(3)
	v_fma_f32 v5, v114, v5, v115
	v_mov_b32_e32 v115, v5
	s_waitcnt lgkmcnt(2)
	v_fma_f32 v5, v116, v5, v117
	v_mov_b32_e32 v117, v5
	s_waitcnt lgkmcnt(1)
	v_fma_f32 v5, v118, v5, v119
	v_mov_b32_e32 v119, v5
	s_waitcnt lgkmcnt(0)
	v_fma_f32 v5, v120, v5, v121
	v_mov_b32_e32 v121, v5
	ds_write_b32 v3, v107 offset:21508
	ds_write_b32 v3, v109 offset:22020
	ds_write_b32 v3, v111 offset:22532
	ds_write_b32 v3, v113 offset:23044
	ds_write_b32 v3, v115 offset:23556
	ds_write_b32 v3, v117 offset:24068
	ds_write_b32 v3, v119 offset:24580
	ds_write_b32 v3, v121 offset:25092
	ds_read_b64 v[106:107], v3 offset:25600
	ds_read_b64 v[108:109], v3 offset:26112
	ds_read_b64 v[110:111], v3 offset:26624
	ds_read_b64 v[112:113], v3 offset:27136
	ds_read_b64 v[114:115], v3 offset:27648
	ds_read_b64 v[116:117], v3 offset:28160
	ds_read_b64 v[118:119], v3 offset:28672
	ds_read_b64 v[120:121], v3 offset:29184
	s_waitcnt lgkmcnt(7)
	v_fma_f32 v5, v106, v5, v107
	v_mov_b32_e32 v107, v5
	s_waitcnt lgkmcnt(6)
	v_fma_f32 v5, v108, v5, v109
	v_mov_b32_e32 v109, v5
	s_waitcnt lgkmcnt(5)
	v_fma_f32 v5, v110, v5, v111
	v_mov_b32_e32 v111, v5
	s_waitcnt lgkmcnt(4)
	v_fma_f32 v5, v112, v5, v113
	v_mov_b32_e32 v113, v5
	s_waitcnt lgkmcnt(3)
	v_fma_f32 v5, v114, v5, v115
	v_mov_b32_e32 v115, v5
	s_waitcnt lgkmcnt(2)
	v_fma_f32 v5, v116, v5, v117
	v_mov_b32_e32 v117, v5
	s_waitcnt lgkmcnt(1)
	v_fma_f32 v5, v118, v5, v119
	v_mov_b32_e32 v119, v5
	s_waitcnt lgkmcnt(0)
	v_fma_f32 v5, v120, v5, v121
	v_mov_b32_e32 v121, v5
	ds_write_b32 v3, v107 offset:25604
	ds_write_b32 v3, v109 offset:26116
	ds_write_b32 v3, v111 offset:26628
	ds_write_b32 v3, v113 offset:27140
	ds_write_b32 v3, v115 offset:27652
	ds_write_b32 v3, v117 offset:28164
	ds_write_b32 v3, v119 offset:28676
	ds_write_b32 v3, v121 offset:29188
	ds_read_b64 v[106:107], v3 offset:29696
	ds_read_b64 v[108:109], v3 offset:30208
	ds_read_b64 v[110:111], v3 offset:30720
	ds_read_b64 v[112:113], v3 offset:31232
	ds_read_b64 v[114:115], v3 offset:31744
	ds_read_b64 v[116:117], v3 offset:32256
	ds_read_b64 v[118:119], v3 offset:32768
	ds_read_b64 v[120:121], v3 offset:33280
	s_waitcnt lgkmcnt(7)
	v_fma_f32 v5, v106, v5, v107
	v_mov_b32_e32 v107, v5
	s_waitcnt lgkmcnt(6)
	v_fma_f32 v5, v108, v5, v109
	v_mov_b32_e32 v109, v5
	s_waitcnt lgkmcnt(5)
	v_fma_f32 v5, v110, v5, v111
	v_mov_b32_e32 v111, v5
	s_waitcnt lgkmcnt(4)
	v_fma_f32 v5, v112, v5, v113
	v_mov_b32_e32 v113, v5
	s_waitcnt lgkmcnt(3)
	v_fma_f32 v5, v114, v5, v115
	v_mov_b32_e32 v115, v5
	s_waitcnt lgkmcnt(2)
	v_fma_f32 v5, v116, v5, v117
	v_mov_b32_e32 v117, v5
	s_waitcnt lgkmcnt(1)
	v_fma_f32 v5, v118, v5, v119
	v_mov_b32_e32 v119, v5
	s_waitcnt lgkmcnt(0)
	v_fma_f32 v5, v120, v5, v121
	v_mov_b32_e32 v121, v5
	ds_write_b32 v3, v107 offset:29700
	ds_write_b32 v3, v109 offset:30212
	ds_write_b32 v3, v111 offset:30724
	ds_write_b32 v3, v113 offset:31236
	ds_write_b32 v3, v115 offset:31748
	ds_write_b32 v3, v117 offset:32260
	ds_write_b32 v3, v119 offset:32772
	ds_write_b32 v3, v121 offset:33284
	ds_read_b64 v[106:107], v3 offset:33792
	ds_read_b64 v[108:109], v3 offset:34304
	ds_read_b64 v[110:111], v3 offset:34816
	ds_read_b64 v[112:113], v3 offset:35328
	ds_read_b64 v[114:115], v3 offset:35840
	ds_read_b64 v[116:117], v3 offset:36352
	ds_read_b64 v[118:119], v3 offset:36864
	ds_read_b64 v[120:121], v3 offset:37376
	s_waitcnt lgkmcnt(7)
	v_fma_f32 v5, v106, v5, v107
	v_mov_b32_e32 v107, v5
	s_waitcnt lgkmcnt(6)
	v_fma_f32 v5, v108, v5, v109
	v_mov_b32_e32 v109, v5
	s_waitcnt lgkmcnt(5)
	v_fma_f32 v5, v110, v5, v111
	v_mov_b32_e32 v111, v5
	s_waitcnt lgkmcnt(4)
	v_fma_f32 v5, v112, v5, v113
	v_mov_b32_e32 v113, v5
	s_waitcnt lgkmcnt(3)
	v_fma_f32 v5, v114, v5, v115
	v_mov_b32_e32 v115, v5
	s_waitcnt lgkmcnt(2)
	v_fma_f32 v5, v116, v5, v117
	v_mov_b32_e32 v117, v5
	s_waitcnt lgkmcnt(1)
	v_fma_f32 v5, v118, v5, v119
	v_mov_b32_e32 v119, v5
	s_waitcnt lgkmcnt(0)
	v_fma_f32 v5, v120, v5, v121
	v_mov_b32_e32 v121, v5
	ds_write_b32 v3, v107 offset:33796
	ds_write_b32 v3, v109 offset:34308
	ds_write_b32 v3, v111 offset:34820
	ds_write_b32 v3, v113 offset:35332
	ds_write_b32 v3, v115 offset:35844
	ds_write_b32 v3, v117 offset:36356
	ds_write_b32 v3, v119 offset:36868
	ds_write_b32 v3, v121 offset:37380
	ds_read_b64 v[106:107], v3 offset:37888
	ds_read_b64 v[108:109], v3 offset:38400
	ds_read_b64 v[110:111], v3 offset:38912
	ds_read_b64 v[112:113], v3 offset:39424
	ds_read_b64 v[114:115], v3 offset:39936
	ds_read_b64 v[116:117], v3 offset:40448
	ds_read_b64 v[118:119], v3 offset:40960
	ds_read_b64 v[120:121], v3 offset:41472
	s_waitcnt lgkmcnt(7)
	v_fma_f32 v5, v106, v5, v107
	v_mov_b32_e32 v107, v5
	s_waitcnt lgkmcnt(6)
	v_fma_f32 v5, v108, v5, v109
	v_mov_b32_e32 v109, v5
	s_waitcnt lgkmcnt(5)
	v_fma_f32 v5, v110, v5, v111
	v_mov_b32_e32 v111, v5
	s_waitcnt lgkmcnt(4)
	v_fma_f32 v5, v112, v5, v113
	v_mov_b32_e32 v113, v5
	s_waitcnt lgkmcnt(3)
	v_fma_f32 v5, v114, v5, v115
	v_mov_b32_e32 v115, v5
	s_waitcnt lgkmcnt(2)
	v_fma_f32 v5, v116, v5, v117
	v_mov_b32_e32 v117, v5
	s_waitcnt lgkmcnt(1)
	v_fma_f32 v5, v118, v5, v119
	v_mov_b32_e32 v119, v5
	s_waitcnt lgkmcnt(0)
	v_fma_f32 v5, v120, v5, v121
	v_mov_b32_e32 v121, v5
	ds_write_b32 v3, v107 offset:37892
	ds_write_b32 v3, v109 offset:38404
	ds_write_b32 v3, v111 offset:38916
	ds_write_b32 v3, v113 offset:39428
	ds_write_b32 v3, v115 offset:39940
	ds_write_b32 v3, v117 offset:40452
	ds_write_b32 v3, v119 offset:40964
	ds_write_b32 v3, v121 offset:41476
	s_branch .Llf_scan_done
; DI void lru_item(const Params& p, int l, int b, int chunk, int blk, bool fin, char* smem, int tid) {
;     ...
;       for (int s2 = 0; s2 < 64; s2++) { const int t = dir ? 63 - s2 : s2; float2 v = au[(dir * 64 + t) * 64 + ch]; hst = v.x * hst + v.y; au[(dir * 64 + t) * 64 + ch].y = hst; }
.Llf_scan1:
	ds_read_b64 v[106:107], v3 offset:41472
	ds_read_b64 v[108:109], v3 offset:40960
	ds_read_b64 v[110:111], v3 offset:40448
	ds_read_b64 v[112:113], v3 offset:39936
	ds_read_b64 v[114:115], v3 offset:39424
	ds_read_b64 v[116:117], v3 offset:38912
	ds_read_b64 v[118:119], v3 offset:38400
	ds_read_b64 v[120:121], v3 offset:37888
	s_waitcnt lgkmcnt(7)
	v_fma_f32 v5, v106, v5, v107
	v_mov_b32_e32 v107, v5
	s_waitcnt lgkmcnt(6)
	v_fma_f32 v5, v108, v5, v109
	v_mov_b32_e32 v109, v5
	s_waitcnt lgkmcnt(5)
	v_fma_f32 v5, v110, v5, v111
	v_mov_b32_e32 v111, v5
	s_waitcnt lgkmcnt(4)
	v_fma_f32 v5, v112, v5, v113
	v_mov_b32_e32 v113, v5
	s_waitcnt lgkmcnt(3)
	v_fma_f32 v5, v114, v5, v115
	v_mov_b32_e32 v115, v5
	s_waitcnt lgkmcnt(2)
	v_fma_f32 v5, v116, v5, v117
	v_mov_b32_e32 v117, v5
	s_waitcnt lgkmcnt(1)
	v_fma_f32 v5, v118, v5, v119
	v_mov_b32_e32 v119, v5
	s_waitcnt lgkmcnt(0)
	v_fma_f32 v5, v120, v5, v121
	v_mov_b32_e32 v121, v5
	ds_write_b32 v3, v107 offset:41476
	ds_write_b32 v3, v109 offset:40964
	ds_write_b32 v3, v111 offset:40452
	ds_write_b32 v3, v113 offset:39940
	ds_write_b32 v3, v115 offset:39428
	ds_write_b32 v3, v117 offset:38916
	ds_write_b32 v3, v119 offset:38404
	ds_write_b32 v3, v121 offset:37892
	ds_read_b64 v[106:107], v3 offset:37376
	ds_read_b64 v[108:109], v3 offset:36864
	ds_read_b64 v[110:111], v3 offset:36352
	ds_read_b64 v[112:113], v3 offset:35840
	ds_read_b64 v[114:115], v3 offset:35328
	ds_read_b64 v[116:117], v3 offset:34816
	ds_read_b64 v[118:119], v3 offset:34304
	ds_read_b64 v[120:121], v3 offset:33792
	s_waitcnt lgkmcnt(7)
	v_fma_f32 v5, v106, v5, v107
	v_mov_b32_e32 v107, v5
	s_waitcnt lgkmcnt(6)
	v_fma_f32 v5, v108, v5, v109
	v_mov_b32_e32 v109, v5
	s_waitcnt lgkmcnt(5)
	v_fma_f32 v5, v110, v5, v111
	v_mov_b32_e32 v111, v5
	s_waitcnt lgkmcnt(4)
	v_fma_f32 v5, v112, v5, v113
	v_mov_b32_e32 v113, v5
	s_waitcnt lgkmcnt(3)
	v_fma_f32 v5, v114, v5, v115
	v_mov_b32_e32 v115, v5
	s_waitcnt lgkmcnt(2)
	v_fma_f32 v5, v116, v5, v117
	v_mov_b32_e32 v117, v5
	s_waitcnt lgkmcnt(1)
	v_fma_f32 v5, v118, v5, v119
	v_mov_b32_e32 v119, v5
	s_waitcnt lgkmcnt(0)
	v_fma_f32 v5, v120, v5, v121
	v_mov_b32_e32 v121, v5
	ds_write_b32 v3, v107 offset:37380
	ds_write_b32 v3, v109 offset:36868
	ds_write_b32 v3, v111 offset:36356
	ds_write_b32 v3, v113 offset:35844
	ds_write_b32 v3, v115 offset:35332
	ds_write_b32 v3, v117 offset:34820
	ds_write_b32 v3, v119 offset:34308
	ds_write_b32 v3, v121 offset:33796
	ds_read_b64 v[106:107], v3 offset:33280
	ds_read_b64 v[108:109], v3 offset:32768
	ds_read_b64 v[110:111], v3 offset:32256
	ds_read_b64 v[112:113], v3 offset:31744
	ds_read_b64 v[114:115], v3 offset:31232
	ds_read_b64 v[116:117], v3 offset:30720
	ds_read_b64 v[118:119], v3 offset:30208
	ds_read_b64 v[120:121], v3 offset:29696
	s_waitcnt lgkmcnt(7)
	v_fma_f32 v5, v106, v5, v107
	v_mov_b32_e32 v107, v5
	s_waitcnt lgkmcnt(6)
	v_fma_f32 v5, v108, v5, v109
	v_mov_b32_e32 v109, v5
	s_waitcnt lgkmcnt(5)
	v_fma_f32 v5, v110, v5, v111
	v_mov_b32_e32 v111, v5
	s_waitcnt lgkmcnt(4)
	v_fma_f32 v5, v112, v5, v113
	v_mov_b32_e32 v113, v5
	s_waitcnt lgkmcnt(3)
	v_fma_f32 v5, v114, v5, v115
	v_mov_b32_e32 v115, v5
	s_waitcnt lgkmcnt(2)
	v_fma_f32 v5, v116, v5, v117
	v_mov_b32_e32 v117, v5
	s_waitcnt lgkmcnt(1)
	v_fma_f32 v5, v118, v5, v119
	v_mov_b32_e32 v119, v5
	s_waitcnt lgkmcnt(0)
	v_fma_f32 v5, v120, v5, v121
	v_mov_b32_e32 v121, v5
	ds_write_b32 v3, v107 offset:33284
	ds_write_b32 v3, v109 offset:32772
	ds_write_b32 v3, v111 offset:32260
	ds_write_b32 v3, v113 offset:31748
	ds_write_b32 v3, v115 offset:31236
	ds_write_b32 v3, v117 offset:30724
	ds_write_b32 v3, v119 offset:30212
	ds_write_b32 v3, v121 offset:29700
	ds_read_b64 v[106:107], v3 offset:29184
	ds_read_b64 v[108:109], v3 offset:28672
	ds_read_b64 v[110:111], v3 offset:28160
	ds_read_b64 v[112:113], v3 offset:27648
	ds_read_b64 v[114:115], v3 offset:27136
	ds_read_b64 v[116:117], v3 offset:26624
	ds_read_b64 v[118:119], v3 offset:26112
	ds_read_b64 v[120:121], v3 offset:25600
	s_waitcnt lgkmcnt(7)
	v_fma_f32 v5, v106, v5, v107
	v_mov_b32_e32 v107, v5
	s_waitcnt lgkmcnt(6)
	v_fma_f32 v5, v108, v5, v109
	v_mov_b32_e32 v109, v5
	s_waitcnt lgkmcnt(5)
	v_fma_f32 v5, v110, v5, v111
	v_mov_b32_e32 v111, v5
	s_waitcnt lgkmcnt(4)
	v_fma_f32 v5, v112, v5, v113
	v_mov_b32_e32 v113, v5
	s_waitcnt lgkmcnt(3)
	v_fma_f32 v5, v114, v5, v115
	v_mov_b32_e32 v115, v5
	s_waitcnt lgkmcnt(2)
	v_fma_f32 v5, v116, v5, v117
	v_mov_b32_e32 v117, v5
	s_waitcnt lgkmcnt(1)
	v_fma_f32 v5, v118, v5, v119
	v_mov_b32_e32 v119, v5
	s_waitcnt lgkmcnt(0)
	v_fma_f32 v5, v120, v5, v121
	v_mov_b32_e32 v121, v5
	ds_write_b32 v3, v107 offset:29188
	ds_write_b32 v3, v109 offset:28676
	ds_write_b32 v3, v111 offset:28164
	ds_write_b32 v3, v113 offset:27652
	ds_write_b32 v3, v115 offset:27140
	ds_write_b32 v3, v117 offset:26628
	ds_write_b32 v3, v119 offset:26116
	ds_write_b32 v3, v121 offset:25604
	ds_read_b64 v[106:107], v3 offset:25088
	ds_read_b64 v[108:109], v3 offset:24576
	ds_read_b64 v[110:111], v3 offset:24064
	ds_read_b64 v[112:113], v3 offset:23552
	ds_read_b64 v[114:115], v3 offset:23040
	ds_read_b64 v[116:117], v3 offset:22528
	ds_read_b64 v[118:119], v3 offset:22016
	ds_read_b64 v[120:121], v3 offset:21504
	s_waitcnt lgkmcnt(7)
	v_fma_f32 v5, v106, v5, v107
	v_mov_b32_e32 v107, v5
	s_waitcnt lgkmcnt(6)
	v_fma_f32 v5, v108, v5, v109
	v_mov_b32_e32 v109, v5
	s_waitcnt lgkmcnt(5)
	v_fma_f32 v5, v110, v5, v111
	v_mov_b32_e32 v111, v5
	s_waitcnt lgkmcnt(4)
	v_fma_f32 v5, v112, v5, v113
	v_mov_b32_e32 v113, v5
	s_waitcnt lgkmcnt(3)
	v_fma_f32 v5, v114, v5, v115
	v_mov_b32_e32 v115, v5
	s_waitcnt lgkmcnt(2)
; DI void lru_item(const Params& p, int l, int b, int chunk, int blk, bool fin, char* smem, int tid) {
;     ...
;       for (int s2 = 0; s2 < 64; s2++) { const int t = dir ? 63 - s2 : s2; float2 v = au[(dir * 64 + t) * 64 + ch]; hst = v.x * hst + v.y; au[(dir * 64 + t) * 64 + ch].y = hst; }
;     ...
;   if (fin) {
;     __syncthreads();
;     const int ch4 = (tid & 15) * 4;
; #pragma unroll
;     for (int ps = 0; ps < 4; ps++) {
;       const int t = (tid >> 4) + 16 * ps;
;       const size_t row = (size_t)b * SEQA + pos0 + t;
;       uint2 zz = *(const uint2*)(p.Pk + row * PKW + 768 + 512 + c0 + ch4);
	v_fma_f32 v5, v116, v5, v117
	v_mov_b32_e32 v117, v5
	s_waitcnt lgkmcnt(1)
	v_fma_f32 v5, v118, v5, v119
	v_mov_b32_e32 v119, v5
	s_waitcnt lgkmcnt(0)
	v_fma_f32 v5, v120, v5, v121
	v_mov_b32_e32 v121, v5
	ds_write_b32 v3, v107 offset:25092
	ds_write_b32 v3, v109 offset:24580
	ds_write_b32 v3, v111 offset:24068
	ds_write_b32 v3, v113 offset:23556
	ds_write_b32 v3, v115 offset:23044
	ds_write_b32 v3, v117 offset:22532
	ds_write_b32 v3, v119 offset:22020
	ds_write_b32 v3, v121 offset:21508
	ds_read_b64 v[106:107], v3 offset:20992
	ds_read_b64 v[108:109], v3 offset:20480
	ds_read_b64 v[110:111], v3 offset:19968
	ds_read_b64 v[112:113], v3 offset:19456
	ds_read_b64 v[114:115], v3 offset:18944
	ds_read_b64 v[116:117], v3 offset:18432
	ds_read_b64 v[118:119], v3 offset:17920
	ds_read_b64 v[120:121], v3 offset:17408
	s_waitcnt lgkmcnt(7)
	v_fma_f32 v5, v106, v5, v107
	v_mov_b32_e32 v107, v5
	s_waitcnt lgkmcnt(6)
	v_fma_f32 v5, v108, v5, v109
	v_mov_b32_e32 v109, v5
	s_waitcnt lgkmcnt(5)
	v_fma_f32 v5, v110, v5, v111
	v_mov_b32_e32 v111, v5
	s_waitcnt lgkmcnt(4)
	v_fma_f32 v5, v112, v5, v113
	v_mov_b32_e32 v113, v5
	s_waitcnt lgkmcnt(3)
	v_fma_f32 v5, v114, v5, v115
	v_mov_b32_e32 v115, v5
	s_waitcnt lgkmcnt(2)
	v_fma_f32 v5, v116, v5, v117
	v_mov_b32_e32 v117, v5
	s_waitcnt lgkmcnt(1)
	v_fma_f32 v5, v118, v5, v119
	v_mov_b32_e32 v119, v5
	s_waitcnt lgkmcnt(0)
	v_fma_f32 v5, v120, v5, v121
	v_mov_b32_e32 v121, v5
	ds_write_b32 v3, v107 offset:20996
	ds_write_b32 v3, v109 offset:20484
	ds_write_b32 v3, v111 offset:19972
	ds_write_b32 v3, v113 offset:19460
	ds_write_b32 v3, v115 offset:18948
	ds_write_b32 v3, v117 offset:18436
	ds_write_b32 v3, v119 offset:17924
	ds_write_b32 v3, v121 offset:17412
	ds_read_b64 v[106:107], v3 offset:16896
	ds_read_b64 v[108:109], v3 offset:16384
	ds_read_b64 v[110:111], v3 offset:15872
	ds_read_b64 v[112:113], v3 offset:15360
	ds_read_b64 v[114:115], v3 offset:14848
	ds_read_b64 v[116:117], v3 offset:14336
	ds_read_b64 v[118:119], v3 offset:13824
	ds_read_b64 v[120:121], v3 offset:13312
	s_waitcnt lgkmcnt(7)
	v_fma_f32 v5, v106, v5, v107
	v_mov_b32_e32 v107, v5
	s_waitcnt lgkmcnt(6)
	v_fma_f32 v5, v108, v5, v109
	v_mov_b32_e32 v109, v5
	s_waitcnt lgkmcnt(5)
	v_fma_f32 v5, v110, v5, v111
	v_mov_b32_e32 v111, v5
	s_waitcnt lgkmcnt(4)
	v_fma_f32 v5, v112, v5, v113
	v_mov_b32_e32 v113, v5
	s_waitcnt lgkmcnt(3)
	v_fma_f32 v5, v114, v5, v115
	v_mov_b32_e32 v115, v5
	s_waitcnt lgkmcnt(2)
	v_fma_f32 v5, v116, v5, v117
	v_mov_b32_e32 v117, v5
	s_waitcnt lgkmcnt(1)
	v_fma_f32 v5, v118, v5, v119
	v_mov_b32_e32 v119, v5
	s_waitcnt lgkmcnt(0)
	v_fma_f32 v5, v120, v5, v121
	v_mov_b32_e32 v121, v5
	ds_write_b32 v3, v107 offset:16900
	ds_write_b32 v3, v109 offset:16388
	ds_write_b32 v3, v111 offset:15876
	ds_write_b32 v3, v113 offset:15364
	ds_write_b32 v3, v115 offset:14852
	ds_write_b32 v3, v117 offset:14340
	ds_write_b32 v3, v119 offset:13828
	ds_write_b32 v3, v121 offset:13316
	ds_read_b64 v[106:107], v3 offset:12800
	ds_read_b64 v[108:109], v3 offset:12288
	ds_read_b64 v[110:111], v3 offset:11776
	ds_read_b64 v[112:113], v3 offset:11264
	ds_read_b64 v[114:115], v3 offset:10752
	ds_read_b64 v[116:117], v3 offset:10240
	ds_read_b64 v[118:119], v3 offset:9728
	ds_read_b64 v[120:121], v3 offset:9216
	s_waitcnt lgkmcnt(7)
	v_fma_f32 v5, v106, v5, v107
	v_mov_b32_e32 v107, v5
	s_waitcnt lgkmcnt(6)
	v_fma_f32 v5, v108, v5, v109
	v_mov_b32_e32 v109, v5
	s_waitcnt lgkmcnt(5)
	v_fma_f32 v5, v110, v5, v111
	v_mov_b32_e32 v111, v5
	s_waitcnt lgkmcnt(4)
	v_fma_f32 v5, v112, v5, v113
	v_mov_b32_e32 v113, v5
	s_waitcnt lgkmcnt(3)
	v_fma_f32 v5, v114, v5, v115
	v_mov_b32_e32 v115, v5
	s_waitcnt lgkmcnt(2)
	v_fma_f32 v5, v116, v5, v117
	v_mov_b32_e32 v117, v5
	s_waitcnt lgkmcnt(1)
	v_fma_f32 v5, v118, v5, v119
	v_mov_b32_e32 v119, v5
	s_waitcnt lgkmcnt(0)
	v_fma_f32 v5, v120, v5, v121
	v_mov_b32_e32 v121, v5
	ds_write_b32 v3, v107 offset:12804
	ds_write_b32 v3, v109 offset:12292
	ds_write_b32 v3, v111 offset:11780
	ds_write_b32 v3, v113 offset:11268
	ds_write_b32 v3, v115 offset:10756
	ds_write_b32 v3, v117 offset:10244
	ds_write_b32 v3, v119 offset:9732
	ds_write_b32 v3, v121 offset:9220
.Llf_scan_done:
.LBB0_1085:
	s_or_b64 exec, exec, s[0:1]
	v_ashrrev_i32_e32 v77, 31, v76
	s_movk_i32 s0, 0x1100
	v_mad_i64_i32 v[6:7], s[0:1], v73, s0, v[76:77]
	v_lshl_add_u64 v[8:9], v[6:7], 0, v[44:45]
	v_mov_b64_e32 v[4:5], s[90:91]
	v_mad_u64_u32 v[10:11], s[0:1], v8, s33, v[4:5]
	v_mad_i32_i24 v11, v9, s33, v11
	v_lshlrev_b64 v[2:3], 1, v[74:75]
	v_lshl_add_u64 v[10:11], v[10:11], 0, v[2:3]
	v_mov_b32_e32 v73, v1
	v_lshl_add_u64 v[10:11], v[10:11], 0, v[72:73]
	s_waitcnt lgkmcnt(0)
	s_barrier
; DI unsigned pack2(float a, float b) { f32v2 v = {a, b}; return __builtin_bit_cast(unsigned, __builtin_convertvector(v, bf16v2)); }
; DI float bflo(unsigned v) { return __uint_as_float(v << 16); }
; DI float bfhi(unsigned v) { return __uint_as_float(v & 0xffff0000u); }
; DI float silu(float x) { return x * sigm(x); }
; DI void lru_item(const Params& p, int l, int b, int chunk, int blk, bool fin, char* smem, int tid) {
;     ...
;     const int ch4 = (tid & 15) * 4;
; #pragma unroll
;     for (int ps = 0; ps < 4; ps++) {
;       const int t = (tid >> 4) + 16 * ps;
;       const size_t row = (size_t)b * SEQA + pos0 + t;
;       uint2 zz = *(const uint2*)(p.Pk + row * PKW + 768 + 512 + c0 + ch4);
;       float y0 = au[(t) * 64 + ch4].y + au[(64 + t) * 64 + ch4].y, y1 = au[(t) * 64 + ch4 + 1].y + au[(64 + t) * 64 + ch4 + 1].y;
;       float y2 = au[(t) * 64 + ch4 + 2].y + au[(64 + t) * 64 + ch4 + 2].y, y3 = au[(t) * 64 + ch4 + 3].y + au[(64 + t) * 64 + ch4 + 3].y;
;       uint2 o; o.x = pack2(y0 * silu(bflo(zz.x)), y1 * silu(bfhi(zz.x))); o.y = pack2(y2 * silu(bflo(zz.y)), y3 * silu(bfhi(zz.y)));
;       *(uint2*)(p.G + row * 1024 + 512 + c0 + ch4) = o;
;     }
	global_load_dwordx2 v[10:11], v[10:11], off offset:2560
	v_add_u32_e32 v0, 0x2400, v90
	ds_read2_b32 v[12:13], v0 offset0:1 offset1:3
	ds_read2_b32 v[14:15], v0 offset0:5 offset1:7
	v_add_u32_e32 v0, 0xa400, v90
	ds_read2_b32 v[16:17], v0 offset0:1 offset1:3
	ds_read2_b32 v[18:19], v0 offset0:5 offset1:7
	v_readlane_b32 s2, v253, 48
	v_lshlrev_b64 v[8:9], 11, v[8:9]
	v_readlane_b32 s3, v253, 49
	s_waitcnt lgkmcnt(1)
	v_pk_add_f32 v[12:13], v[12:13], v[16:17]
	s_waitcnt lgkmcnt(0)
	v_pk_add_f32 v[14:15], v[14:15], v[18:19]
	v_lshl_add_u64 v[8:9], s[2:3], 0, v[8:9]
	v_lshl_add_u64 v[8:9], v[8:9], 0, v[2:3]
	v_lshl_add_u64 v[8:9], v[8:9], 0, v[72:73]
	s_waitcnt vmcnt(0)
	v_lshlrev_b32_e32 v20, 16, v10
	v_mul_f32_e32 v0, 0xbfb8aa3b, v20
	v_exp_f32_e32 v0, v0
	v_and_b32_e32 v21, 0xffff0000, v10
	v_add_f32_e32 v0, 1.0, v0
	v_rcp_f32_e32 v16, v0
	v_mul_f32_e32 v0, 0xbfb8aa3b, v21
	v_exp_f32_e32 v0, v0
	s_nop 0
	v_add_f32_e32 v0, 1.0, v0
	v_rcp_f32_e32 v17, v0
	s_nop 0
	v_pk_mul_f32 v[16:17], v[16:17], v[20:21]
	s_nop 0
	v_pk_mul_f32 v[12:13], v[12:13], v[16:17]
	s_nop 0
	v_cvt_pk_bf16_f32 v10, v12, v13
	v_lshlrev_b32_e32 v12, 16, v11
	v_mul_f32_e32 v0, 0xbfb8aa3b, v12
	v_exp_f32_e32 v0, v0
	v_and_b32_e32 v13, 0xffff0000, v11
	v_add_f32_e32 v0, 1.0, v0
	v_rcp_f32_e32 v16, v0
	v_mul_f32_e32 v0, 0xbfb8aa3b, v13
	v_exp_f32_e32 v0, v0
	s_nop 0
	v_add_f32_e32 v0, 1.0, v0
	v_rcp_f32_e32 v17, v0
	v_add_u32_e32 v0, 0x2400, v91
	v_pk_mul_f32 v[12:13], v[16:17], v[12:13]
	s_nop 0
	v_pk_mul_f32 v[12:13], v[14:15], v[12:13]
	s_nop 0
	v_cvt_pk_bf16_f32 v11, v12, v13
	global_store_dwordx2 v[8:9], v[10:11], off offset:1024
	v_lshl_add_u64 v[8:9], v[6:7], 0, v[46:47]
	v_mad_u64_u32 v[10:11], s[0:1], v8, s33, v[4:5]
	v_mad_i32_i24 v11, v9, s33, v11
	v_lshl_add_u64 v[10:11], v[10:11], 0, v[2:3]
	v_lshl_add_u64 v[10:11], v[10:11], 0, v[72:73]
	global_load_dwordx2 v[10:11], v[10:11], off offset:2560
	ds_read2_b32 v[12:13], v0 offset0:1 offset1:3
	ds_read2_b32 v[14:15], v0 offset0:5 offset1:7
	v_add_u32_e32 v0, 0xa400, v91
	ds_read2_b32 v[16:17], v0 offset0:1 offset1:3
	ds_read2_b32 v[18:19], v0 offset0:5 offset1:7
	v_lshlrev_b64 v[8:9], 11, v[8:9]
	v_lshl_add_u64 v[8:9], s[2:3], 0, v[8:9]
	v_lshl_add_u64 v[8:9], v[8:9], 0, v[2:3]
	s_waitcnt lgkmcnt(1)
	v_pk_add_f32 v[12:13], v[12:13], v[16:17]
	s_waitcnt lgkmcnt(0)
	v_pk_add_f32 v[14:15], v[14:15], v[18:19]
	v_lshl_add_u64 v[8:9], v[8:9], 0, v[72:73]
	s_waitcnt vmcnt(0)
	v_lshlrev_b32_e32 v20, 16, v10
	v_mul_f32_e32 v0, 0xbfb8aa3b, v20
	v_exp_f32_e32 v0, v0
	v_and_b32_e32 v21, 0xffff0000, v10
	v_add_f32_e32 v0, 1.0, v0
	v_rcp_f32_e32 v16, v0
	v_mul_f32_e32 v0, 0xbfb8aa3b, v21
	v_exp_f32_e32 v0, v0
	s_nop 0
	v_add_f32_e32 v0, 1.0, v0
	v_rcp_f32_e32 v17, v0
	s_nop 0
	v_pk_mul_f32 v[16:17], v[16:17], v[20:21]
	s_nop 0
	v_pk_mul_f32 v[12:13], v[12:13], v[16:17]
	s_nop 0
	v_cvt_pk_bf16_f32 v10, v12, v13
	v_lshlrev_b32_e32 v12, 16, v11
	v_mul_f32_e32 v0, 0xbfb8aa3b, v12
	v_exp_f32_e32 v0, v0
	v_and_b32_e32 v13, 0xffff0000, v11
	v_add_f32_e32 v0, 1.0, v0
	v_rcp_f32_e32 v16, v0
	v_mul_f32_e32 v0, 0xbfb8aa3b, v13
	v_exp_f32_e32 v0, v0
	s_nop 0
	v_add_f32_e32 v0, 1.0, v0
	v_rcp_f32_e32 v17, v0
	v_add_u32_e32 v0, 0x2400, v92
	v_pk_mul_f32 v[12:13], v[16:17], v[12:13]
	s_nop 0
	v_pk_mul_f32 v[12:13], v[14:15], v[12:13]
	s_nop 0
	v_cvt_pk_bf16_f32 v11, v12, v13
	global_store_dwordx2 v[8:9], v[10:11], off offset:1024
	v_lshl_add_u64 v[8:9], v[6:7], 0, v[48:49]
	v_mad_u64_u32 v[10:11], s[0:1], v8, s33, v[4:5]
	v_mad_i32_i24 v11, v9, s33, v11
	v_lshl_add_u64 v[10:11], v[10:11], 0, v[2:3]
	v_lshl_add_u64 v[10:11], v[10:11], 0, v[72:73]
	global_load_dwordx2 v[10:11], v[10:11], off offset:2560
	ds_read2_b32 v[12:13], v0 offset0:1 offset1:3
	ds_read2_b32 v[14:15], v0 offset0:5 offset1:7
	v_add_u32_e32 v0, 0xa400, v92
	ds_read2_b32 v[16:17], v0 offset0:1 offset1:3
	ds_read2_b32 v[18:19], v0 offset0:5 offset1:7
	v_lshlrev_b64 v[8:9], 11, v[8:9]
	v_lshl_add_u64 v[6:7], v[6:7], 0, v[50:51]
	v_lshl_add_u64 v[8:9], s[2:3], 0, v[8:9]
	s_waitcnt lgkmcnt(1)
	v_pk_add_f32 v[12:13], v[12:13], v[16:17]
	s_waitcnt lgkmcnt(0)
	v_pk_add_f32 v[14:15], v[14:15], v[18:19]
	v_mad_u64_u32 v[4:5], s[0:1], v6, s33, v[4:5]
	v_lshl_add_u64 v[8:9], v[8:9], 0, v[2:3]
	v_mad_i32_i24 v5, v7, s33, v5
	v_lshl_add_u64 v[8:9], v[8:9], 0, v[72:73]
	v_lshl_add_u64 v[4:5], v[4:5], 0, v[2:3]
	v_lshl_add_u64 v[4:5], v[4:5], 0, v[72:73]
	v_lshlrev_b64 v[6:7], 11, v[6:7]
	v_lshl_add_u64 v[6:7], s[2:3], 0, v[6:7]
	v_lshl_add_u64 v[2:3], v[6:7], 0, v[2:3]
	v_lshl_add_u64 v[2:3], v[2:3], 0, v[72:73]
	s_waitcnt vmcnt(0)
	v_lshlrev_b32_e32 v20, 16, v10
	v_mul_f32_e32 v0, 0xbfb8aa3b, v20
	v_exp_f32_e32 v0, v0
	v_and_b32_e32 v21, 0xffff0000, v10
	v_add_f32_e32 v0, 1.0, v0
	v_rcp_f32_e32 v16, v0
	v_mul_f32_e32 v0, 0xbfb8aa3b, v21
	v_exp_f32_e32 v0, v0
	s_nop 0
	v_add_f32_e32 v0, 1.0, v0
	v_rcp_f32_e32 v17, v0
	s_nop 0
	v_pk_mul_f32 v[16:17], v[16:17], v[20:21]
	s_nop 0
	v_pk_mul_f32 v[12:13], v[12:13], v[16:17]
	s_nop 0
	v_cvt_pk_bf16_f32 v10, v12, v13
	v_lshlrev_b32_e32 v12, 16, v11
	v_mul_f32_e32 v0, 0xbfb8aa3b, v12
	v_exp_f32_e32 v0, v0
	v_and_b32_e32 v13, 0xffff0000, v11
	v_add_f32_e32 v0, 1.0, v0
	v_rcp_f32_e32 v16, v0
	v_mul_f32_e32 v0, 0xbfb8aa3b, v13
	v_exp_f32_e32 v0, v0
	s_nop 0
	v_add_f32_e32 v0, 1.0, v0
	v_rcp_f32_e32 v17, v0
	v_add_u32_e32 v0, 0x2400, v93
	v_pk_mul_f32 v[12:13], v[16:17], v[12:13]
	s_nop 0
	v_pk_mul_f32 v[12:13], v[14:15], v[12:13]
	s_nop 0
	v_cvt_pk_bf16_f32 v11, v12, v13
	global_store_dwordx2 v[8:9], v[10:11], off offset:1024
	global_load_dwordx2 v[4:5], v[4:5], off offset:2560
	ds_read2_b32 v[8:9], v0 offset0:1 offset1:3
	ds_read2_b32 v[10:11], v0 offset0:5 offset1:7
	v_add_u32_e32 v0, 0xa400, v93
	ds_read2_b32 v[12:13], v0 offset0:1 offset1:3
	ds_read2_b32 v[14:15], v0 offset0:5 offset1:7
	s_waitcnt lgkmcnt(1)
	v_pk_add_f32 v[8:9], v[8:9], v[12:13]
	s_waitcnt lgkmcnt(0)
	v_pk_add_f32 v[10:11], v[10:11], v[14:15]
	s_waitcnt vmcnt(0)
	v_lshlrev_b32_e32 v16, 16, v4
	v_mul_f32_e32 v0, 0xbfb8aa3b, v16
	v_exp_f32_e32 v0, v0
	v_and_b32_e32 v17, 0xffff0000, v4
	v_add_f32_e32 v0, 1.0, v0
	v_rcp_f32_e32 v12, v0
	v_mul_f32_e32 v0, 0xbfb8aa3b, v17
	v_exp_f32_e32 v0, v0
	s_nop 0
	v_add_f32_e32 v0, 1.0, v0
	v_rcp_f32_e32 v13, v0
	s_nop 0
	v_pk_mul_f32 v[12:13], v[12:13], v[16:17]
	s_nop 0
	v_pk_mul_f32 v[8:9], v[8:9], v[12:13]
	s_nop 0
	v_cvt_pk_bf16_f32 v4, v8, v9
	v_lshlrev_b32_e32 v8, 16, v5
	v_mul_f32_e32 v0, 0xbfb8aa3b, v8
	v_exp_f32_e32 v0, v0
	v_and_b32_e32 v9, 0xffff0000, v5
	v_add_f32_e32 v0, 1.0, v0
	v_rcp_f32_e32 v12, v0
	v_mul_f32_e32 v0, 0xbfb8aa3b, v9
	v_exp_f32_e32 v0, v0
	s_nop 0
	v_add_f32_e32 v0, 1.0, v0
	v_rcp_f32_e32 v13, v0
	s_nop 0
	v_pk_mul_f32 v[8:9], v[12:13], v[8:9]
	s_nop 0
	v_pk_mul_f32 v[8:9], v[10:11], v[8:9]
	s_nop 0
	v_cvt_pk_bf16_f32 v5, v8, v9
	global_store_dwordx2 v[2:3], v[4:5], off offset:1024
	s_barrier
; DI int fetch_item(unsigned* ctr, char* smem) {
;   volatile int* slot = (volatile int*)(smem + SMEM_BYTES - 16);
;   __syncthreads();
;   if (threadIdx.x == 0) *slot = (int)__hip_atomic_fetch_add(ctr, 1u, __ATOMIC_RELAXED, __HIP_MEMORY_SCOPE_AGENT);
;   __syncthreads();
;   return *slot;
; }
; DI void phase_mix(const Params& p, int l, char* smem, int tid) {
;     ...
;   for (int j = fetch_item(q + 256, smem); j < NLRU; j = fetch_item(q + 256, smem)) {
	s_and_saveexec_b64 s[0:1], s[92:93]
	s_cbranch_execz .LBB0_1035
	s_mov_b64 s[12:13], exec
	v_mbcnt_lo_u32_b32 v0, s12, 0
	v_mbcnt_hi_u32_b32 v0, s13, v0
	v_cmp_eq_u32_e32 vcc, 0, v0
	s_and_saveexec_b64 s[2:3], vcc
	s_cbranch_execz .LBB0_1034
	s_bcnt1_i32_b64 s12, s[12:13]
	v_mov_b32_e32 v2, s12
	v_readlane_b32 s12, v254, 51
	v_readlane_b32 s13, v254, 52
	s_nop 4
	global_atomic_add v2, v1, v2, s[12:13] offset:1024 sc0
	s_branch .LBB0_1034

; DI void phase_merge(const Params& p, int l, char* smem, int tid) {
;     ...
;   for (int it = (dyn ? fetch_item(qc, smem) : (int)blockIdx.x); it < 544 * 8; it = (dyn ? fetch_item(qc, smem) : it + (int)gridDim.x)) {
;     const int mt = it >> 3, nt = it & 7, m0 = mt * 64, n0 = nt * 128;
;     if (l == 1 && (mt % 68) < 4) continue;
;     f32x16 accT[1][2]; zero_acc<1>(accT);
; #pragma unroll 1
;     for (int i = 0; i < 4; i++) {
;       if ((ZERO_MASK >> i) & 1) continue;
;       unsigned sg[2][8];
;       {
;         f32x16 m[1][2]; zero_acc<1>(m);
;         gemm_main<1>(p.xn + (size_t)m0 * 1024, 1024, p.WtM + (size_t)l * 4096 * 1024 + ((size_t)i * 1024 + n0) * 1024, 1024, 1024, m, s, tid);
.Lmg_decoded:
	s_lshr_b32 s3, s19, 14
	s_lshl_b32 s2, s19, 18
	s_add_u32 s2, s96, s2
	s_addc_u32 s3, s97, s3
	s_lshl_b32 s19, s13, 18
	s_mov_b32 s94, 0
.Lmg_again:
	v_mov_b32_e32 v2, 0
	v_mov_b32_e32 v3, 0
	v_mov_b32_e32 v4, 0
	v_mov_b32_e32 v5, 0
	v_mov_b32_e32 v6, 0
	v_mov_b32_e32 v7, 0
	v_mov_b32_e32 v8, 0
	v_mov_b32_e32 v9, 0
	v_mov_b32_e32 v10, 0
	v_mov_b32_e32 v11, 0
	v_mov_b32_e32 v12, 0
	v_mov_b32_e32 v13, 0
	v_mov_b32_e32 v14, 0
	v_mov_b32_e32 v15, 0
	v_mov_b32_e32 v16, 0
	v_mov_b32_e32 v17, 0
	v_mov_b32_e32 v18, 0
	v_mov_b32_e32 v19, 0
	v_mov_b32_e32 v20, 0
	v_mov_b32_e32 v21, 0
	v_mov_b32_e32 v22, 0
	v_mov_b32_e32 v23, 0
	v_mov_b32_e32 v24, 0
	v_mov_b32_e32 v25, 0
	v_mov_b32_e32 v26, 0
	v_mov_b32_e32 v27, 0
	v_mov_b32_e32 v28, 0
	v_mov_b32_e32 v29, 0
	v_mov_b32_e32 v30, 0
	v_mov_b32_e32 v31, 0
	v_mov_b32_e32 v32, 0
	v_mov_b32_e32 v33, 0
	v_mov_b32_e32 v34, 0
	v_mov_b32_e32 v35, 0
	v_mov_b32_e32 v36, 0
	v_mov_b32_e32 v37, 0
	v_mov_b32_e32 v38, 0
	v_mov_b32_e32 v39, 0
	v_mov_b32_e32 v40, 0
	v_mov_b32_e32 v41, 0
	v_mov_b32_e32 v42, 0
	v_mov_b32_e32 v43, 0
	v_mov_b32_e32 v44, 0
	v_mov_b32_e32 v45, 0
	v_mov_b32_e32 v46, 0
	v_mov_b32_e32 v47, 0
	v_mov_b32_e32 v48, 0
	v_mov_b32_e32 v49, 0
	v_mov_b32_e32 v50, 0
	v_mov_b32_e32 v51, 0
	v_mov_b32_e32 v52, 0
	v_mov_b32_e32 v53, 0
	v_mov_b32_e32 v54, 0
	v_mov_b32_e32 v55, 0
	v_mov_b32_e32 v56, 0
	v_mov_b32_e32 v57, 0
	v_mov_b32_e32 v58, 0
	v_mov_b32_e32 v59, 0
	v_mov_b32_e32 v60, 0
	v_mov_b32_e32 v61, 0
	v_mov_b32_e32 v62, 0
	v_mov_b32_e32 v63, 0
	v_mov_b32_e32 v64, 0
	v_mov_b32_e32 v65, 0
	s_mov_b32 s13, 0
	s_mov_b32 s4, s2
	s_mov_b32 s5, s3
	s_add_u32 s8, s14, s19
	s_addc_u32 s9, s15, 0
	s_add_u32 m0, s10, 0x0
	s_nop 0
	global_load_lds_dwordx4 v200, s[4:5]
	s_add_u32 m0, s10, 0x400
	s_nop 0
	global_load_lds_dwordx4 v201, s[4:5]
	s_add_u32 m0, s10, 0x800
	s_nop 0
	global_load_lds_dwordx4 v202, s[4:5]
	s_add_u32 m0, s10, 0xc00
	s_nop 0
	global_load_lds_dwordx4 v203, s[4:5]
	s_add_u32 m0, s10, 0x4000
	s_nop 0
	global_load_lds_dwordx4 v200, s[8:9]
	s_add_u32 m0, s10, 0x4400
	s_nop 0
	global_load_lds_dwordx4 v201, s[8:9]
	s_add_u32 m0, s10, 0x4800
	s_nop 0
	global_load_lds_dwordx4 v202, s[8:9]
	s_add_u32 m0, s10, 0x4c00
	s_nop 0
	global_load_lds_dwordx4 v203, s[8:9]
	s_add_u32 s4, s4, 128
	s_addc_u32 s5, s5, 0
	s_add_u32 s8, s8, 128
	s_addc_u32 s9, s9, 0

; #define G_STORE(S, bf) { *(uint4*)&s->a[bf][srow][skc] = S##a0; *(uint4*)&s->a[bf][srow + 32][skc] = S##a1; \
;     if (MB == 2) { *(uint4*)&s->a[bf][srow + 64][skc] = S##a2; *(uint4*)&s->a[bf][srow + 96][skc] = S##a3; } \
;     *(uint4*)&s->b[bf][srow][skc] = S##b0; *(uint4*)&s->b[bf][srow + 32][skc] = S##b1; *(uint4*)&s->b[bf][srow + 64][skc] = S##b2; *(uint4*)&s->b[bf][srow + 96][skc] = S##b3; }
; template <int MB, bool PF2 = true>
; DI void gemm_main(const u16* __restrict__ A, int lda, const u16* __restrict__ B, int ldb, int K, f32x16 (&acc)[MB][2], GemmLds* s, int tid) {
;     ...
;   __syncthreads();
;   G_LOAD(p, 0); G_STORE(p, 0);
;   if (!PF2) {
;     __syncthreads();
;     for (int kt = 0; kt < KT; kt++) {
;       const int buf = kt & 1;
;       if (kt + 1 < KT) G_LOAD(p, (kt + 1) * 64);
;       if (buf) { G_COMPUTE(1); } else { G_COMPUTE(0); }
;       if (kt + 1 < KT) { if (buf) { G_STORE(p, 0); } else { G_STORE(p, 1); } }
;       __syncthreads();
;     }
;     return;
;   }
;   const int klast = K - 64;
;   G_LOAD(p, 64);
;   __syncthreads();
; DI void phase_outproj(const Params& p, int l, char* smem, int tid) {
;     ...
;   for (int it = (dyn ? fetch_item(qc, smem) : (int)blockIdx.x); it < 272 * 8; it = (dyn ? fetch_item(qc, smem) : it + (int)gridDim.x)) {
;     const int mt = it >> 3, nt = it & 7, m0 = mt * 128, n0 = nt * 128;
;     if (l == 1 && (mt % 34) < 2) continue;
;     f32x16 acc[2][2]; zero_acc<2>(acc);
;     gemm_main<2>(ACC + (size_t)m0 * 1024, 1024, p.WtOut + (size_t)l * 1024 * 1024 + (size_t)n0 * 1024, 1024, 1024, acc, s, tid);
;     u16* O = p.G;
; #pragma unroll
;     for (int mb = 0; mb < 2; mb++)
; #pragma unroll
;       for (int nb = 0; nb < 2; nb++) {
;         const int rowb = m0 + wm * 64 + mb * 32, col = n0 + wn * 64 + nb * 32 + r;
;         const int b = rowb / SEQA, pos0 = rowb % SEQA;
;         const float gate = p.mod[((size_t)l * 9 + ((pos0 < CTXL) ? 8 : b)) * 3072 + 2048 + col];
.Lop_fetch_wait:
	s_barrier
	v_mov_b32_e32 v115, 0x125f0
	ds_read_b32 v114, v115
	s_waitcnt lgkmcnt(0)
	v_readfirstlane_b32 s12, v114
	s_cmpk_lt_u32 s12, 0x880
	s_cbranch_scc0 .Lop_done
	s_lshr_b32 s20, s12, 3
	s_mul_hi_u32 s6, s20, 0x78787879
	s_lshr_b32 s6, s6, 4
	s_mul_i32 s7, s6, 34
	s_sub_u32 s7, s20, s7
	s_cmp_lt_u32 s7, 2
	s_cselect_b32 s21, 8, s6
	s_branch .Lop_decoded
.Lop_static:
	s_barrier
	s_cmpk_lt_u32 s12, 0x800
	s_cbranch_scc0 .Lop_done
	s_lshr_b32 s21, s12, 8
	s_mul_i32 s7, s21, 34
	s_bfe_u32 s20, s12, 0x50003
	s_add_u32 s20, s20, s7
	s_add_u32 s20, s20, 2
.Lop_decoded:
	s_mov_b32 s94, 0
.Lop_again:
	s_and_b32 s13, s12, 7
	s_mul_i32 s7, s18, 9
	s_add_u32 s7, s7, s21
	s_mul_i32 s7, s7, 0x3000
	s_lshl_b32 s6, s13, 9
	s_add_u32 s7, s7, s6
	s_add_u32 s7, s7, 0x1d002000
	s_add_u32 s6, s96, s7
	s_addc_u32 s7, s97, 0
	global_load_dwordx4 v[116:119], v111, s[6:7] offset:0
	global_load_dwordx4 v[120:123], v111, s[6:7] offset:32
	global_load_dwordx4 v[124:127], v111, s[6:7] offset:64
	global_load_dwordx4 v[128:131], v111, s[6:7] offset:96
	global_load_dwordx4 v[132:135], v111, s[6:7] offset:128
	global_load_dwordx4 v[136:139], v111, s[6:7] offset:160
	global_load_dwordx4 v[140:143], v111, s[6:7] offset:192
	global_load_dwordx4 v[144:147], v111, s[6:7] offset:224
	s_lshl_b32 s2, s20, 18
	s_add_u32 s4, s90, s2
	s_addc_u32 s5, s91, 0
	s_lshl_b32 s3, s13, 18
	s_add_u32 s8, s14, s3
	s_addc_u32 s9, s15, 0
	s_lshl_b32 s3, s13, 8
	s_add_u32 s2, s2, s3
	s_add_u32 s2, s2, 0x16720000
	s_add_u32 s16, s96, s2
	s_addc_u32 s17, s97, 0
	v_mov_b32_e32 v2, 0
	v_mov_b32_e32 v3, 0
	v_mov_b32_e32 v4, 0
	v_mov_b32_e32 v5, 0
	v_mov_b32_e32 v6, 0
	v_mov_b32_e32 v7, 0
	v_mov_b32_e32 v8, 0
	v_mov_b32_e32 v9, 0
	v_mov_b32_e32 v10, 0
	v_mov_b32_e32 v11, 0
	v_mov_b32_e32 v12, 0
	v_mov_b32_e32 v13, 0
	v_mov_b32_e32 v14, 0
	v_mov_b32_e32 v15, 0
	v_mov_b32_e32 v16, 0
	v_mov_b32_e32 v17, 0
	v_mov_b32_e32 v18, 0
	v_mov_b32_e32 v19, 0
	v_mov_b32_e32 v20, 0
	v_mov_b32_e32 v21, 0
	v_mov_b32_e32 v22, 0
	v_mov_b32_e32 v23, 0
	v_mov_b32_e32 v24, 0
	v_mov_b32_e32 v25, 0
	v_mov_b32_e32 v26, 0
	v_mov_b32_e32 v27, 0
	v_mov_b32_e32 v28, 0
	v_mov_b32_e32 v29, 0
	v_mov_b32_e32 v30, 0
	v_mov_b32_e32 v31, 0
	v_mov_b32_e32 v32, 0
	v_mov_b32_e32 v33, 0
	v_mov_b32_e32 v34, 0
	v_mov_b32_e32 v35, 0
	v_mov_b32_e32 v36, 0
	v_mov_b32_e32 v37, 0
	v_mov_b32_e32 v38, 0
	v_mov_b32_e32 v39, 0
	v_mov_b32_e32 v40, 0
	v_mov_b32_e32 v41, 0
	v_mov_b32_e32 v42, 0
	v_mov_b32_e32 v43, 0
	v_mov_b32_e32 v44, 0
	v_mov_b32_e32 v45, 0
	v_mov_b32_e32 v46, 0
	v_mov_b32_e32 v47, 0
	v_mov_b32_e32 v48, 0
	v_mov_b32_e32 v49, 0
	v_mov_b32_e32 v50, 0
	v_mov_b32_e32 v51, 0
	v_mov_b32_e32 v52, 0
	v_mov_b32_e32 v53, 0
	v_mov_b32_e32 v54, 0
	v_mov_b32_e32 v55, 0
	v_mov_b32_e32 v56, 0
	v_mov_b32_e32 v57, 0
	v_mov_b32_e32 v58, 0
	v_mov_b32_e32 v59, 0
	v_mov_b32_e32 v60, 0
	v_mov_b32_e32 v61, 0
	v_mov_b32_e32 v62, 0
	v_mov_b32_e32 v63, 0
	v_mov_b32_e32 v64, 0
	v_mov_b32_e32 v65, 0
	s_add_u32 m0, s10, 0x0
	s_nop 0
	global_load_lds_dwordx4 v98, s[4:5]
	s_add_u32 m0, s10, 0x400
	s_nop 0
	global_load_lds_dwordx4 v99, s[4:5]
	s_add_u32 m0, s10, 0x800
	s_nop 0
	global_load_lds_dwordx4 v100, s[4:5]
	s_add_u32 m0, s10, 0xc00
	s_nop 0
	global_load_lds_dwordx4 v101, s[4:5]
	s_add_u32 m0, s10, 0x4000
	s_nop 0
	global_load_lds_dwordx4 v98, s[8:9]
	s_add_u32 m0, s10, 0x4400
	s_nop 0
	global_load_lds_dwordx4 v99, s[8:9]
	s_add_u32 m0, s10, 0x4800
	s_nop 0
	global_load_lds_dwordx4 v100, s[8:9]
	s_add_u32 m0, s10, 0x4c00
	s_nop 0
	global_load_lds_dwordx4 v101, s[8:9]
	s_add_u32 s4, s4, 128
	s_addc_u32 s5, s5, 0
	s_add_u32 s8, s8, 128
	s_addc_u32 s9, s9, 0
	s_waitcnt vmcnt(0) lgkmcnt(0)
	s_barrier
	ds_read_b128 v[66:69], v102 offset:0
	ds_read_b128 v[74:77], v106 offset:0
	ds_read_b128 v[70:73], v102 offset:4096
	ds_read_b128 v[78:81], v106 offset:4096
	s_add_u32 m0, s10, 0x8000
	s_nop 0
	global_load_lds_dwordx4 v98, s[4:5]
	s_add_u32 m0, s10, 0x8400
	s_nop 0
	global_load_lds_dwordx4 v99, s[4:5]
	s_add_u32 m0, s10, 0x8800
	s_nop 0
	global_load_lds_dwordx4 v100, s[4:5]
	s_add_u32 m0, s10, 0x8c00
	s_nop 0
	global_load_lds_dwordx4 v101, s[4:5]
	s_add_u32 s4, s4, 128
	s_addc_u32 s5, s5, 0
	s_mov_b32 s11, 7
